# attention loop: 4 staging register sets (4-tile lookahead), counted LDS waits, scalar row sums; GLU task: s5_d table staged in LDS, yw/uw loads hoisted with counted vmcnt
# speedup vs baseline: 1.0225x; 1.0225x over previous
; #define LAS __attribute__((address_space(3)))
; #define MFMA16(a, b, c) __builtin_amdgcn_mfma_f32_16x16x32_bf16((a), (b), (c), 0, 0, 0)
; #define ATT_LOAD(S_, tt) do { const bf16_t* kt_ = kg + (size_t)(tt) * 64 * 96; rk0[S_] = ld8(kt_ + kp0 * 8); if (kp1 < 768) rk1[S_] = ld8(kt_ + kp1 * 8); rv[S_] = ld8(vg + (size_t)vd * NKEY + (tt) * 64 + vpart * 8); } while (0)
; #define ATT_STORE(S_, bufi) do { LAS unsigned char* kb_ = lds + (bufi) * KBUF; *(LAS u32x4*)(kb_ + (kp0 / 12) * KST + (kp0 % 12) * 16) = rk0[S_]; if (kp1 < 768) *(LAS u32x4*)(kb_ + (kp1 / 12) * KST + (kp1 % 12) * 16) = rk1[S_]; \
;         *(LAS u32x4*)(lds + VOFF + (bufi) * VBUF + vd * VST + vpart * 16) = rv[S_]; } while (0)
; __device__ __forceinline__ void attn_unit(LAS unsigned char* lds, const bf16_t* QB, const bf16_t* KB, const bf16_t* VT, const bf16_t* P, bf16_t* Z0, int b, int h, int qrow0, int nkeys) {
;     ...
;     __syncthreads();
;     ATT_LOAD(0, 0); ATT_STORE(0, 0);
;     __syncthreads();
;     if (1 < ntile) ATT_LOAD(0, 1);
;     if (2 < ntile) ATT_LOAD(1, 2);
;     f32x4 o[2][4]; float lsum[2];
; #pragma unroll
;     for (int qb = 0; qb < 2; ++qb) { lsum[qb] = 0.f;
; #pragma unroll
;         for (int db = 0; db < 4; ++db) o[qb][db] = (f32x4){0.f, 0.f, 0.f, 0.f}; }
;     for (int t2 = 0; t2 < ntile; t2 += 2) {
; #pragma unroll
;       for (int half = 0; half < 2; ++half) { const int tt = t2 + half; if (tt < ntile) {
;         const int cur = half;
;         const LAS unsigned char* kb = lds + cur * KBUF; const LAS unsigned char* vb = lds + VOFF + cur * VBUF;
;         f32x4 s[2][4];
; #pragma unroll
;         for (int kbk = 0; kbk < 4; ++kbk) { s[0][kbk] = (f32x4){0.f, 0.f, 0.f, 0.f}; s[1][kbk] = s[0][kbk];
; #pragma unroll
;             for (int ks = 0; ks < 3; ++ks) { const bf16x8 kf = *(const LAS bf16x8*)(kb + (kbk * 16 + fr) * KST + ks * 64 + fq * 16);
;                 s[0][kbk] = MFMA16(kf, qf[0][ks], s[0][kbk]); s[1][kbk] = MFMA16(kf, qf[1][ks], s[1][kbk]); } }
.LBB0_1041:
	s_or_b64 exec, exec, s[24:25]
	v_mul_lo_u32 v16, v58, s15
	s_add_u32 s24, s22, 0x3000
	v_add_u32_e32 v16, 0, v16
	s_addc_u32 s25, s23, 0
	v_add_u32_e32 v172, v16, v0
	v_lshl_add_u64 v[16:17], v[26:27], 1, s[24:25]
	ds_write_b128 v172, v[22:25] offset:26624
	s_waitcnt lgkmcnt(0)
	s_barrier
	global_load_dwordx4 v[62:65], v[16:17], off
	s_and_saveexec_b64 s[6:7], vcc
	s_xor_b64 s[26:27], exec, s[6:7]
	v_lshlrev_b32_e32 v28, 3, v33
	s_andn2_saveexec_b64 s[26:27], s[26:27]
	s_cbranch_execz .LBB0_1045
	v_ashrrev_i32_e32 v29, 31, v28
	v_lshl_add_u64 v[2:3], v[28:29], 1, s[24:25]
	global_load_dwordx4 v[2:5], v[2:3], off
.LBB0_1045:
	s_or_b64 exec, exec, s[26:27]
	s_add_u32 s22, s22, 0x6000
	s_addc_u32 s23, s23, 0
	v_lshl_add_u64 v[16:17], v[26:27], 1, s[22:23]
	global_load_dwordx4 v[70:73], v[30:31], off offset:128
	global_load_dwordx4 v[66:69], v[16:17], off
	s_and_saveexec_b64 s[6:7], vcc
	s_xor_b64 s[24:25], exec, s[6:7]
	v_mov_b32_e32 v29, v1
	s_andn2_saveexec_b64 s[24:25], s[24:25]
	s_cbranch_execz .LBB0_1049
	v_ashrrev_i32_e32 v29, 31, v28
	v_lshl_add_u64 v[6:7], v[28:29], 1, s[22:23]
	global_load_dwordx4 v[6:9], v[6:7], off
.LBB0_1049:
	s_or_b64 exec, exec, s[24:25]
	global_load_dwordx4 v[78:81], v[30:31], off offset:256
	v_add_u32_e32 v14, v15, v14
	v_mul_lo_u32 v15, v14, s33
	v_mul_lo_u32 v14, v14, 12
	v_mad_i64_i32 v[16:17], s[6:7], v58, s88, 0
	v_sub_u32_e32 v14, v33, v14
	v_lshlrev_b32_e32 v18, 3, v170
	v_lshl_add_u32 v19, v170, 4, 0
	v_lshlrev_b32_e32 v173, 4, v14
	v_add_u32_e32 v174, 0, v15
	v_lshl_add_u64 v[14:15], s[20:21], 0, v[16:17]
	v_sub_u32_e32 v18, v19, v18
	v_mul_u32_u24_e32 v20, 0xd0, v32
	v_mul_u32_u24_e32 v21, 0x90, v32
	v_lshl_add_u64 v[96:97], v[14:15], 0, v[0:1]
	v_mov_b32_e32 v14, 0
	v_ashrrev_i32_e32 v91, 31, v90
	v_ashrrev_i32_e32 v87, 31, v86
	v_lshl_add_u64 v[92:93], v[28:29], 1, s[4:5]
	v_lshl_add_u64 v[94:95], v[26:27], 1, s[4:5]
	s_mov_b32 s6, 0
	v_add_u32_e32 v0, v19, v20
	v_add_u32_e32 v175, v18, v21
	v_mov_b32_e32 v15, v14
	v_mov_b32_e32 v16, v14
	v_mov_b32_e32 v17, v14
	v_mov_b32_e32 v18, v14
	v_mov_b32_e32 v19, v14
	v_mov_b32_e32 v20, v14
	v_mov_b32_e32 v21, v14
	v_mov_b32_e32 v22, v14
	v_mov_b32_e32 v23, v14
	v_mov_b32_e32 v24, v14
	v_mov_b32_e32 v25, v14
	v_mov_b32_e32 v26, v14
	v_mov_b32_e32 v27, v14
	v_mov_b32_e32 v28, v14
	v_mov_b32_e32 v29, v14
	v_mov_b32_e32 v30, v14
	v_mov_b32_e32 v31, v14
	v_mov_b32_e32 v32, v14
	v_mov_b32_e32 v33, v14
	v_mov_b32_e32 v58, v14
	v_mov_b32_e32 v59, v14
	v_mov_b32_e32 v60, v14
	v_mov_b32_e32 v61, v14
	v_mov_b32_e32 v74, v14
	v_mov_b32_e32 v75, v14
	v_mov_b32_e32 v76, v14
	v_mov_b32_e32 v77, v14
	v_mov_b32_e32 v82, v14
	v_mov_b32_e32 v83, v14
	v_mov_b32_e32 v84, v14
	v_mov_b32_e32 v85, v14
	v_mov_b32_e32 v88, v14
	v_mov_b32_e32 v89, v14
	s_branch .LBB0_1052
.LBB0_1052:
	s_add_u32 s22, s40, 0x7841000
	s_addc_u32 s23, s41, 0
	s_add_u32 s24, s40, 0x85b8180
	s_addc_u32 s25, s41, 0
	s_mov_b64 s[18:19], 0x3000
	s_mov_b64 s[20:21], 0x80
	v_lshl_add_u64 v[94:95], v[94:95], 0, s[22:23]
	v_lshl_add_u64 v[92:93], v[92:93], 0, s[22:23]
	v_lshl_add_u64 v[96:97], v[96:97], 0, s[24:25]
	s_cmp_lg_u64 s[36:37], 0
	s_cbranch_scc1 .Lmy_att_nodummy
	global_load_dwordx4 v[144:147], v[94:95], off
	global_load_dwordx4 v[144:147], v[94:95], off
.Lmy_att_nodummy:
	global_load_dwordx4 v[214:217], v[94:95], off
	global_load_dwordx4 v[222:225], v[96:97], off
	global_load_dwordx4 v[218:221], v[92:93], off
	v_lshl_add_u64 v[94:95], v[94:95], 0, s[18:19]
	v_lshl_add_u64 v[92:93], v[92:93], 0, s[18:19]
	v_lshl_add_u64 v[96:97], v[96:97], 0, s[20:21]
	global_load_dwordx4 v[226:229], v[94:95], off
	global_load_dwordx4 v[234:237], v[96:97], off
	global_load_dwordx4 v[230:233], v[92:93], off
	v_lshl_add_u64 v[94:95], v[94:95], 0, s[18:19]
	v_lshl_add_u64 v[92:93], v[92:93], 0, s[18:19]
	v_lshl_add_u64 v[96:97], v[96:97], 0, s[20:21]
	v_add_u32_e32 v169, v174, v173
	v_mov_b32_e32 v98, 0
	v_mov_b32_e32 v192, 0
	v_mov_b32_e32 v99, 0
	v_mov_b32_e32 v193, 0
.Lmy_att_loop:
	ds_read_b128 v[132:135], v0 offset:0
	ds_read_b128 v[136:139], v0 offset:64
	ds_read_b128 v[140:143], v0 offset:128
	ds_read_b128 v[156:159], v0 offset:3328
	ds_read_b128 v[160:163], v0 offset:3392
	ds_read_b128 v[164:167], v0 offset:3456
	ds_read_b128 v[238:241], v0 offset:6656
	ds_read_b128 v[242:245], v0 offset:6720
	ds_read_b128 v[246:249], v0 offset:6784
	s_waitcnt lgkmcnt(6)
	v_mfma_f32_16x16x32_bf16 v[100:103], v[132:135], v[34:37], 0
	v_mfma_f32_16x16x32_bf16 v[116:119], v[132:135], v[46:49], 0
	v_mfma_f32_16x16x32_bf16 v[100:103], v[136:139], v[38:41], v[100:103]
	v_mfma_f32_16x16x32_bf16 v[116:119], v[136:139], v[50:53], v[116:119]
	v_mfma_f32_16x16x32_bf16 v[100:103], v[140:143], v[42:45], v[100:103]
	v_mfma_f32_16x16x32_bf16 v[116:119], v[140:143], v[54:57], v[116:119]
	ds_read_b128 v[132:135], v0 offset:9984
	ds_read_b128 v[136:139], v0 offset:10048
	ds_read_b128 v[140:143], v0 offset:10112
	s_waitcnt lgkmcnt(6)
	v_mfma_f32_16x16x32_bf16 v[104:107], v[156:159], v[34:37], 0
	v_mfma_f32_16x16x32_bf16 v[120:123], v[156:159], v[46:49], 0
	v_mfma_f32_16x16x32_bf16 v[104:107], v[160:163], v[38:41], v[104:107]
	v_mfma_f32_16x16x32_bf16 v[120:123], v[160:163], v[50:53], v[120:123]
	v_mfma_f32_16x16x32_bf16 v[104:107], v[164:167], v[42:45], v[104:107]
	v_mfma_f32_16x16x32_bf16 v[120:123], v[164:167], v[54:57], v[120:123]
	ds_read_b64 v[156:157], v175 offset:26624
	ds_read_b64 v[158:159], v175 offset:26656
	ds_read_b64 v[160:161], v175 offset:28928
	ds_read_b64 v[162:163], v175 offset:28960
	ds_read_b64 v[164:165], v175 offset:31232
	ds_read_b64 v[166:167], v175 offset:31264
	s_waitcnt lgkmcnt(9)
; #define LAS __attribute__((address_space(3)))
; __device__ __forceinline__ unsigned cvt_pk_bf16(float lo, float hi) { unsigned r; asm volatile("v_cvt_pk_bf16_f32 %0, %1, %2" : "=v"(r) : "v"(lo), "v"(hi)); return r; }
; #define MFMA16(a, b, c) __builtin_amdgcn_mfma_f32_16x16x32_bf16((a), (b), (c), 0, 0, 0)
; #define ATT_LOAD(S_, tt) do { const bf16_t* kt_ = kg + (size_t)(tt) * 64 * 96; rk0[S_] = ld8(kt_ + kp0 * 8); if (kp1 < 768) rk1[S_] = ld8(kt_ + kp1 * 8); rv[S_] = ld8(vg + (size_t)vd * NKEY + (tt) * 64 + vpart * 8); } while (0)
; __device__ __forceinline__ void attn_unit(LAS unsigned char* lds, const bf16_t* QB, const bf16_t* KB, const bf16_t* VT, const bf16_t* P, bf16_t* Z0, int b, int h, int qrow0, int nkeys) {
;     ...
;         bf16x8 pf[2][2];
; #pragma unroll
;         for (int qb = 0; qb < 2; ++qb) {
;             float ps = 0.f;
; #pragma unroll
;             for (int kbk = 0; kbk < 4; ++kbk)
; #pragma unroll
;                 for (int q = 0; q < 4; ++q) { const float pv = __builtin_amdgcn_exp2f(s[qb][kbk][q]); s[qb][kbk][q] = pv; ps += pv; }
;             lsum[qb] += ps;
; #pragma unroll
;             for (int k2 = 0; k2 < 2; ++k2) { u32x4 w; w.x = cvt_pk_bf16(s[qb][2 * k2][0], s[qb][2 * k2][1]); w.y = cvt_pk_bf16(s[qb][2 * k2][2], s[qb][2 * k2][3]);
;                 w.z = cvt_pk_bf16(s[qb][2 * k2 + 1][0], s[qb][2 * k2 + 1][1]); w.w = cvt_pk_bf16(s[qb][2 * k2 + 1][2], s[qb][2 * k2 + 1][3]); pf[qb][k2] = asfrag(w); }
;         }
; #pragma unroll
;         for (int db = 0; db < 4; ++db)
; #pragma unroll
;             for (int k2 = 0; k2 < 2; ++k2) { const LAS unsigned char* vp = vb + (db * 16 + fr) * VST + (k2 * 32 + fq * 4) * 2;
;                 const u32x2 lo = *(const LAS u32x2*)vp, hi = *(const LAS u32x2*)(vp + 32);
;                 const bf16x8 vf = asfrag((u32x4){lo.x, lo.y, hi.x, hi.y});
;                 o[0][db] = MFMA16(vf, pf[0][k2], o[0][db]); o[1][db] = MFMA16(vf, pf[1][k2], o[1][db]); }
;         if (tt + 1 < ntile) ATT_STORE(half, cur ^ 1);
;         __syncthreads();
;         if (tt + 3 < ntile) ATT_LOAD(half, tt + 3);
	v_mfma_f32_16x16x32_bf16 v[108:111], v[238:241], v[34:37], 0
	v_exp_f32_e32 v100, v100
	v_exp_f32_e32 v101, v101
	v_exp_f32_e32 v102, v102
	v_exp_f32_e32 v103, v103
	v_mfma_f32_16x16x32_bf16 v[124:127], v[238:241], v[46:49], 0
	v_exp_f32_e32 v116, v116
	v_exp_f32_e32 v117, v117
	v_exp_f32_e32 v118, v118
	v_exp_f32_e32 v119, v119
	v_mfma_f32_16x16x32_bf16 v[108:111], v[242:245], v[38:41], v[108:111]
	v_add_f32_e32 v98, v98, v100
	v_add_f32_e32 v99, v99, v101
	v_cvt_pk_bf16_f32 v176, v100, v101
	v_mfma_f32_16x16x32_bf16 v[124:127], v[242:245], v[50:53], v[124:127]
	v_add_f32_e32 v98, v98, v102
	v_add_f32_e32 v99, v99, v103
	v_cvt_pk_bf16_f32 v177, v102, v103
	v_mfma_f32_16x16x32_bf16 v[108:111], v[246:249], v[42:45], v[108:111]
	v_add_f32_e32 v192, v192, v116
	v_add_f32_e32 v193, v193, v117
	v_cvt_pk_bf16_f32 v184, v116, v117
	v_mfma_f32_16x16x32_bf16 v[124:127], v[246:249], v[54:57], v[124:127]
	v_add_f32_e32 v192, v192, v118
	v_add_f32_e32 v193, v193, v119
	v_cvt_pk_bf16_f32 v185, v118, v119
	ds_read_b64 v[238:239], v175 offset:33536
	ds_read_b64 v[240:241], v175 offset:33568
	ds_read_b64 v[242:243], v175 offset:26688
	ds_read_b64 v[244:245], v175 offset:26720
	ds_read_b64 v[246:247], v175 offset:28992
	ds_read_b64 v[248:249], v175 offset:29024
	s_waitcnt lgkmcnt(12)
	v_mfma_f32_16x16x32_bf16 v[112:115], v[132:135], v[34:37], 0
	v_exp_f32_e32 v104, v104
	v_exp_f32_e32 v105, v105
	v_exp_f32_e32 v106, v106
	v_exp_f32_e32 v107, v107
	v_mfma_f32_16x16x32_bf16 v[128:131], v[132:135], v[46:49], 0
	v_exp_f32_e32 v120, v120
	v_exp_f32_e32 v121, v121
	v_exp_f32_e32 v122, v122
	v_exp_f32_e32 v123, v123
	v_mfma_f32_16x16x32_bf16 v[112:115], v[136:139], v[38:41], v[112:115]
	v_add_f32_e32 v98, v98, v104
	v_add_f32_e32 v99, v99, v105
	v_cvt_pk_bf16_f32 v178, v104, v105
	v_mfma_f32_16x16x32_bf16 v[128:131], v[136:139], v[50:53], v[128:131]
	v_add_f32_e32 v98, v98, v106
	v_add_f32_e32 v99, v99, v107
	v_cvt_pk_bf16_f32 v179, v106, v107
	v_mfma_f32_16x16x32_bf16 v[112:115], v[140:143], v[42:45], v[112:115]
	v_add_f32_e32 v192, v192, v120
	v_add_f32_e32 v193, v193, v121
	v_cvt_pk_bf16_f32 v186, v120, v121
	v_mfma_f32_16x16x32_bf16 v[128:131], v[140:143], v[54:57], v[128:131]
	v_add_f32_e32 v192, v192, v122
	v_add_f32_e32 v193, v193, v123
	v_cvt_pk_bf16_f32 v187, v122, v123
	s_waitcnt lgkmcnt(6)
	ds_read_b64 v[132:133], v175 offset:31296
	ds_read_b64 v[134:135], v175 offset:31328
	ds_read_b64 v[136:137], v175 offset:33600
	ds_read_b64 v[138:139], v175 offset:33632
	v_mfma_f32_16x16x32_bf16 v[82:85], v[156:159], v[176:179], v[82:85]
	v_exp_f32_e32 v108, v108
	v_exp_f32_e32 v109, v109
	v_exp_f32_e32 v110, v110
	v_exp_f32_e32 v111, v111
	v_exp_f32_e32 v124, v124
	v_mfma_f32_16x16x32_bf16 v[26:29], v[156:159], v[184:187], v[26:29]
	v_exp_f32_e32 v125, v125
	v_exp_f32_e32 v126, v126
	v_exp_f32_e32 v127, v127
	v_add_f32_e32 v98, v98, v108
	v_add_f32_e32 v99, v99, v109
	v_mfma_f32_16x16x32_bf16 v[74:77], v[160:163], v[176:179], v[74:77]
	v_cvt_pk_bf16_f32 v180, v108, v109
	v_add_f32_e32 v98, v98, v110
	v_add_f32_e32 v99, v99, v111
	v_cvt_pk_bf16_f32 v181, v110, v111
	v_add_f32_e32 v192, v192, v124
	v_mfma_f32_16x16x32_bf16 v[22:25], v[160:163], v[184:187], v[22:25]
	v_add_f32_e32 v193, v193, v125
	v_cvt_pk_bf16_f32 v188, v124, v125
	v_add_f32_e32 v192, v192, v126
	v_add_f32_e32 v193, v193, v127
	v_cvt_pk_bf16_f32 v189, v126, v127
	v_mfma_f32_16x16x32_bf16 v[58:61], v[164:167], v[176:179], v[58:61]
	v_exp_f32_e32 v112, v112
	v_exp_f32_e32 v113, v113
	v_exp_f32_e32 v114, v114
	v_exp_f32_e32 v115, v115
	v_exp_f32_e32 v128, v128
	v_mfma_f32_16x16x32_bf16 v[18:21], v[164:167], v[184:187], v[18:21]
	v_exp_f32_e32 v129, v129
	v_exp_f32_e32 v130, v130
	v_exp_f32_e32 v131, v131
	v_add_f32_e32 v98, v98, v112
	v_add_f32_e32 v99, v99, v113
	s_waitcnt lgkmcnt(8)
	v_mfma_f32_16x16x32_bf16 v[30:33], v[238:241], v[176:179], v[30:33]
	v_cvt_pk_bf16_f32 v182, v112, v113
	v_add_f32_e32 v98, v98, v114
	v_add_f32_e32 v99, v99, v115
	v_cvt_pk_bf16_f32 v183, v114, v115
	v_add_f32_e32 v192, v192, v128
	v_mfma_f32_16x16x32_bf16 v[14:17], v[238:241], v[184:187], v[14:17]
	v_add_f32_e32 v193, v193, v129
	v_cvt_pk_bf16_f32 v190, v128, v129
	v_add_f32_e32 v192, v192, v130
	v_add_f32_e32 v193, v193, v131
	v_cvt_pk_bf16_f32 v191, v130, v131
	s_waitcnt lgkmcnt(0)
	v_mfma_f32_16x16x32_bf16 v[82:85], v[242:245], v[180:183], v[82:85]
	v_mfma_f32_16x16x32_bf16 v[26:29], v[242:245], v[188:191], v[26:29]
	s_waitcnt vmcnt(9)
	s_cmp_lt_u32 s6, 32
	s_cbranch_scc1 .Lmy_att_ok0
	s_waitcnt vmcnt(0)
.Lmy_att_ok0:
	ds_write_b128 v171, v[62:65] offset:13312
	ds_write_b128 v172, v[70:73] offset:35840
	s_and_saveexec_b64 s[4:5], s[36:37]
	s_cbranch_execz .Lmy_att_w0
	ds_write_b128 v169, v[2:5] offset:13312
.Lmy_att_w0:
	s_or_b64 exec, exec, s[4:5]
	v_mfma_f32_16x16x32_bf16 v[74:77], v[246:249], v[180:183], v[74:77]
	v_mfma_f32_16x16x32_bf16 v[22:25], v[246:249], v[188:191], v[22:25]
	v_mfma_f32_16x16x32_bf16 v[58:61], v[132:135], v[180:183], v[58:61]
	v_mfma_f32_16x16x32_bf16 v[18:21], v[132:135], v[188:191], v[18:21]
	s_cmp_gt_u32 s6, 28
	s_cbranch_scc1 .Lmy_att_nl0
	global_load_dwordx4 v[62:65], v[94:95], off
	global_load_dwordx4 v[70:73], v[96:97], off
	global_load_dwordx4 v[2:5], v[92:93], off
	v_lshl_add_u64 v[94:95], v[94:95], 0, s[18:19]
	v_lshl_add_u64 v[92:93], v[92:93], 0, s[18:19]
	v_lshl_add_u64 v[96:97], v[96:97], 0, s[20:21]
; #define LAS __attribute__((address_space(3)))
; __device__ __forceinline__ unsigned cvt_pk_bf16(float lo, float hi) { unsigned r; asm volatile("v_cvt_pk_bf16_f32 %0, %1, %2" : "=v"(r) : "v"(lo), "v"(hi)); return r; }
; #define MFMA16(a, b, c) __builtin_amdgcn_mfma_f32_16x16x32_bf16((a), (b), (c), 0, 0, 0)
; __device__ __forceinline__ void attn_unit(LAS unsigned char* lds, const bf16_t* QB, const bf16_t* KB, const bf16_t* VT, const bf16_t* P, bf16_t* Z0, int b, int h, int qrow0, int nkeys) {
;     ...
;       for (int half = 0; half < 2; ++half) { const int tt = t2 + half; if (tt < ntile) {
;         const int cur = half;
;         const LAS unsigned char* kb = lds + cur * KBUF; const LAS unsigned char* vb = lds + VOFF + cur * VBUF;
;         f32x4 s[2][4];
; #pragma unroll
;         for (int kbk = 0; kbk < 4; ++kbk) { s[0][kbk] = (f32x4){0.f, 0.f, 0.f, 0.f}; s[1][kbk] = s[0][kbk];
; #pragma unroll
;             for (int ks = 0; ks < 3; ++ks) { const bf16x8 kf = *(const LAS bf16x8*)(kb + (kbk * 16 + fr) * KST + ks * 64 + fq * 16);
;                 s[0][kbk] = MFMA16(kf, qf[0][ks], s[0][kbk]); s[1][kbk] = MFMA16(kf, qf[1][ks], s[1][kbk]); } }
;         bf16x8 pf[2][2];
; #pragma unroll
;         for (int qb = 0; qb < 2; ++qb) {
;             float ps = 0.f;
; #pragma unroll
;             for (int kbk = 0; kbk < 4; ++kbk)
; #pragma unroll
;                 for (int q = 0; q < 4; ++q) { const float pv = __builtin_amdgcn_exp2f(s[qb][kbk][q]); s[qb][kbk][q] = pv; ps += pv; }
;             lsum[qb] += ps;
; #pragma unroll
;             for (int k2 = 0; k2 < 2; ++k2) { u32x4 w; w.x = cvt_pk_bf16(s[qb][2 * k2][0], s[qb][2 * k2][1]); w.y = cvt_pk_bf16(s[qb][2 * k2][2], s[qb][2 * k2][3]);
;                 w.z = cvt_pk_bf16(s[qb][2 * k2 + 1][0], s[qb][2 * k2 + 1][1]); w.w = cvt_pk_bf16(s[qb][2 * k2 + 1][2], s[qb][2 * k2 + 1][3]); pf[qb][k2] = asfrag(w); }
;         }
; #pragma unroll
;         for (int db = 0; db < 4; ++db)
; #pragma unroll
;             for (int k2 = 0; k2 < 2; ++k2) { const LAS unsigned char* vp = vb + (db * 16 + fr) * VST + (k2 * 32 + fq * 4) * 2;
;                 const u32x2 lo = *(const LAS u32x2*)vp, hi = *(const LAS u32x2*)(vp + 32);
;                 const bf16x8 vf = asfrag((u32x4){lo.x, lo.y, hi.x, hi.y});
;                 o[0][db] = MFMA16(vf, pf[0][k2], o[0][db]); o[1][db] = MFMA16(vf, pf[1][k2], o[1][db]); }
.Lmy_att_nl0:
	v_mfma_f32_16x16x32_bf16 v[30:33], v[136:139], v[180:183], v[30:33]
	v_mfma_f32_16x16x32_bf16 v[14:17], v[136:139], v[188:191], v[14:17]
	s_waitcnt lgkmcnt(0)
	s_barrier
	ds_read_b128 v[132:135], v0 offset:13312
	ds_read_b128 v[136:139], v0 offset:13376
	ds_read_b128 v[140:143], v0 offset:13440
	ds_read_b128 v[156:159], v0 offset:16640
	ds_read_b128 v[160:163], v0 offset:16704
	ds_read_b128 v[164:167], v0 offset:16768
	ds_read_b128 v[238:241], v0 offset:19968
	ds_read_b128 v[242:245], v0 offset:20032
	ds_read_b128 v[246:249], v0 offset:20096
	s_waitcnt lgkmcnt(6)
	v_mfma_f32_16x16x32_bf16 v[100:103], v[132:135], v[34:37], 0
	v_mfma_f32_16x16x32_bf16 v[116:119], v[132:135], v[46:49], 0
	v_mfma_f32_16x16x32_bf16 v[100:103], v[136:139], v[38:41], v[100:103]
	v_mfma_f32_16x16x32_bf16 v[116:119], v[136:139], v[50:53], v[116:119]
	v_mfma_f32_16x16x32_bf16 v[100:103], v[140:143], v[42:45], v[100:103]
	v_mfma_f32_16x16x32_bf16 v[116:119], v[140:143], v[54:57], v[116:119]
	ds_read_b128 v[132:135], v0 offset:23296
	ds_read_b128 v[136:139], v0 offset:23360
	ds_read_b128 v[140:143], v0 offset:23424
	s_waitcnt lgkmcnt(6)
	v_mfma_f32_16x16x32_bf16 v[104:107], v[156:159], v[34:37], 0
	v_mfma_f32_16x16x32_bf16 v[120:123], v[156:159], v[46:49], 0
	v_mfma_f32_16x16x32_bf16 v[104:107], v[160:163], v[38:41], v[104:107]
	v_mfma_f32_16x16x32_bf16 v[120:123], v[160:163], v[50:53], v[120:123]
	v_mfma_f32_16x16x32_bf16 v[104:107], v[164:167], v[42:45], v[104:107]
	v_mfma_f32_16x16x32_bf16 v[120:123], v[164:167], v[54:57], v[120:123]
	ds_read_b64 v[156:157], v175 offset:35840
	ds_read_b64 v[158:159], v175 offset:35872
	ds_read_b64 v[160:161], v175 offset:38144
	ds_read_b64 v[162:163], v175 offset:38176
	ds_read_b64 v[164:165], v175 offset:40448
	ds_read_b64 v[166:167], v175 offset:40480
	s_waitcnt lgkmcnt(9)
	v_mfma_f32_16x16x32_bf16 v[108:111], v[238:241], v[34:37], 0
	v_exp_f32_e32 v100, v100
	v_exp_f32_e32 v101, v101
	v_exp_f32_e32 v102, v102
	v_exp_f32_e32 v103, v103
	v_mfma_f32_16x16x32_bf16 v[124:127], v[238:241], v[46:49], 0
	v_exp_f32_e32 v116, v116
	v_exp_f32_e32 v117, v117
	v_exp_f32_e32 v118, v118
	v_exp_f32_e32 v119, v119
	v_mfma_f32_16x16x32_bf16 v[108:111], v[242:245], v[38:41], v[108:111]
	v_add_f32_e32 v98, v98, v100
	v_add_f32_e32 v99, v99, v101
	v_cvt_pk_bf16_f32 v176, v100, v101
	v_mfma_f32_16x16x32_bf16 v[124:127], v[242:245], v[50:53], v[124:127]
	v_add_f32_e32 v98, v98, v102
	v_add_f32_e32 v99, v99, v103
	v_cvt_pk_bf16_f32 v177, v102, v103
	v_mfma_f32_16x16x32_bf16 v[108:111], v[246:249], v[42:45], v[108:111]
	v_add_f32_e32 v192, v192, v116
	v_add_f32_e32 v193, v193, v117
	v_cvt_pk_bf16_f32 v184, v116, v117
	v_mfma_f32_16x16x32_bf16 v[124:127], v[246:249], v[54:57], v[124:127]
	v_add_f32_e32 v192, v192, v118
	v_add_f32_e32 v193, v193, v119
	v_cvt_pk_bf16_f32 v185, v118, v119
	ds_read_b64 v[238:239], v175 offset:42752
	ds_read_b64 v[240:241], v175 offset:42784
	ds_read_b64 v[242:243], v175 offset:35904
	ds_read_b64 v[244:245], v175 offset:35936
	ds_read_b64 v[246:247], v175 offset:38208
	ds_read_b64 v[248:249], v175 offset:38240
	s_waitcnt lgkmcnt(12)
	v_mfma_f32_16x16x32_bf16 v[112:115], v[132:135], v[34:37], 0
	v_exp_f32_e32 v104, v104
	v_exp_f32_e32 v105, v105
	v_exp_f32_e32 v106, v106
	v_exp_f32_e32 v107, v107
	v_mfma_f32_16x16x32_bf16 v[128:131], v[132:135], v[46:49], 0
	v_exp_f32_e32 v120, v120
	v_exp_f32_e32 v121, v121
	v_exp_f32_e32 v122, v122
	v_exp_f32_e32 v123, v123
	v_mfma_f32_16x16x32_bf16 v[112:115], v[136:139], v[38:41], v[112:115]
	v_add_f32_e32 v98, v98, v104
	v_add_f32_e32 v99, v99, v105
	v_cvt_pk_bf16_f32 v178, v104, v105
	v_mfma_f32_16x16x32_bf16 v[128:131], v[136:139], v[50:53], v[128:131]
	v_add_f32_e32 v98, v98, v106
	v_add_f32_e32 v99, v99, v107
	v_cvt_pk_bf16_f32 v179, v106, v107
	v_mfma_f32_16x16x32_bf16 v[112:115], v[140:143], v[42:45], v[112:115]
	v_add_f32_e32 v192, v192, v120
	v_add_f32_e32 v193, v193, v121
	v_cvt_pk_bf16_f32 v186, v120, v121
	v_mfma_f32_16x16x32_bf16 v[128:131], v[140:143], v[54:57], v[128:131]
	v_add_f32_e32 v192, v192, v122
	v_add_f32_e32 v193, v193, v123
	v_cvt_pk_bf16_f32 v187, v122, v123
	s_waitcnt lgkmcnt(6)
	ds_read_b64 v[132:133], v175 offset:40512
	ds_read_b64 v[134:135], v175 offset:40544
	ds_read_b64 v[136:137], v175 offset:42816
	ds_read_b64 v[138:139], v175 offset:42848
	v_mfma_f32_16x16x32_bf16 v[82:85], v[156:159], v[176:179], v[82:85]
	v_exp_f32_e32 v108, v108
	v_exp_f32_e32 v109, v109
	v_exp_f32_e32 v110, v110
	v_exp_f32_e32 v111, v111
	v_exp_f32_e32 v124, v124
	v_mfma_f32_16x16x32_bf16 v[26:29], v[156:159], v[184:187], v[26:29]
	v_exp_f32_e32 v125, v125
	v_exp_f32_e32 v126, v126
	v_exp_f32_e32 v127, v127
	v_add_f32_e32 v98, v98, v108
	v_add_f32_e32 v99, v99, v109
	v_mfma_f32_16x16x32_bf16 v[74:77], v[160:163], v[176:179], v[74:77]
	v_cvt_pk_bf16_f32 v180, v108, v109
	v_add_f32_e32 v98, v98, v110
	v_add_f32_e32 v99, v99, v111
	v_cvt_pk_bf16_f32 v181, v110, v111
	v_add_f32_e32 v192, v192, v124
	v_mfma_f32_16x16x32_bf16 v[22:25], v[160:163], v[184:187], v[22:25]
	v_add_f32_e32 v193, v193, v125
	v_cvt_pk_bf16_f32 v188, v124, v125
	v_add_f32_e32 v192, v192, v126
	v_add_f32_e32 v193, v193, v127
	v_cvt_pk_bf16_f32 v189, v126, v127
	v_mfma_f32_16x16x32_bf16 v[58:61], v[164:167], v[176:179], v[58:61]
	v_exp_f32_e32 v112, v112
	v_exp_f32_e32 v113, v113
	v_exp_f32_e32 v114, v114
	v_exp_f32_e32 v115, v115
	v_exp_f32_e32 v128, v128
	v_mfma_f32_16x16x32_bf16 v[18:21], v[164:167], v[184:187], v[18:21]
	v_exp_f32_e32 v129, v129
	v_exp_f32_e32 v130, v130
	v_exp_f32_e32 v131, v131
	v_add_f32_e32 v98, v98, v112
	v_add_f32_e32 v99, v99, v113
	s_waitcnt lgkmcnt(8)
	v_mfma_f32_16x16x32_bf16 v[30:33], v[238:241], v[176:179], v[30:33]
	v_cvt_pk_bf16_f32 v182, v112, v113
	v_add_f32_e32 v98, v98, v114
	v_add_f32_e32 v99, v99, v115
	v_cvt_pk_bf16_f32 v183, v114, v115
	v_add_f32_e32 v192, v192, v128
	v_mfma_f32_16x16x32_bf16 v[14:17], v[238:241], v[184:187], v[14:17]
	v_add_f32_e32 v193, v193, v129
	v_cvt_pk_bf16_f32 v190, v128, v129
	v_add_f32_e32 v192, v192, v130
	v_add_f32_e32 v193, v193, v131
	v_cvt_pk_bf16_f32 v191, v130, v131
	s_waitcnt lgkmcnt(0)
	v_mfma_f32_16x16x32_bf16 v[82:85], v[242:245], v[180:183], v[82:85]
	v_mfma_f32_16x16x32_bf16 v[26:29], v[242:245], v[188:191], v[26:29]
	s_waitcnt vmcnt(9)
	s_cmp_lt_u32 s6, 32
	s_cbranch_scc1 .Lmy_att_ok1
	s_waitcnt vmcnt(0)
; #define LAS __attribute__((address_space(3)))
; #define MFMA16(a, b, c) __builtin_amdgcn_mfma_f32_16x16x32_bf16((a), (b), (c), 0, 0, 0)
; __device__ __forceinline__ void attn_unit(LAS unsigned char* lds, const bf16_t* QB, const bf16_t* KB, const bf16_t* VT, const bf16_t* P, bf16_t* Z0, int b, int h, int qrow0, int nkeys) {
;     ...
;       for (int half = 0; half < 2; ++half) { const int tt = t2 + half; if (tt < ntile) {
;         const int cur = half;
;         const LAS unsigned char* kb = lds + cur * KBUF; const LAS unsigned char* vb = lds + VOFF + cur * VBUF;
;         f32x4 s[2][4];
; #pragma unroll
;         for (int kbk = 0; kbk < 4; ++kbk) { s[0][kbk] = (f32x4){0.f, 0.f, 0.f, 0.f}; s[1][kbk] = s[0][kbk];
; #pragma unroll
;             for (int ks = 0; ks < 3; ++ks) { const bf16x8 kf = *(const LAS bf16x8*)(kb + (kbk * 16 + fr) * KST + ks * 64 + fq * 16);
;                 s[0][kbk] = MFMA16(kf, qf[0][ks], s[0][kbk]); s[1][kbk] = MFMA16(kf, qf[1][ks], s[1][kbk]); } }
;         bf16x8 pf[2][2];
; #pragma unroll
;         for (int qb = 0; qb < 2; ++qb) {
;             float ps = 0.f;
; #pragma unroll
;             for (int kbk = 0; kbk < 4; ++kbk)
; #pragma unroll
;                 for (int q = 0; q < 4; ++q) { const float pv = __builtin_amdgcn_exp2f(s[qb][kbk][q]); s[qb][kbk][q] = pv; ps += pv; }
;             lsum[qb] += ps;
; #pragma unroll
;             for (int k2 = 0; k2 < 2; ++k2) { u32x4 w; w.x = cvt_pk_bf16(s[qb][2 * k2][0], s[qb][2 * k2][1]); w.y = cvt_pk_bf16(s[qb][2 * k2][2], s[qb][2 * k2][3]);
;                 w.z = cvt_pk_bf16(s[qb][2 * k2 + 1][0], s[qb][2 * k2 + 1][1]); w.w = cvt_pk_bf16(s[qb][2 * k2 + 1][2], s[qb][2 * k2 + 1][3]); pf[qb][k2] = asfrag(w); }
;         }
; #pragma unroll
;         for (int db = 0; db < 4; ++db)
; #pragma unroll
;             for (int k2 = 0; k2 < 2; ++k2) { const LAS unsigned char* vp = vb + (db * 16 + fr) * VST + (k2 * 32 + fq * 4) * 2;
;                 const u32x2 lo = *(const LAS u32x2*)vp, hi = *(const LAS u32x2*)(vp + 32);
;                 const bf16x8 vf = asfrag((u32x4){lo.x, lo.y, hi.x, hi.y});
;                 o[0][db] = MFMA16(vf, pf[0][k2], o[0][db]); o[1][db] = MFMA16(vf, pf[1][k2], o[1][db]); }
;         if (tt + 1 < ntile) ATT_STORE(half, cur ^ 1);
;         __syncthreads();
;         if (tt + 3 < ntile) ATT_LOAD(half, tt + 3);
.Lmy_att_ok1:
	ds_write_b128 v171, v[66:69]
	ds_write_b128 v172, v[78:81] offset:26624
	s_and_saveexec_b64 s[4:5], s[36:37]
	s_cbranch_execz .Lmy_att_w1
	ds_write_b128 v169, v[6:9]
.Lmy_att_w1:
	s_or_b64 exec, exec, s[4:5]
	v_mfma_f32_16x16x32_bf16 v[74:77], v[246:249], v[180:183], v[74:77]
	v_mfma_f32_16x16x32_bf16 v[22:25], v[246:249], v[188:191], v[22:25]
	v_mfma_f32_16x16x32_bf16 v[58:61], v[132:135], v[180:183], v[58:61]
	v_mfma_f32_16x16x32_bf16 v[18:21], v[132:135], v[188:191], v[18:21]
	s_cmp_gt_u32 s6, 28
	s_cbranch_scc1 .Lmy_att_nl1
	global_load_dwordx4 v[66:69], v[94:95], off
	global_load_dwordx4 v[78:81], v[96:97], off
	global_load_dwordx4 v[6:9], v[92:93], off
	v_lshl_add_u64 v[94:95], v[94:95], 0, s[18:19]
	v_lshl_add_u64 v[92:93], v[92:93], 0, s[18:19]
	v_lshl_add_u64 v[96:97], v[96:97], 0, s[20:21]
.Lmy_att_nl1:
	v_mfma_f32_16x16x32_bf16 v[30:33], v[136:139], v[180:183], v[30:33]
	v_mfma_f32_16x16x32_bf16 v[14:17], v[136:139], v[188:191], v[14:17]
	s_waitcnt lgkmcnt(0)
	s_barrier
	ds_read_b128 v[132:135], v0 offset:0
	ds_read_b128 v[136:139], v0 offset:64
	ds_read_b128 v[140:143], v0 offset:128
	ds_read_b128 v[156:159], v0 offset:3328
	ds_read_b128 v[160:163], v0 offset:3392
	ds_read_b128 v[164:167], v0 offset:3456
	ds_read_b128 v[238:241], v0 offset:6656
	ds_read_b128 v[242:245], v0 offset:6720
	ds_read_b128 v[246:249], v0 offset:6784
	s_waitcnt lgkmcnt(6)
	v_mfma_f32_16x16x32_bf16 v[100:103], v[132:135], v[34:37], 0
	v_mfma_f32_16x16x32_bf16 v[116:119], v[132:135], v[46:49], 0
	v_mfma_f32_16x16x32_bf16 v[100:103], v[136:139], v[38:41], v[100:103]
	v_mfma_f32_16x16x32_bf16 v[116:119], v[136:139], v[50:53], v[116:119]
	v_mfma_f32_16x16x32_bf16 v[100:103], v[140:143], v[42:45], v[100:103]
	v_mfma_f32_16x16x32_bf16 v[116:119], v[140:143], v[54:57], v[116:119]
	ds_read_b128 v[132:135], v0 offset:9984
	ds_read_b128 v[136:139], v0 offset:10048
	ds_read_b128 v[140:143], v0 offset:10112
	s_waitcnt lgkmcnt(6)
	v_mfma_f32_16x16x32_bf16 v[104:107], v[156:159], v[34:37], 0
	v_mfma_f32_16x16x32_bf16 v[120:123], v[156:159], v[46:49], 0
	v_mfma_f32_16x16x32_bf16 v[104:107], v[160:163], v[38:41], v[104:107]
	v_mfma_f32_16x16x32_bf16 v[120:123], v[160:163], v[50:53], v[120:123]
	v_mfma_f32_16x16x32_bf16 v[104:107], v[164:167], v[42:45], v[104:107]
	v_mfma_f32_16x16x32_bf16 v[120:123], v[164:167], v[54:57], v[120:123]
	ds_read_b64 v[156:157], v175 offset:26624
	ds_read_b64 v[158:159], v175 offset:26656
	ds_read_b64 v[160:161], v175 offset:28928
	ds_read_b64 v[162:163], v175 offset:28960
	ds_read_b64 v[164:165], v175 offset:31232
	ds_read_b64 v[166:167], v175 offset:31264
	s_waitcnt lgkmcnt(9)
	v_mfma_f32_16x16x32_bf16 v[108:111], v[238:241], v[34:37], 0
	v_exp_f32_e32 v100, v100
	v_exp_f32_e32 v101, v101
	v_exp_f32_e32 v102, v102
	v_exp_f32_e32 v103, v103
	v_mfma_f32_16x16x32_bf16 v[124:127], v[238:241], v[46:49], 0
	v_exp_f32_e32 v116, v116
	v_exp_f32_e32 v117, v117
	v_exp_f32_e32 v118, v118
	v_exp_f32_e32 v119, v119
	v_mfma_f32_16x16x32_bf16 v[108:111], v[242:245], v[38:41], v[108:111]
	v_add_f32_e32 v98, v98, v100
	v_add_f32_e32 v99, v99, v101
	v_cvt_pk_bf16_f32 v176, v100, v101
	v_mfma_f32_16x16x32_bf16 v[124:127], v[242:245], v[50:53], v[124:127]
	v_add_f32_e32 v98, v98, v102
	v_add_f32_e32 v99, v99, v103
	v_cvt_pk_bf16_f32 v177, v102, v103
	v_mfma_f32_16x16x32_bf16 v[108:111], v[246:249], v[42:45], v[108:111]
	v_add_f32_e32 v192, v192, v116
	v_add_f32_e32 v193, v193, v117
	v_cvt_pk_bf16_f32 v184, v116, v117
	v_mfma_f32_16x16x32_bf16 v[124:127], v[246:249], v[54:57], v[124:127]
	v_add_f32_e32 v192, v192, v118
	v_add_f32_e32 v193, v193, v119
	v_cvt_pk_bf16_f32 v185, v118, v119
	ds_read_b64 v[238:239], v175 offset:33536
	ds_read_b64 v[240:241], v175 offset:33568
	ds_read_b64 v[242:243], v175 offset:26688
	ds_read_b64 v[244:245], v175 offset:26720
	ds_read_b64 v[246:247], v175 offset:28992
	ds_read_b64 v[248:249], v175 offset:29024
	s_waitcnt lgkmcnt(12)
	v_mfma_f32_16x16x32_bf16 v[112:115], v[132:135], v[34:37], 0
	v_exp_f32_e32 v104, v104
	v_exp_f32_e32 v105, v105
	v_exp_f32_e32 v106, v106
	v_exp_f32_e32 v107, v107
	v_mfma_f32_16x16x32_bf16 v[128:131], v[132:135], v[46:49], 0
	v_exp_f32_e32 v120, v120
	v_exp_f32_e32 v121, v121
	v_exp_f32_e32 v122, v122
	v_exp_f32_e32 v123, v123
	v_mfma_f32_16x16x32_bf16 v[112:115], v[136:139], v[38:41], v[112:115]
	v_add_f32_e32 v98, v98, v104
	v_add_f32_e32 v99, v99, v105
	v_cvt_pk_bf16_f32 v178, v104, v105
	v_mfma_f32_16x16x32_bf16 v[128:131], v[136:139], v[50:53], v[128:131]
	v_add_f32_e32 v98, v98, v106
	v_add_f32_e32 v99, v99, v107
	v_cvt_pk_bf16_f32 v179, v106, v107
	v_mfma_f32_16x16x32_bf16 v[112:115], v[140:143], v[42:45], v[112:115]
	v_add_f32_e32 v192, v192, v120
	v_add_f32_e32 v193, v193, v121
	v_cvt_pk_bf16_f32 v186, v120, v121
	v_mfma_f32_16x16x32_bf16 v[128:131], v[140:143], v[54:57], v[128:131]
	v_add_f32_e32 v192, v192, v122
	v_add_f32_e32 v193, v193, v123
	v_cvt_pk_bf16_f32 v187, v122, v123
	s_waitcnt lgkmcnt(6)
; #define LAS __attribute__((address_space(3)))
; __device__ __forceinline__ unsigned cvt_pk_bf16(float lo, float hi) { unsigned r; asm volatile("v_cvt_pk_bf16_f32 %0, %1, %2" : "=v"(r) : "v"(lo), "v"(hi)); return r; }
; #define MFMA16(a, b, c) __builtin_amdgcn_mfma_f32_16x16x32_bf16((a), (b), (c), 0, 0, 0)
; #define ATT_LOAD(S_, tt) do { const bf16_t* kt_ = kg + (size_t)(tt) * 64 * 96; rk0[S_] = ld8(kt_ + kp0 * 8); if (kp1 < 768) rk1[S_] = ld8(kt_ + kp1 * 8); rv[S_] = ld8(vg + (size_t)vd * NKEY + (tt) * 64 + vpart * 8); } while (0)
; __device__ __forceinline__ void attn_unit(LAS unsigned char* lds, const bf16_t* QB, const bf16_t* KB, const bf16_t* VT, const bf16_t* P, bf16_t* Z0, int b, int h, int qrow0, int nkeys) {
;     ...
;         bf16x8 pf[2][2];
; #pragma unroll
;         for (int qb = 0; qb < 2; ++qb) {
;             float ps = 0.f;
; #pragma unroll
;             for (int kbk = 0; kbk < 4; ++kbk)
; #pragma unroll
;                 for (int q = 0; q < 4; ++q) { const float pv = __builtin_amdgcn_exp2f(s[qb][kbk][q]); s[qb][kbk][q] = pv; ps += pv; }
;             lsum[qb] += ps;
; #pragma unroll
;             for (int k2 = 0; k2 < 2; ++k2) { u32x4 w; w.x = cvt_pk_bf16(s[qb][2 * k2][0], s[qb][2 * k2][1]); w.y = cvt_pk_bf16(s[qb][2 * k2][2], s[qb][2 * k2][3]);
;                 w.z = cvt_pk_bf16(s[qb][2 * k2 + 1][0], s[qb][2 * k2 + 1][1]); w.w = cvt_pk_bf16(s[qb][2 * k2 + 1][2], s[qb][2 * k2 + 1][3]); pf[qb][k2] = asfrag(w); }
;         }
; #pragma unroll
;         for (int db = 0; db < 4; ++db)
; #pragma unroll
;             for (int k2 = 0; k2 < 2; ++k2) { const LAS unsigned char* vp = vb + (db * 16 + fr) * VST + (k2 * 32 + fq * 4) * 2;
;                 const u32x2 lo = *(const LAS u32x2*)vp, hi = *(const LAS u32x2*)(vp + 32);
;                 const bf16x8 vf = asfrag((u32x4){lo.x, lo.y, hi.x, hi.y});
;                 o[0][db] = MFMA16(vf, pf[0][k2], o[0][db]); o[1][db] = MFMA16(vf, pf[1][k2], o[1][db]); }
;         if (tt + 1 < ntile) ATT_STORE(half, cur ^ 1);
;         __syncthreads();
;         if (tt + 3 < ntile) ATT_LOAD(half, tt + 3);
	ds_read_b64 v[132:133], v175 offset:31296
	ds_read_b64 v[134:135], v175 offset:31328
	ds_read_b64 v[136:137], v175 offset:33600
	ds_read_b64 v[138:139], v175 offset:33632
	v_mfma_f32_16x16x32_bf16 v[82:85], v[156:159], v[176:179], v[82:85]
	v_exp_f32_e32 v108, v108
	v_exp_f32_e32 v109, v109
	v_exp_f32_e32 v110, v110
	v_exp_f32_e32 v111, v111
	v_exp_f32_e32 v124, v124
	v_mfma_f32_16x16x32_bf16 v[26:29], v[156:159], v[184:187], v[26:29]
	v_exp_f32_e32 v125, v125
	v_exp_f32_e32 v126, v126
	v_exp_f32_e32 v127, v127
	v_add_f32_e32 v98, v98, v108
	v_add_f32_e32 v99, v99, v109
	v_mfma_f32_16x16x32_bf16 v[74:77], v[160:163], v[176:179], v[74:77]
	v_cvt_pk_bf16_f32 v180, v108, v109
	v_add_f32_e32 v98, v98, v110
	v_add_f32_e32 v99, v99, v111
	v_cvt_pk_bf16_f32 v181, v110, v111
	v_add_f32_e32 v192, v192, v124
	v_mfma_f32_16x16x32_bf16 v[22:25], v[160:163], v[184:187], v[22:25]
	v_add_f32_e32 v193, v193, v125
	v_cvt_pk_bf16_f32 v188, v124, v125
	v_add_f32_e32 v192, v192, v126
	v_add_f32_e32 v193, v193, v127
	v_cvt_pk_bf16_f32 v189, v126, v127
	v_mfma_f32_16x16x32_bf16 v[58:61], v[164:167], v[176:179], v[58:61]
	v_exp_f32_e32 v112, v112
	v_exp_f32_e32 v113, v113
	v_exp_f32_e32 v114, v114
	v_exp_f32_e32 v115, v115
	v_exp_f32_e32 v128, v128
	v_mfma_f32_16x16x32_bf16 v[18:21], v[164:167], v[184:187], v[18:21]
	v_exp_f32_e32 v129, v129
	v_exp_f32_e32 v130, v130
	v_exp_f32_e32 v131, v131
	v_add_f32_e32 v98, v98, v112
	v_add_f32_e32 v99, v99, v113
	s_waitcnt lgkmcnt(8)
	v_mfma_f32_16x16x32_bf16 v[30:33], v[238:241], v[176:179], v[30:33]
	v_cvt_pk_bf16_f32 v182, v112, v113
	v_add_f32_e32 v98, v98, v114
	v_add_f32_e32 v99, v99, v115
	v_cvt_pk_bf16_f32 v183, v114, v115
	v_add_f32_e32 v192, v192, v128
	v_mfma_f32_16x16x32_bf16 v[14:17], v[238:241], v[184:187], v[14:17]
	v_add_f32_e32 v193, v193, v129
	v_cvt_pk_bf16_f32 v190, v128, v129
	v_add_f32_e32 v192, v192, v130
	v_add_f32_e32 v193, v193, v131
	v_cvt_pk_bf16_f32 v191, v130, v131
	s_waitcnt lgkmcnt(0)
	v_mfma_f32_16x16x32_bf16 v[82:85], v[242:245], v[180:183], v[82:85]
	v_mfma_f32_16x16x32_bf16 v[26:29], v[242:245], v[188:191], v[26:29]
	s_waitcnt vmcnt(9)
	s_cmp_lt_u32 s6, 32
	s_cbranch_scc1 .Lmy_att_ok2
	s_waitcnt vmcnt(0)
.Lmy_att_ok2:
	ds_write_b128 v171, v[214:217] offset:13312
	ds_write_b128 v172, v[222:225] offset:35840
	s_and_saveexec_b64 s[4:5], s[36:37]
	s_cbranch_execz .Lmy_att_w2
	ds_write_b128 v169, v[218:221] offset:13312
.Lmy_att_w2:
	s_or_b64 exec, exec, s[4:5]
	v_mfma_f32_16x16x32_bf16 v[74:77], v[246:249], v[180:183], v[74:77]
	v_mfma_f32_16x16x32_bf16 v[22:25], v[246:249], v[188:191], v[22:25]
	v_mfma_f32_16x16x32_bf16 v[58:61], v[132:135], v[180:183], v[58:61]
	v_mfma_f32_16x16x32_bf16 v[18:21], v[132:135], v[188:191], v[18:21]
	s_cmp_gt_u32 s6, 28
	s_cbranch_scc1 .Lmy_att_nl2
	global_load_dwordx4 v[214:217], v[94:95], off
	global_load_dwordx4 v[222:225], v[96:97], off
	global_load_dwordx4 v[218:221], v[92:93], off
	v_lshl_add_u64 v[94:95], v[94:95], 0, s[18:19]
	v_lshl_add_u64 v[92:93], v[92:93], 0, s[18:19]
	v_lshl_add_u64 v[96:97], v[96:97], 0, s[20:21]
; #define LAS __attribute__((address_space(3)))
; __device__ __forceinline__ unsigned cvt_pk_bf16(float lo, float hi) { unsigned r; asm volatile("v_cvt_pk_bf16_f32 %0, %1, %2" : "=v"(r) : "v"(lo), "v"(hi)); return r; }
; __device__ __forceinline__ void attn_unit(LAS unsigned char* lds, const bf16_t* QB, const bf16_t* KB, const bf16_t* VT, const bf16_t* P, bf16_t* Z0, int b, int h, int qrow0, int nkeys) {
;     ...
;       for (int half = 0; half < 2; ++half) { const int tt = t2 + half; if (tt < ntile) {
;         const int cur = half;
;         const LAS unsigned char* kb = lds + cur * KBUF; const LAS unsigned char* vb = lds + VOFF + cur * VBUF;
;         f32x4 s[2][4];
; #pragma unroll
;         for (int kbk = 0; kbk < 4; ++kbk) { s[0][kbk] = (f32x4){0.f, 0.f, 0.f, 0.f}; s[1][kbk] = s[0][kbk];
; #pragma unroll
;             for (int ks = 0; ks < 3; ++ks) { const bf16x8 kf = *(const LAS bf16x8*)(kb + (kbk * 16 + fr) * KST + ks * 64 + fq * 16);
;                 s[0][kbk] = MFMA16(kf, qf[0][ks], s[0][kbk]); s[1][kbk] = MFMA16(kf, qf[1][ks], s[1][kbk]); } }
;         bf16x8 pf[2][2];
; #pragma unroll
;         for (int qb = 0; qb < 2; ++qb) {
;             float ps = 0.f;
; #pragma unroll
;             for (int kbk = 0; kbk < 4; ++kbk)
; #pragma unroll
;                 for (int q = 0; q < 4; ++q) { const float pv = __builtin_amdgcn_exp2f(s[qb][kbk][q]); s[qb][kbk][q] = pv; ps += pv; }
;             lsum[qb] += ps;
; #pragma unroll
;             for (int k2 = 0; k2 < 2; ++k2) { u32x4 w; w.x = cvt_pk_bf16(s[qb][2 * k2][0], s[qb][2 * k2][1]); w.y = cvt_pk_bf16(s[qb][2 * k2][2], s[qb][2 * k2][3]);
;                 w.z = cvt_pk_bf16(s[qb][2 * k2 + 1][0], s[qb][2 * k2 + 1][1]); w.w = cvt_pk_bf16(s[qb][2 * k2 + 1][2], s[qb][2 * k2 + 1][3]); pf[qb][k2] = asfrag(w); }
;         }
; #pragma unroll
;         for (int db = 0; db < 4; ++db)
; #pragma unroll
;             for (int k2 = 0; k2 < 2; ++k2) { const LAS unsigned char* vp = vb + (db * 16 + fr) * VST + (k2 * 32 + fq * 4) * 2;
;                 const u32x2 lo = *(const LAS u32x2*)vp, hi = *(const LAS u32x2*)(vp + 32);
;                 const bf16x8 vf = asfrag((u32x4){lo.x, lo.y, hi.x, hi.y});
;                 o[0][db] = MFMA16(vf, pf[0][k2], o[0][db]); o[1][db] = MFMA16(vf, pf[1][k2], o[1][db]); }
;         if (tt + 1 < ntile) ATT_STORE(half, cur ^ 1);
.Lmy_att_nl2:
	v_mfma_f32_16x16x32_bf16 v[30:33], v[136:139], v[180:183], v[30:33]
	v_mfma_f32_16x16x32_bf16 v[14:17], v[136:139], v[188:191], v[14:17]
	s_waitcnt lgkmcnt(0)
	s_barrier
	ds_read_b128 v[132:135], v0 offset:13312
	ds_read_b128 v[136:139], v0 offset:13376
	ds_read_b128 v[140:143], v0 offset:13440
	ds_read_b128 v[156:159], v0 offset:16640
	ds_read_b128 v[160:163], v0 offset:16704
	ds_read_b128 v[164:167], v0 offset:16768
	ds_read_b128 v[238:241], v0 offset:19968
	ds_read_b128 v[242:245], v0 offset:20032
	ds_read_b128 v[246:249], v0 offset:20096
	s_waitcnt lgkmcnt(6)
	v_mfma_f32_16x16x32_bf16 v[100:103], v[132:135], v[34:37], 0
	v_mfma_f32_16x16x32_bf16 v[116:119], v[132:135], v[46:49], 0
	v_mfma_f32_16x16x32_bf16 v[100:103], v[136:139], v[38:41], v[100:103]
	v_mfma_f32_16x16x32_bf16 v[116:119], v[136:139], v[50:53], v[116:119]
	v_mfma_f32_16x16x32_bf16 v[100:103], v[140:143], v[42:45], v[100:103]
	v_mfma_f32_16x16x32_bf16 v[116:119], v[140:143], v[54:57], v[116:119]
	ds_read_b128 v[132:135], v0 offset:23296
	ds_read_b128 v[136:139], v0 offset:23360
	ds_read_b128 v[140:143], v0 offset:23424
	s_waitcnt lgkmcnt(6)
	v_mfma_f32_16x16x32_bf16 v[104:107], v[156:159], v[34:37], 0
	v_mfma_f32_16x16x32_bf16 v[120:123], v[156:159], v[46:49], 0
	v_mfma_f32_16x16x32_bf16 v[104:107], v[160:163], v[38:41], v[104:107]
	v_mfma_f32_16x16x32_bf16 v[120:123], v[160:163], v[50:53], v[120:123]
	v_mfma_f32_16x16x32_bf16 v[104:107], v[164:167], v[42:45], v[104:107]
	v_mfma_f32_16x16x32_bf16 v[120:123], v[164:167], v[54:57], v[120:123]
	ds_read_b64 v[156:157], v175 offset:35840
	ds_read_b64 v[158:159], v175 offset:35872
	ds_read_b64 v[160:161], v175 offset:38144
	ds_read_b64 v[162:163], v175 offset:38176
	ds_read_b64 v[164:165], v175 offset:40448
	ds_read_b64 v[166:167], v175 offset:40480
	s_waitcnt lgkmcnt(9)
	v_mfma_f32_16x16x32_bf16 v[108:111], v[238:241], v[34:37], 0
	v_exp_f32_e32 v100, v100
	v_exp_f32_e32 v101, v101
	v_exp_f32_e32 v102, v102
	v_exp_f32_e32 v103, v103
	v_mfma_f32_16x16x32_bf16 v[124:127], v[238:241], v[46:49], 0
	v_exp_f32_e32 v116, v116
	v_exp_f32_e32 v117, v117
	v_exp_f32_e32 v118, v118
	v_exp_f32_e32 v119, v119
	v_mfma_f32_16x16x32_bf16 v[108:111], v[242:245], v[38:41], v[108:111]
	v_add_f32_e32 v98, v98, v100
	v_add_f32_e32 v99, v99, v101
	v_cvt_pk_bf16_f32 v176, v100, v101
	v_mfma_f32_16x16x32_bf16 v[124:127], v[242:245], v[50:53], v[124:127]
	v_add_f32_e32 v98, v98, v102
	v_add_f32_e32 v99, v99, v103
	v_cvt_pk_bf16_f32 v177, v102, v103
	v_mfma_f32_16x16x32_bf16 v[108:111], v[246:249], v[42:45], v[108:111]
	v_add_f32_e32 v192, v192, v116
	v_add_f32_e32 v193, v193, v117
	v_cvt_pk_bf16_f32 v184, v116, v117
	v_mfma_f32_16x16x32_bf16 v[124:127], v[246:249], v[54:57], v[124:127]
	v_add_f32_e32 v192, v192, v118
	v_add_f32_e32 v193, v193, v119
	v_cvt_pk_bf16_f32 v185, v118, v119
	ds_read_b64 v[238:239], v175 offset:42752
	ds_read_b64 v[240:241], v175 offset:42784
	ds_read_b64 v[242:243], v175 offset:35904
	ds_read_b64 v[244:245], v175 offset:35936
	ds_read_b64 v[246:247], v175 offset:38208
	ds_read_b64 v[248:249], v175 offset:38240
	s_waitcnt lgkmcnt(12)
	v_mfma_f32_16x16x32_bf16 v[112:115], v[132:135], v[34:37], 0
	v_exp_f32_e32 v104, v104
	v_exp_f32_e32 v105, v105
	v_exp_f32_e32 v106, v106
	v_exp_f32_e32 v107, v107
	v_mfma_f32_16x16x32_bf16 v[128:131], v[132:135], v[46:49], 0
	v_exp_f32_e32 v120, v120
	v_exp_f32_e32 v121, v121
	v_exp_f32_e32 v122, v122
	v_exp_f32_e32 v123, v123
	v_mfma_f32_16x16x32_bf16 v[112:115], v[136:139], v[38:41], v[112:115]
	v_add_f32_e32 v98, v98, v104
	v_add_f32_e32 v99, v99, v105
	v_cvt_pk_bf16_f32 v178, v104, v105
	v_mfma_f32_16x16x32_bf16 v[128:131], v[136:139], v[50:53], v[128:131]
	v_add_f32_e32 v98, v98, v106
	v_add_f32_e32 v99, v99, v107
	v_cvt_pk_bf16_f32 v179, v106, v107
	v_mfma_f32_16x16x32_bf16 v[112:115], v[140:143], v[42:45], v[112:115]
	v_add_f32_e32 v192, v192, v120
	v_add_f32_e32 v193, v193, v121
	v_cvt_pk_bf16_f32 v186, v120, v121
	v_mfma_f32_16x16x32_bf16 v[128:131], v[140:143], v[54:57], v[128:131]
	v_add_f32_e32 v192, v192, v122
	v_add_f32_e32 v193, v193, v123
	v_cvt_pk_bf16_f32 v187, v122, v123
	s_waitcnt lgkmcnt(6)
	ds_read_b64 v[132:133], v175 offset:40512
	ds_read_b64 v[134:135], v175 offset:40544
	ds_read_b64 v[136:137], v175 offset:42816
	ds_read_b64 v[138:139], v175 offset:42848
	v_mfma_f32_16x16x32_bf16 v[82:85], v[156:159], v[176:179], v[82:85]
	v_exp_f32_e32 v108, v108
	v_exp_f32_e32 v109, v109
	v_exp_f32_e32 v110, v110
	v_exp_f32_e32 v111, v111
	v_exp_f32_e32 v124, v124
	v_mfma_f32_16x16x32_bf16 v[26:29], v[156:159], v[184:187], v[26:29]
	v_exp_f32_e32 v125, v125
	v_exp_f32_e32 v126, v126
	v_exp_f32_e32 v127, v127
	v_add_f32_e32 v98, v98, v108
	v_add_f32_e32 v99, v99, v109
	v_mfma_f32_16x16x32_bf16 v[74:77], v[160:163], v[176:179], v[74:77]
	v_cvt_pk_bf16_f32 v180, v108, v109
	v_add_f32_e32 v98, v98, v110
	v_add_f32_e32 v99, v99, v111
	v_cvt_pk_bf16_f32 v181, v110, v111
	v_add_f32_e32 v192, v192, v124
	v_mfma_f32_16x16x32_bf16 v[22:25], v[160:163], v[184:187], v[22:25]
	v_add_f32_e32 v193, v193, v125
	v_cvt_pk_bf16_f32 v188, v124, v125
	v_add_f32_e32 v192, v192, v126
	v_add_f32_e32 v193, v193, v127
	v_cvt_pk_bf16_f32 v189, v126, v127
	v_mfma_f32_16x16x32_bf16 v[58:61], v[164:167], v[176:179], v[58:61]
	v_exp_f32_e32 v112, v112
	v_exp_f32_e32 v113, v113
	v_exp_f32_e32 v114, v114
	v_exp_f32_e32 v115, v115
	v_exp_f32_e32 v128, v128
	v_mfma_f32_16x16x32_bf16 v[18:21], v[164:167], v[184:187], v[18:21]
	v_exp_f32_e32 v129, v129
	v_exp_f32_e32 v130, v130
	v_exp_f32_e32 v131, v131
	v_add_f32_e32 v98, v98, v112
	v_add_f32_e32 v99, v99, v113
	s_waitcnt lgkmcnt(8)
	v_mfma_f32_16x16x32_bf16 v[30:33], v[238:241], v[176:179], v[30:33]
	v_cvt_pk_bf16_f32 v182, v112, v113
	v_add_f32_e32 v98, v98, v114
	v_add_f32_e32 v99, v99, v115
	v_cvt_pk_bf16_f32 v183, v114, v115
	v_add_f32_e32 v192, v192, v128
	v_mfma_f32_16x16x32_bf16 v[14:17], v[238:241], v[184:187], v[14:17]
	v_add_f32_e32 v193, v193, v129
	v_cvt_pk_bf16_f32 v190, v128, v129
	v_add_f32_e32 v192, v192, v130
	v_add_f32_e32 v193, v193, v131
	v_cvt_pk_bf16_f32 v191, v130, v131
	s_waitcnt lgkmcnt(0)
	v_mfma_f32_16x16x32_bf16 v[82:85], v[242:245], v[180:183], v[82:85]
	v_mfma_f32_16x16x32_bf16 v[26:29], v[242:245], v[188:191], v[26:29]
	s_cmp_gt_u32 s6, 28
	s_cbranch_scc1 .Lmy_att_ns3
	s_waitcnt vmcnt(9)
	ds_write_b128 v171, v[226:229]
	ds_write_b128 v172, v[234:237] offset:26624
	s_and_saveexec_b64 s[4:5], s[36:37]
	s_cbranch_execz .Lmy_att_w3
	ds_write_b128 v169, v[230:233]

; #define ATT_LOAD(S_, tt) do { const bf16_t* kt_ = kg + (size_t)(tt) * 64 * 96; rk0[S_] = ld8(kt_ + kp0 * 8); if (kp1 < 768) rk1[S_] = ld8(kt_ + kp1 * 8); rv[S_] = ld8(vg + (size_t)vd * NKEY + (tt) * 64 + vpart * 8); } while (0)
; #define ATT_STORE(S_, bufi) do { LAS unsigned char* kb_ = lds + (bufi) * KBUF; *(LAS u32x4*)(kb_ + (kp0 / 12) * KST + (kp0 % 12) * 16) = rk0[S_]; if (kp1 < 768) *(LAS u32x4*)(kb_ + (kp1 / 12) * KST + (kp1 % 12) * 16) = rk1[S_]; \
;         *(LAS u32x4*)(lds + VOFF + (bufi) * VBUF + vd * VST + vpart * 16) = rv[S_]; } while (0)
; __device__ __forceinline__ void attn_unit(LAS unsigned char* lds, const bf16_t* QB, const bf16_t* KB, const bf16_t* VT, const bf16_t* P, bf16_t* Z0, int b, int h, int qrow0, int nkeys) {
;     ...
;         if (tt + 1 < ntile) ATT_STORE(half, cur ^ 1);
;         __syncthreads();
;         if (tt + 3 < ntile) ATT_LOAD(half, tt + 3);
;       } }
;     }
;     ...
; #pragma unroll
;     for (int qb = 0; qb < 2; ++qb) {
;         float lt = lsum[qb]; lt += __shfl_xor(lt, 16); lt += __shfl_xor(lt, 32);
.Lmy_att_ns3:
	v_mfma_f32_16x16x32_bf16 v[74:77], v[246:249], v[180:183], v[74:77]
	v_mfma_f32_16x16x32_bf16 v[22:25], v[246:249], v[188:191], v[22:25]
	v_mfma_f32_16x16x32_bf16 v[58:61], v[132:135], v[180:183], v[58:61]
	v_mfma_f32_16x16x32_bf16 v[18:21], v[132:135], v[188:191], v[18:21]
	s_cmp_gt_u32 s6, 24
	s_cbranch_scc1 .Lmy_att_nl3
	global_load_dwordx4 v[226:229], v[94:95], off
	global_load_dwordx4 v[234:237], v[96:97], off
	global_load_dwordx4 v[230:233], v[92:93], off
	v_lshl_add_u64 v[94:95], v[94:95], 0, s[18:19]
	v_lshl_add_u64 v[92:93], v[92:93], 0, s[18:19]
	v_lshl_add_u64 v[96:97], v[96:97], 0, s[20:21]
.Lmy_att_nl3:
	v_mfma_f32_16x16x32_bf16 v[30:33], v[136:139], v[180:183], v[30:33]
	v_mfma_f32_16x16x32_bf16 v[14:17], v[136:139], v[188:191], v[14:17]
	s_waitcnt lgkmcnt(0)
	s_barrier
	s_add_i32 s6, s6, 4
	s_cmp_lt_u32 s6, 36
	s_cbranch_scc1 .Lmy_att_loop
	s_nop 1
	v_add_f32_e32 v88, v98, v99
	v_add_f32_e32 v89, v192, v193
	s_branch .LBB0_1008

; __device__ __forceinline__ unsigned cvt_pk_bf16(float lo, float hi) { unsigned r; asm volatile("v_cvt_pk_bf16_f32 %0, %1, %2" : "=v"(r) : "v"(lo), "v"(hi)); return r; }
; __device__ __forceinline__ float gelu_tanh(float x) { const float u = 0.7978845608028654f * (x + 0.044715f * x * x * x); return x * sigm(2.f * u); }
; #define UNPK8(VV_, XX_) float XX_[8] = {bflo((VV_).x), bfhi((VV_).x), bflo((VV_).y), bfhi((VV_).y), bflo((VV_).z), bfhi((VV_).z), bflo((VV_).w), bfhi((VV_).w)}
; __device__ __forceinline__ void glu_task(int t, int l, const float* s5d, const bf16_t* P, const bf16_t* YB, const bf16_t* WGLU, bf16_t* Z1, int fr, int fq) {
;     const int cb0 = (t & 3) * 4; const size_t row0 = (size_t)((t >> 2) * 32 + fr);
;     bf16x8 bfr[2][8];
; #pragma unroll
;     for (int tb = 0; tb < 2; ++tb) { const size_t row = row0 + tb * 16;
; #pragma unroll
;         for (int ks = 0; ks < 8; ++ks) { const int k0 = ks * 32 + fq * 8; const u32x4 yw = ld8(YB + row * 256 + k0), uw = ld8(P + row * INP + OFF_S5 + k0);
;             const f32x4 d0 = *(const f32x4*)(s5d + l * 256 + k0), d1 = *(const f32x4*)(s5d + l * 256 + k0 + 4); UNPK8(yw, y); UNPK8(uw, u); u32x4 o;
;             o.x = cvt_pk_bf16(gelu_tanh(y[0] + d0[0] * u[0]), gelu_tanh(y[1] + d0[1] * u[1])); o.y = cvt_pk_bf16(gelu_tanh(y[2] + d0[2] * u[2]), gelu_tanh(y[3] + d0[3] * u[3]));
;             o.z = cvt_pk_bf16(gelu_tanh(y[4] + d1[0] * u[4]), gelu_tanh(y[5] + d1[1] * u[5])); o.w = cvt_pk_bf16(gelu_tanh(y[6] + d1[2] * u[6]), gelu_tanh(y[7] + d1[3] * u[7]));
;             bfr[tb][ks] = asfrag(o); } }
.LBB0_1280:
	s_or_b64 exec, exec, s[4:5]
	v_readlane_b32 s72, v253, 59
	v_readlane_b32 s73, v253, 60
	s_mov_b64 s[4:5], s[72:73]
	s_waitcnt lgkmcnt(0)
	s_barrier
	v_mov_b32 v0, v194
	v_readlane_b32 s69, v254, 13
	v_readfirstlane_b32 s1, v0
	s_ashr_i32 s6, s1, 6
	s_add_i32 s20, s6, s69
	v_readlane_b32 s14, v253, 25
	v_readlane_b32 s22, v254, 48
	v_readlane_b32 s74, v253, 61
	s_cmp_lt_i32 s20, s38
	v_readlane_b32 s15, v253, 26
	s_movk_i32 s18, 0x6000
	s_mov_b64 s[64:65], 0x100
	v_readlane_b32 s23, v254, 49
	v_readlane_b32 s75, v253, 62
	v_and_b32_e32 v60, 63, v194
	v_lshlrev_b32_e32 v60, 4, v60
	s_nop 2
	global_load_dwordx4 v[62:65], v60, s[22:23]
	s_waitcnt vmcnt(0)
	ds_write_b128 v60, v[62:65]
	s_waitcnt lgkmcnt(0)
	s_barrier
	s_cbranch_scc0 .LBB0_1283
	s_add_u32 s36, s4, 0x8eb8000
	s_addc_u32 s37, s5, 0
	s_mov_b32 s19, s38
	s_add_u32 s38, s4, 0x13538000
	v_bfe_u32 v3, v0, 4, 2
	v_lshlrev_b32_e32 v246, 5, v3
	s_addc_u32 s39, s5, 0
	v_and_b32_e32 v174, 15, v0
	s_add_u32 s40, s4, 0x4fb8000
	v_lshlrev_b32_e32 v0, 5, v3
	s_addc_u32 s41, s5, 0
	v_lshl_add_u64 v[134:135], s[22:23], 0, v[0:1]
	v_lshlrev_b32_e32 v0, 4, v3
	s_and_b32 s1, s1, 0x1c0
	v_lshl_add_u64 v[4:5], s[4:5], 0, v[0:1]
	s_mov_b64 s[4:5], 0x22a0000
	s_cmp_eq_u32 s1, 0
	v_lshlrev_b32_e32 v2, 3, v3
	v_lshl_add_u64 v[136:137], v[4:5], 0, s[4:5]
	s_cselect_b64 s[42:43], -1, 0
	s_ashr_i32 s4, s20, 3
	v_readlane_b32 s6, v254, 21
	v_lshlrev_b32_e32 v175, 2, v3
	s_addk_i32 s4, 0x800
	v_or_b32_e32 v176, s6, v174
	v_mov_b32_e32 v177, 0
	v_lshlrev_b32_e32 v0, 1, v2
	v_readlane_b32 s7, v254, 22
.LBB0_1282:
	s_lshl_b32 s5, s20, 3
	s_andn2_b32 s5, s5, 31
	v_or_b32_e32 v2, s5, v174
	v_ashrrev_i32_e32 v3, 31, v2
	v_lshlrev_b64 v[114:115], 9, v[2:3]
	v_lshl_add_u64 v[70:71], s[38:39], 0, v[114:115]
	v_mov_b64_e32 v[4:5], s[36:37]
	v_mad_i64_i32 v[72:73], s[6:7], v2, s84, v[4:5]
	v_lshl_add_u64 v[34:35], v[70:71], 0, v[0:1]
	v_lshl_add_u64 v[36:37], v[72:73], 0, v[0:1]
	ds_read_b128 v[14:17], v246 offset:16
	ds_read_b128 v[18:21], v246
	v_or_b32_e32 v138, 0x2000, v114
	v_mov_b32_e32 v139, v115
	v_lshl_add_u64 v[74:75], s[38:39], 0, v[138:139]
	s_mov_b64 s[6:7], 0x22000
	v_lshl_add_u64 v[76:77], v[72:73], 0, s[6:7]
	v_lshl_add_u64 v[66:67], v[74:75], 0, v[0:1]
	v_lshl_add_u64 v[68:69], v[76:77], 0, v[0:1]
	s_lshl_b32 s1, s20, 6
	s_and_b32 s5, s1, 0xc0
	v_or_b32_e32 v178, s5, v175
	v_lshlrev_b32_e32 v158, 1, v178
	v_mov_b32_e32 v159, v1
	v_lshl_add_u64 v[70:71], v[70:71], 0, v[158:159]
	v_lshl_add_u64 v[72:73], v[72:73], 0, v[158:159]
	v_lshlrev_b32_e32 v178, 2, v178
	s_add_i32 s1, s20, s60
	global_load_dwordx4 v[98:101], v[34:35], off
	global_load_dwordx4 v[102:105], v[36:37], off offset:320
	global_load_dwordx4 v[106:109], v[34:35], off offset:64
	global_load_dwordx4 v[110:113], v[36:37], off offset:384
	global_load_dwordx4 v[118:121], v[34:35], off offset:128
	global_load_dwordx4 v[122:125], v[36:37], off offset:448
	global_load_dwordx4 v[126:129], v[34:35], off offset:192
	global_load_dwordx4 v[130:133], v[36:37], off offset:512
	global_load_dwordx4 v[140:143], v[34:35], off offset:256
	global_load_dwordx4 v[144:147], v[36:37], off offset:576
	global_load_dwordx4 v[160:163], v[34:35], off offset:320
	global_load_dwordx4 v[164:167], v[36:37], off offset:640
	global_load_dwordx4 v[180:183], v[34:35], off offset:384
	global_load_dwordx4 v[184:187], v[36:37], off offset:704
	global_load_dwordx4 v[214:217], v[34:35], off offset:448
	global_load_dwordx4 v[218:221], v[36:37], off offset:768
	global_load_dwordx4 v[222:225], v[66:67], off
	global_load_dwordx4 v[226:229], v[68:69], off offset:320
	global_load_dwordx4 v[230:233], v[66:67], off offset:64
	global_load_dwordx4 v[234:237], v[68:69], off offset:384
	global_load_dwordx4 v[238:241], v[66:67], off offset:128
	global_load_dwordx4 v[242:245], v[68:69], off offset:448
	global_load_dwordx4 v[168:171], v[66:67], off offset:192
	global_load_dwordx4 v[188:191], v[68:69], off offset:512
	s_waitcnt vmcnt(22) lgkmcnt(0)
	v_mov_b32_e32 v2, v98
	v_mov_b32_e32 v3, v99
	v_mov_b32_e32 v4, v100
	v_mov_b32_e32 v5, v101
	v_mov_b32_e32 v6, v102
	v_mov_b32_e32 v7, v103
	v_mov_b32_e32 v8, v104
	v_mov_b32_e32 v9, v105
	global_load_dwordx4 v[98:101], v[66:67], off offset:256
	global_load_dwordx4 v[102:105], v[68:69], off offset:576
	v_lshlrev_b32_e32 v26, 16, v6
	v_lshlrev_b32_e32 v22, 16, v2
	v_and_b32_e32 v2, 0xffff0000, v2
	v_and_b32_e32 v6, 0xffff0000, v6
	v_fmac_f32_e32 v2, v19, v6
	v_mul_f32_e32 v6, 0x3d372713, v2
	v_mul_f32_e32 v6, v2, v6
	v_fma_f32 v6, v2, v6, v2
	v_mul_f32_e32 v6, 0x3f4c422a, v6
	v_add_f32_e32 v6, v6, v6
	v_mul_f32_e32 v6, 0xbfb8aa3b, v6
	v_exp_f32_e32 v6, v6
	v_lshlrev_b32_e32 v23, 16, v3
	v_and_b32_e32 v3, 0xffff0000, v3
	v_lshlrev_b32_e32 v27, 16, v7
	v_add_f32_e32 v6, 1.0, v6
	v_rcp_f32_e32 v6, v6
	v_and_b32_e32 v7, 0xffff0000, v7
	v_fmac_f32_e32 v23, v20, v27
	v_fmac_f32_e32 v3, v21, v7
	v_fmac_f32_e32 v22, v18, v26
	v_mul_f32_e32 v2, v2, v6
	v_mul_f32_e32 v6, 0x3d372713, v23
	v_mul_f32_e32 v7, 0x3d372713, v3
	v_mul_f32_e32 v18, 0x3d372713, v22
	v_mul_f32_e32 v6, v23, v6
	v_mul_f32_e32 v7, v3, v7
	v_mul_f32_e32 v18, v22, v18
	v_fma_f32 v6, v23, v6, v23
	v_fma_f32 v7, v3, v7, v3
	v_fma_f32 v18, v22, v18, v22
	v_mul_f32_e32 v6, 0x3f4c422a, v6
	v_mul_f32_e32 v7, 0x3f4c422a, v7
	v_mul_f32_e32 v18, 0x3f4c422a, v18
	v_add_f32_e32 v6, v6, v6
	v_add_f32_e32 v7, v7, v7
	v_add_f32_e32 v18, v18, v18
	v_mul_f32_e32 v6, 0xbfb8aa3b, v6
	v_mul_f32_e32 v7, 0xbfb8aa3b, v7
	v_mul_f32_e32 v18, 0xbfb8aa3b, v18
	v_exp_f32_e32 v6, v6
	v_exp_f32_e32 v7, v7
	v_exp_f32_e32 v18, v18
	v_lshlrev_b32_e32 v24, 16, v4
	v_add_f32_e32 v6, 1.0, v6
	v_add_f32_e32 v7, 1.0, v7
; __device__ __forceinline__ unsigned cvt_pk_bf16(float lo, float hi) { unsigned r; asm volatile("v_cvt_pk_bf16_f32 %0, %1, %2" : "=v"(r) : "v"(lo), "v"(hi)); return r; }
; __device__ __forceinline__ float gelu_tanh(float x) { const float u = 0.7978845608028654f * (x + 0.044715f * x * x * x); return x * sigm(2.f * u); }
; #define UNPK8(VV_, XX_) float XX_[8] = {bflo((VV_).x), bfhi((VV_).x), bflo((VV_).y), bfhi((VV_).y), bflo((VV_).z), bfhi((VV_).z), bflo((VV_).w), bfhi((VV_).w)}
; __device__ __forceinline__ void glu_task(int t, int l, const float* s5d, const bf16_t* P, const bf16_t* YB, const bf16_t* WGLU, bf16_t* Z1, int fr, int fq) {
;     ...
;     for (int tb = 0; tb < 2; ++tb) { const size_t row = row0 + tb * 16;
; #pragma unroll
;         for (int ks = 0; ks < 8; ++ks) { const int k0 = ks * 32 + fq * 8; const u32x4 yw = ld8(YB + row * 256 + k0), uw = ld8(P + row * INP + OFF_S5 + k0);
;             const f32x4 d0 = *(const f32x4*)(s5d + l * 256 + k0), d1 = *(const f32x4*)(s5d + l * 256 + k0 + 4); UNPK8(yw, y); UNPK8(uw, u); u32x4 o;
;             o.x = cvt_pk_bf16(gelu_tanh(y[0] + d0[0] * u[0]), gelu_tanh(y[1] + d0[1] * u[1])); o.y = cvt_pk_bf16(gelu_tanh(y[2] + d0[2] * u[2]), gelu_tanh(y[3] + d0[3] * u[3]));
;             o.z = cvt_pk_bf16(gelu_tanh(y[4] + d1[0] * u[4]), gelu_tanh(y[5] + d1[1] * u[5])); o.w = cvt_pk_bf16(gelu_tanh(y[6] + d1[2] * u[6]), gelu_tanh(y[7] + d1[3] * u[7]));
;             bfr[tb][ks] = asfrag(o); } }
	v_add_f32_e32 v18, 1.0, v18
	v_rcp_f32_e32 v6, v6
	v_rcp_f32_e32 v7, v7
	v_rcp_f32_e32 v18, v18
	v_and_b32_e32 v4, 0xffff0000, v4
	v_lshlrev_b32_e32 v28, 16, v8
	v_and_b32_e32 v8, 0xffff0000, v8
	v_mul_f32_e32 v6, v23, v6
	v_mul_f32_e32 v3, v3, v7
	v_fmac_f32_e32 v24, v14, v28
	v_fmac_f32_e32 v4, v15, v8
	v_mul_f32_e32 v18, v22, v18
	v_cvt_pk_bf16_f32 v2, v18, v2
	v_cvt_pk_bf16_f32 v3, v6, v3
	v_mul_f32_e32 v6, 0x3d372713, v24
	v_mul_f32_e32 v7, 0x3d372713, v4
	v_mul_f32_e32 v6, v24, v6
	v_mul_f32_e32 v7, v4, v7
	v_fma_f32 v6, v24, v6, v24
	v_fma_f32 v7, v4, v7, v4
	v_mul_f32_e32 v6, 0x3f4c422a, v6
	v_mul_f32_e32 v7, 0x3f4c422a, v7
	v_add_f32_e32 v6, v6, v6
	v_add_f32_e32 v7, v7, v7
	v_mul_f32_e32 v6, 0xbfb8aa3b, v6
	v_mul_f32_e32 v7, 0xbfb8aa3b, v7
	v_exp_f32_e32 v6, v6
	v_exp_f32_e32 v7, v7
	v_lshlrev_b32_e32 v25, 16, v5
	v_and_b32_e32 v5, 0xffff0000, v5
	v_add_f32_e32 v6, 1.0, v6
	v_add_f32_e32 v7, 1.0, v7
	v_rcp_f32_e32 v6, v6
	v_rcp_f32_e32 v7, v7
	v_lshlrev_b32_e32 v29, 16, v9
	v_and_b32_e32 v9, 0xffff0000, v9
	v_mul_f32_e32 v6, v24, v6
	v_mul_f32_e32 v4, v4, v7
	v_fmac_f32_e32 v25, v16, v29
	v_fmac_f32_e32 v5, v17, v9
	v_cvt_pk_bf16_f32 v4, v6, v4
	v_mul_f32_e32 v6, 0x3d372713, v25
	v_mul_f32_e32 v7, 0x3d372713, v5
	v_mul_f32_e32 v6, v25, v6
	v_mul_f32_e32 v7, v5, v7
	v_fma_f32 v6, v25, v6, v25
	v_fma_f32 v7, v5, v7, v5
	v_mul_f32_e32 v6, 0x3f4c422a, v6
	v_mul_f32_e32 v7, 0x3f4c422a, v7
	v_add_f32_e32 v6, v6, v6
	v_add_f32_e32 v7, v7, v7
	v_mul_f32_e32 v6, 0xbfb8aa3b, v6
	v_mul_f32_e32 v7, 0xbfb8aa3b, v7
	v_exp_f32_e32 v6, v6
	v_exp_f32_e32 v7, v7
	v_add_f32_e32 v6, 1.0, v6
	v_add_f32_e32 v7, 1.0, v7
	v_rcp_f32_e32 v6, v6
	v_rcp_f32_e32 v7, v7
	v_mul_f32_e32 v6, v25, v6
	v_mul_f32_e32 v5, v5, v7
	v_cvt_pk_bf16_f32 v5, v6, v5
	ds_read_b128 v[18:21], v246 offset:144
	ds_read_b128 v[22:25], v246 offset:128
	s_waitcnt vmcnt(22) lgkmcnt(0)
	v_mov_b32_e32 v6, v106
	v_mov_b32_e32 v7, v107
	v_mov_b32_e32 v8, v108
	v_mov_b32_e32 v9, v109
	v_mov_b32_e32 v14, v110
	v_mov_b32_e32 v15, v111
	v_mov_b32_e32 v16, v112
	v_mov_b32_e32 v17, v113
	global_load_dwordx4 v[106:109], v[66:67], off offset:320
	global_load_dwordx4 v[110:113], v[68:69], off offset:640
	v_lshlrev_b32_e32 v26, 16, v6
	v_and_b32_e32 v6, 0xffff0000, v6
	v_lshlrev_b32_e32 v30, 16, v14
	v_and_b32_e32 v14, 0xffff0000, v14
	v_fmac_f32_e32 v6, v23, v14
	v_mul_f32_e32 v14, 0x3d372713, v6
	v_mul_f32_e32 v14, v6, v14
	v_fma_f32 v14, v6, v14, v6
	v_mul_f32_e32 v14, 0x3f4c422a, v14
	v_add_f32_e32 v14, v14, v14
	v_mul_f32_e32 v14, 0xbfb8aa3b, v14
	v_exp_f32_e32 v14, v14
	v_lshlrev_b32_e32 v27, 16, v7
	v_and_b32_e32 v7, 0xffff0000, v7
	v_lshlrev_b32_e32 v31, 16, v15
	v_add_f32_e32 v14, 1.0, v14
	v_rcp_f32_e32 v14, v14
	v_and_b32_e32 v15, 0xffff0000, v15
	v_fmac_f32_e32 v27, v24, v31
	v_fmac_f32_e32 v7, v25, v15
	v_fmac_f32_e32 v26, v22, v30
	v_mul_f32_e32 v6, v6, v14
	v_mul_f32_e32 v14, 0x3d372713, v27
	v_mul_f32_e32 v15, 0x3d372713, v7
	v_mul_f32_e32 v22, 0x3d372713, v26
	v_mul_f32_e32 v14, v27, v14
	v_mul_f32_e32 v15, v7, v15
	v_mul_f32_e32 v22, v26, v22
	v_fma_f32 v14, v27, v14, v27
	v_fma_f32 v15, v7, v15, v7
	v_fma_f32 v22, v26, v22, v26
	v_mul_f32_e32 v14, 0x3f4c422a, v14
	v_mul_f32_e32 v15, 0x3f4c422a, v15
	v_mul_f32_e32 v22, 0x3f4c422a, v22
	v_add_f32_e32 v14, v14, v14
	v_add_f32_e32 v15, v15, v15
	v_add_f32_e32 v22, v22, v22
	v_mul_f32_e32 v14, 0xbfb8aa3b, v14
	v_mul_f32_e32 v15, 0xbfb8aa3b, v15
	v_mul_f32_e32 v22, 0xbfb8aa3b, v22
	v_exp_f32_e32 v14, v14
	v_exp_f32_e32 v15, v15
	v_exp_f32_e32 v22, v22
	v_lshlrev_b32_e32 v28, 16, v8
	v_add_f32_e32 v14, 1.0, v14
	v_add_f32_e32 v15, 1.0, v15
	v_add_f32_e32 v22, 1.0, v22
	v_rcp_f32_e32 v14, v14
	v_rcp_f32_e32 v15, v15
	v_rcp_f32_e32 v22, v22
	v_and_b32_e32 v8, 0xffff0000, v8
	v_lshlrev_b32_e32 v32, 16, v16
	v_and_b32_e32 v16, 0xffff0000, v16
	v_mul_f32_e32 v14, v27, v14
	v_mul_f32_e32 v7, v7, v15
	v_fmac_f32_e32 v28, v18, v32
	v_fmac_f32_e32 v8, v19, v16
	v_mul_f32_e32 v22, v26, v22
	v_cvt_pk_bf16_f32 v6, v22, v6
	v_cvt_pk_bf16_f32 v7, v14, v7
	v_mul_f32_e32 v14, 0x3d372713, v28
	v_mul_f32_e32 v15, 0x3d372713, v8
	v_mul_f32_e32 v14, v28, v14
	v_mul_f32_e32 v15, v8, v15
	v_fma_f32 v14, v28, v14, v28
	v_fma_f32 v15, v8, v15, v8
	v_mul_f32_e32 v14, 0x3f4c422a, v14
	v_mul_f32_e32 v15, 0x3f4c422a, v15
	v_add_f32_e32 v14, v14, v14
	v_add_f32_e32 v15, v15, v15
	v_mul_f32_e32 v14, 0xbfb8aa3b, v14
	v_mul_f32_e32 v15, 0xbfb8aa3b, v15
	v_exp_f32_e32 v14, v14
	v_exp_f32_e32 v15, v15
	v_lshlrev_b32_e32 v29, 16, v9
	v_and_b32_e32 v9, 0xffff0000, v9
	v_add_f32_e32 v14, 1.0, v14
	v_add_f32_e32 v15, 1.0, v15
	v_rcp_f32_e32 v14, v14
	v_rcp_f32_e32 v15, v15
	v_lshlrev_b32_e32 v33, 16, v17
	v_and_b32_e32 v17, 0xffff0000, v17
	v_mul_f32_e32 v14, v28, v14
	v_mul_f32_e32 v8, v8, v15
	v_fmac_f32_e32 v29, v20, v33
	v_fmac_f32_e32 v9, v21, v17
	v_cvt_pk_bf16_f32 v8, v14, v8
	v_mul_f32_e32 v14, 0x3d372713, v29
	v_mul_f32_e32 v15, 0x3d372713, v9
	v_mul_f32_e32 v14, v29, v14
	v_mul_f32_e32 v15, v9, v15
	v_fma_f32 v14, v29, v14, v29
	v_fma_f32 v15, v9, v15, v9
	v_mul_f32_e32 v14, 0x3f4c422a, v14
	v_mul_f32_e32 v15, 0x3f4c422a, v15
	v_add_f32_e32 v14, v14, v14
	v_add_f32_e32 v15, v15, v15
	v_mul_f32_e32 v14, 0xbfb8aa3b, v14
	v_mul_f32_e32 v15, 0xbfb8aa3b, v15
	v_exp_f32_e32 v14, v14
	v_exp_f32_e32 v15, v15
	v_add_f32_e32 v14, 1.0, v14
	v_add_f32_e32 v15, 1.0, v15
	v_rcp_f32_e32 v14, v14
	v_rcp_f32_e32 v15, v15
	v_mul_f32_e32 v14, v29, v14
	v_mul_f32_e32 v9, v9, v15
	v_cvt_pk_bf16_f32 v9, v14, v9
	ds_read_b128 v[22:25], v246 offset:272
	ds_read_b128 v[26:29], v246 offset:256
	s_waitcnt vmcnt(22) lgkmcnt(0)
; __device__ __forceinline__ unsigned cvt_pk_bf16(float lo, float hi) { unsigned r; asm volatile("v_cvt_pk_bf16_f32 %0, %1, %2" : "=v"(r) : "v"(lo), "v"(hi)); return r; }
; __device__ __forceinline__ float gelu_tanh(float x) { const float u = 0.7978845608028654f * (x + 0.044715f * x * x * x); return x * sigm(2.f * u); }
; #define UNPK8(VV_, XX_) float XX_[8] = {bflo((VV_).x), bfhi((VV_).x), bflo((VV_).y), bfhi((VV_).y), bflo((VV_).z), bfhi((VV_).z), bflo((VV_).w), bfhi((VV_).w)}
; __device__ __forceinline__ void glu_task(int t, int l, const float* s5d, const bf16_t* P, const bf16_t* YB, const bf16_t* WGLU, bf16_t* Z1, int fr, int fq) {
;     ...
;     for (int tb = 0; tb < 2; ++tb) { const size_t row = row0 + tb * 16;
; #pragma unroll
;         for (int ks = 0; ks < 8; ++ks) { const int k0 = ks * 32 + fq * 8; const u32x4 yw = ld8(YB + row * 256 + k0), uw = ld8(P + row * INP + OFF_S5 + k0);
;             const f32x4 d0 = *(const f32x4*)(s5d + l * 256 + k0), d1 = *(const f32x4*)(s5d + l * 256 + k0 + 4); UNPK8(yw, y); UNPK8(uw, u); u32x4 o;
;             o.x = cvt_pk_bf16(gelu_tanh(y[0] + d0[0] * u[0]), gelu_tanh(y[1] + d0[1] * u[1])); o.y = cvt_pk_bf16(gelu_tanh(y[2] + d0[2] * u[2]), gelu_tanh(y[3] + d0[3] * u[3]));
;             o.z = cvt_pk_bf16(gelu_tanh(y[4] + d1[0] * u[4]), gelu_tanh(y[5] + d1[1] * u[5])); o.w = cvt_pk_bf16(gelu_tanh(y[6] + d1[2] * u[6]), gelu_tanh(y[7] + d1[3] * u[7]));
;             bfr[tb][ks] = asfrag(o); } }
	v_mov_b32_e32 v14, v118
	v_mov_b32_e32 v15, v119
	v_mov_b32_e32 v16, v120
	v_mov_b32_e32 v17, v121
	v_mov_b32_e32 v18, v122
	v_mov_b32_e32 v19, v123
	v_mov_b32_e32 v20, v124
	v_mov_b32_e32 v21, v125
	global_load_dwordx4 v[118:121], v[66:67], off offset:384
	global_load_dwordx4 v[122:125], v[68:69], off offset:704
	v_lshlrev_b32_e32 v30, 16, v14
	v_and_b32_e32 v14, 0xffff0000, v14
	v_lshlrev_b32_e32 v38, 16, v18
	v_and_b32_e32 v18, 0xffff0000, v18
	v_fmac_f32_e32 v14, v27, v18
	v_mul_f32_e32 v18, 0x3d372713, v14
	v_mul_f32_e32 v18, v14, v18
	v_fma_f32 v18, v14, v18, v14
	v_mul_f32_e32 v18, 0x3f4c422a, v18
	v_add_f32_e32 v18, v18, v18
	v_mul_f32_e32 v18, 0xbfb8aa3b, v18
	v_exp_f32_e32 v18, v18
	v_lshlrev_b32_e32 v31, 16, v15
	v_and_b32_e32 v15, 0xffff0000, v15
	v_lshlrev_b32_e32 v39, 16, v19
	v_add_f32_e32 v18, 1.0, v18
	v_rcp_f32_e32 v18, v18
	v_and_b32_e32 v19, 0xffff0000, v19
	v_fmac_f32_e32 v31, v28, v39
	v_fmac_f32_e32 v15, v29, v19
	v_fmac_f32_e32 v30, v26, v38
	v_mul_f32_e32 v14, v14, v18
	v_mul_f32_e32 v18, 0x3d372713, v31
	v_mul_f32_e32 v19, 0x3d372713, v15
	v_mul_f32_e32 v26, 0x3d372713, v30
	v_mul_f32_e32 v18, v31, v18
	v_mul_f32_e32 v19, v15, v19
	v_mul_f32_e32 v26, v30, v26
	v_fma_f32 v18, v31, v18, v31
	v_fma_f32 v19, v15, v19, v15
	v_fma_f32 v26, v30, v26, v30
	v_mul_f32_e32 v18, 0x3f4c422a, v18
	v_mul_f32_e32 v19, 0x3f4c422a, v19
	v_mul_f32_e32 v26, 0x3f4c422a, v26
	v_add_f32_e32 v18, v18, v18
	v_add_f32_e32 v19, v19, v19
	v_add_f32_e32 v26, v26, v26
	v_mul_f32_e32 v18, 0xbfb8aa3b, v18
	v_mul_f32_e32 v19, 0xbfb8aa3b, v19
	v_mul_f32_e32 v26, 0xbfb8aa3b, v26
	v_exp_f32_e32 v18, v18
	v_exp_f32_e32 v19, v19
	v_exp_f32_e32 v26, v26
	v_lshlrev_b32_e32 v32, 16, v16
	v_add_f32_e32 v18, 1.0, v18
	v_add_f32_e32 v19, 1.0, v19
	v_add_f32_e32 v26, 1.0, v26
	v_rcp_f32_e32 v18, v18
	v_rcp_f32_e32 v19, v19
	v_rcp_f32_e32 v26, v26
	v_and_b32_e32 v16, 0xffff0000, v16
	v_lshlrev_b32_e32 v40, 16, v20
	v_and_b32_e32 v20, 0xffff0000, v20
	v_mul_f32_e32 v18, v31, v18
	v_mul_f32_e32 v15, v15, v19
	v_fmac_f32_e32 v32, v22, v40
	v_fmac_f32_e32 v16, v23, v20
	v_mul_f32_e32 v26, v30, v26
	v_cvt_pk_bf16_f32 v14, v26, v14
	v_cvt_pk_bf16_f32 v15, v18, v15
	v_mul_f32_e32 v18, 0x3d372713, v32
	v_mul_f32_e32 v19, 0x3d372713, v16
	v_mul_f32_e32 v18, v32, v18
	v_mul_f32_e32 v19, v16, v19
	v_fma_f32 v18, v32, v18, v32
	v_fma_f32 v19, v16, v19, v16
	v_mul_f32_e32 v18, 0x3f4c422a, v18
	v_mul_f32_e32 v19, 0x3f4c422a, v19
	v_add_f32_e32 v18, v18, v18
	v_add_f32_e32 v19, v19, v19
	v_mul_f32_e32 v18, 0xbfb8aa3b, v18
	v_mul_f32_e32 v19, 0xbfb8aa3b, v19
	v_exp_f32_e32 v18, v18
	v_exp_f32_e32 v19, v19
	v_lshlrev_b32_e32 v33, 16, v17
	v_and_b32_e32 v17, 0xffff0000, v17
	v_add_f32_e32 v18, 1.0, v18
	v_add_f32_e32 v19, 1.0, v19
	v_rcp_f32_e32 v18, v18
	v_rcp_f32_e32 v19, v19
	v_lshlrev_b32_e32 v41, 16, v21
	v_and_b32_e32 v21, 0xffff0000, v21
	v_mul_f32_e32 v18, v32, v18
	v_mul_f32_e32 v16, v16, v19
	v_fmac_f32_e32 v33, v24, v41
	v_fmac_f32_e32 v17, v25, v21
	v_cvt_pk_bf16_f32 v16, v18, v16
	v_mul_f32_e32 v18, 0x3d372713, v33
	v_mul_f32_e32 v19, 0x3d372713, v17
	v_mul_f32_e32 v18, v33, v18
	v_mul_f32_e32 v19, v17, v19
	v_fma_f32 v18, v33, v18, v33
	v_fma_f32 v19, v17, v19, v17
	v_mul_f32_e32 v18, 0x3f4c422a, v18
	v_mul_f32_e32 v19, 0x3f4c422a, v19
	v_add_f32_e32 v18, v18, v18
	v_add_f32_e32 v19, v19, v19
	v_mul_f32_e32 v18, 0xbfb8aa3b, v18
	v_mul_f32_e32 v19, 0xbfb8aa3b, v19
	v_exp_f32_e32 v18, v18
	v_exp_f32_e32 v19, v19
	v_add_f32_e32 v18, 1.0, v18
	v_add_f32_e32 v19, 1.0, v19
	v_rcp_f32_e32 v18, v18
	v_rcp_f32_e32 v19, v19
	v_mul_f32_e32 v18, v33, v18
	v_mul_f32_e32 v17, v17, v19
	v_cvt_pk_bf16_f32 v17, v18, v17
	ds_read_b128 v[26:29], v246 offset:400
	ds_read_b128 v[30:33], v246 offset:384
	s_waitcnt vmcnt(22) lgkmcnt(0)
	v_mov_b32_e32 v18, v126
	v_mov_b32_e32 v19, v127
	v_mov_b32_e32 v20, v128
	v_mov_b32_e32 v21, v129
	v_mov_b32_e32 v22, v130
	v_mov_b32_e32 v23, v131
	v_mov_b32_e32 v24, v132
	v_mov_b32_e32 v25, v133
	global_load_dwordx4 v[126:129], v[66:67], off offset:448
	global_load_dwordx4 v[130:133], v[68:69], off offset:768
	v_lshlrev_b32_e32 v38, 16, v18
	v_and_b32_e32 v18, 0xffff0000, v18
	v_lshlrev_b32_e32 v42, 16, v22
	v_and_b32_e32 v22, 0xffff0000, v22
	v_fmac_f32_e32 v18, v31, v22
	v_mul_f32_e32 v22, 0x3d372713, v18
	v_mul_f32_e32 v22, v18, v22
	v_fma_f32 v22, v18, v22, v18
	v_mul_f32_e32 v22, 0x3f4c422a, v22
	v_add_f32_e32 v22, v22, v22
	v_mul_f32_e32 v22, 0xbfb8aa3b, v22
	v_exp_f32_e32 v22, v22
	v_lshlrev_b32_e32 v39, 16, v19
	v_and_b32_e32 v19, 0xffff0000, v19
	v_lshlrev_b32_e32 v43, 16, v23
	v_add_f32_e32 v22, 1.0, v22
	v_rcp_f32_e32 v22, v22
	v_and_b32_e32 v23, 0xffff0000, v23
	v_fmac_f32_e32 v39, v32, v43
	v_fmac_f32_e32 v19, v33, v23
	v_fmac_f32_e32 v38, v30, v42
	v_mul_f32_e32 v18, v18, v22
	v_mul_f32_e32 v22, 0x3d372713, v39
	v_mul_f32_e32 v23, 0x3d372713, v19
	v_mul_f32_e32 v30, 0x3d372713, v38
	v_mul_f32_e32 v22, v39, v22
	v_mul_f32_e32 v23, v19, v23
	v_mul_f32_e32 v30, v38, v30
	v_fma_f32 v22, v39, v22, v39
	v_fma_f32 v23, v19, v23, v19
	v_fma_f32 v30, v38, v30, v38
	v_mul_f32_e32 v22, 0x3f4c422a, v22
	v_mul_f32_e32 v23, 0x3f4c422a, v23
	v_mul_f32_e32 v30, 0x3f4c422a, v30
	v_add_f32_e32 v22, v22, v22
	v_add_f32_e32 v23, v23, v23
	v_add_f32_e32 v30, v30, v30
	v_mul_f32_e32 v22, 0xbfb8aa3b, v22
	v_mul_f32_e32 v23, 0xbfb8aa3b, v23
	v_mul_f32_e32 v30, 0xbfb8aa3b, v30
	v_exp_f32_e32 v22, v22
	v_exp_f32_e32 v23, v23
	v_exp_f32_e32 v30, v30
	v_lshlrev_b32_e32 v40, 16, v20
	v_add_f32_e32 v22, 1.0, v22
	v_add_f32_e32 v23, 1.0, v23
	v_add_f32_e32 v30, 1.0, v30
	v_rcp_f32_e32 v22, v22
	v_rcp_f32_e32 v23, v23
	v_rcp_f32_e32 v30, v30
	v_and_b32_e32 v20, 0xffff0000, v20
; __device__ __forceinline__ unsigned cvt_pk_bf16(float lo, float hi) { unsigned r; asm volatile("v_cvt_pk_bf16_f32 %0, %1, %2" : "=v"(r) : "v"(lo), "v"(hi)); return r; }
; __device__ __forceinline__ float gelu_tanh(float x) { const float u = 0.7978845608028654f * (x + 0.044715f * x * x * x); return x * sigm(2.f * u); }
; #define UNPK8(VV_, XX_) float XX_[8] = {bflo((VV_).x), bfhi((VV_).x), bflo((VV_).y), bfhi((VV_).y), bflo((VV_).z), bfhi((VV_).z), bflo((VV_).w), bfhi((VV_).w)}
; __device__ __forceinline__ void glu_task(int t, int l, const float* s5d, const bf16_t* P, const bf16_t* YB, const bf16_t* WGLU, bf16_t* Z1, int fr, int fq) {
;     ...
;     for (int tb = 0; tb < 2; ++tb) { const size_t row = row0 + tb * 16;
; #pragma unroll
;         for (int ks = 0; ks < 8; ++ks) { const int k0 = ks * 32 + fq * 8; const u32x4 yw = ld8(YB + row * 256 + k0), uw = ld8(P + row * INP + OFF_S5 + k0);
;             const f32x4 d0 = *(const f32x4*)(s5d + l * 256 + k0), d1 = *(const f32x4*)(s5d + l * 256 + k0 + 4); UNPK8(yw, y); UNPK8(uw, u); u32x4 o;
;             o.x = cvt_pk_bf16(gelu_tanh(y[0] + d0[0] * u[0]), gelu_tanh(y[1] + d0[1] * u[1])); o.y = cvt_pk_bf16(gelu_tanh(y[2] + d0[2] * u[2]), gelu_tanh(y[3] + d0[3] * u[3]));
;             o.z = cvt_pk_bf16(gelu_tanh(y[4] + d1[0] * u[4]), gelu_tanh(y[5] + d1[1] * u[5])); o.w = cvt_pk_bf16(gelu_tanh(y[6] + d1[2] * u[6]), gelu_tanh(y[7] + d1[3] * u[7]));
;             bfr[tb][ks] = asfrag(o); } }
	v_lshlrev_b32_e32 v44, 16, v24
	v_and_b32_e32 v24, 0xffff0000, v24
	v_mul_f32_e32 v22, v39, v22
	v_mul_f32_e32 v19, v19, v23
	v_fmac_f32_e32 v40, v26, v44
	v_fmac_f32_e32 v20, v27, v24
	v_mul_f32_e32 v30, v38, v30
	v_cvt_pk_bf16_f32 v18, v30, v18
	v_cvt_pk_bf16_f32 v19, v22, v19
	v_mul_f32_e32 v22, 0x3d372713, v40
	v_mul_f32_e32 v23, 0x3d372713, v20
	v_mul_f32_e32 v22, v40, v22
	v_mul_f32_e32 v23, v20, v23
	v_fma_f32 v22, v40, v22, v40
	v_fma_f32 v23, v20, v23, v20
	v_mul_f32_e32 v22, 0x3f4c422a, v22
	v_mul_f32_e32 v23, 0x3f4c422a, v23
	v_add_f32_e32 v22, v22, v22
	v_add_f32_e32 v23, v23, v23
	v_mul_f32_e32 v22, 0xbfb8aa3b, v22
	v_mul_f32_e32 v23, 0xbfb8aa3b, v23
	v_exp_f32_e32 v22, v22
	v_exp_f32_e32 v23, v23
	v_lshlrev_b32_e32 v41, 16, v21
	v_and_b32_e32 v21, 0xffff0000, v21
	v_add_f32_e32 v22, 1.0, v22
	v_add_f32_e32 v23, 1.0, v23
	v_rcp_f32_e32 v22, v22
	v_rcp_f32_e32 v23, v23
	v_lshlrev_b32_e32 v45, 16, v25
	v_and_b32_e32 v25, 0xffff0000, v25
	v_mul_f32_e32 v22, v40, v22
	v_mul_f32_e32 v20, v20, v23
	v_fmac_f32_e32 v41, v28, v45
	v_fmac_f32_e32 v21, v29, v25
	v_cvt_pk_bf16_f32 v20, v22, v20
	v_mul_f32_e32 v22, 0x3d372713, v41
	v_mul_f32_e32 v23, 0x3d372713, v21
	v_mul_f32_e32 v22, v41, v22
	v_mul_f32_e32 v23, v21, v23
	v_fma_f32 v22, v41, v22, v41
	v_fma_f32 v23, v21, v23, v21
	v_mul_f32_e32 v22, 0x3f4c422a, v22
	v_mul_f32_e32 v23, 0x3f4c422a, v23
	v_add_f32_e32 v22, v22, v22
	v_add_f32_e32 v23, v23, v23
	v_mul_f32_e32 v22, 0xbfb8aa3b, v22
	v_mul_f32_e32 v23, 0xbfb8aa3b, v23
	v_exp_f32_e32 v22, v22
	v_exp_f32_e32 v23, v23
	v_add_f32_e32 v22, 1.0, v22
	v_add_f32_e32 v23, 1.0, v23
	v_rcp_f32_e32 v22, v22
	v_rcp_f32_e32 v23, v23
	v_mul_f32_e32 v22, v41, v22
	v_mul_f32_e32 v21, v21, v23
	v_cvt_pk_bf16_f32 v21, v22, v21
	ds_read_b128 v[30:33], v246 offset:528
	ds_read_b128 v[38:41], v246 offset:512
	s_waitcnt vmcnt(22) lgkmcnt(0)
	v_mov_b32_e32 v22, v140
	v_mov_b32_e32 v23, v141
	v_mov_b32_e32 v24, v142
	v_mov_b32_e32 v25, v143
	v_mov_b32_e32 v26, v144
	v_mov_b32_e32 v27, v145
	v_mov_b32_e32 v28, v146
	v_mov_b32_e32 v29, v147
	v_lshlrev_b32_e32 v42, 16, v22
	v_and_b32_e32 v22, 0xffff0000, v22
	v_lshlrev_b32_e32 v46, 16, v26
	v_and_b32_e32 v26, 0xffff0000, v26
	v_fmac_f32_e32 v22, v39, v26
	v_mul_f32_e32 v26, 0x3d372713, v22
	v_mul_f32_e32 v26, v22, v26
	v_fma_f32 v26, v22, v26, v22
	v_mul_f32_e32 v26, 0x3f4c422a, v26
	v_add_f32_e32 v26, v26, v26
	v_mul_f32_e32 v26, 0xbfb8aa3b, v26
	v_exp_f32_e32 v26, v26
	v_lshlrev_b32_e32 v43, 16, v23
	v_and_b32_e32 v23, 0xffff0000, v23
	v_lshlrev_b32_e32 v47, 16, v27
	v_add_f32_e32 v26, 1.0, v26
	v_rcp_f32_e32 v26, v26
	v_and_b32_e32 v27, 0xffff0000, v27
	v_fmac_f32_e32 v43, v40, v47
	v_fmac_f32_e32 v23, v41, v27
	v_fmac_f32_e32 v42, v38, v46
	v_mul_f32_e32 v22, v22, v26
	v_mul_f32_e32 v26, 0x3d372713, v43
	v_mul_f32_e32 v27, 0x3d372713, v23
	v_mul_f32_e32 v38, 0x3d372713, v42
	v_mul_f32_e32 v26, v43, v26
	v_mul_f32_e32 v27, v23, v27
	v_mul_f32_e32 v38, v42, v38
	v_fma_f32 v26, v43, v26, v43
	v_fma_f32 v27, v23, v27, v23
	v_fma_f32 v38, v42, v38, v42
	v_mul_f32_e32 v26, 0x3f4c422a, v26
	v_mul_f32_e32 v27, 0x3f4c422a, v27
	v_mul_f32_e32 v38, 0x3f4c422a, v38
	v_add_f32_e32 v26, v26, v26
	v_add_f32_e32 v27, v27, v27
	v_add_f32_e32 v38, v38, v38
	v_mul_f32_e32 v26, 0xbfb8aa3b, v26
	v_mul_f32_e32 v27, 0xbfb8aa3b, v27
	v_mul_f32_e32 v38, 0xbfb8aa3b, v38
	v_exp_f32_e32 v26, v26
	v_exp_f32_e32 v27, v27
	v_exp_f32_e32 v38, v38
	v_lshlrev_b32_e32 v44, 16, v24
	v_add_f32_e32 v26, 1.0, v26
	v_add_f32_e32 v27, 1.0, v27
	v_add_f32_e32 v38, 1.0, v38
	v_rcp_f32_e32 v26, v26
	v_rcp_f32_e32 v27, v27
	v_rcp_f32_e32 v38, v38
	v_and_b32_e32 v24, 0xffff0000, v24
	v_lshlrev_b32_e32 v48, 16, v28
	v_and_b32_e32 v28, 0xffff0000, v28
	v_mul_f32_e32 v26, v43, v26
	v_mul_f32_e32 v23, v23, v27
	v_fmac_f32_e32 v44, v30, v48
	v_fmac_f32_e32 v24, v31, v28
	v_mul_f32_e32 v38, v42, v38
	v_cvt_pk_bf16_f32 v22, v38, v22
	v_cvt_pk_bf16_f32 v23, v26, v23
	v_mul_f32_e32 v26, 0x3d372713, v44
	v_mul_f32_e32 v27, 0x3d372713, v24
	v_mul_f32_e32 v26, v44, v26
	v_mul_f32_e32 v27, v24, v27
	v_fma_f32 v26, v44, v26, v44
	v_fma_f32 v27, v24, v27, v24
	v_mul_f32_e32 v26, 0x3f4c422a, v26
	v_mul_f32_e32 v27, 0x3f4c422a, v27
	v_add_f32_e32 v26, v26, v26
	v_add_f32_e32 v27, v27, v27
	v_mul_f32_e32 v26, 0xbfb8aa3b, v26
	v_mul_f32_e32 v27, 0xbfb8aa3b, v27
	v_exp_f32_e32 v26, v26
	v_exp_f32_e32 v27, v27
	v_lshlrev_b32_e32 v45, 16, v25
	v_and_b32_e32 v25, 0xffff0000, v25
	v_add_f32_e32 v26, 1.0, v26
	v_add_f32_e32 v27, 1.0, v27
	v_rcp_f32_e32 v26, v26
	v_rcp_f32_e32 v27, v27
	v_lshlrev_b32_e32 v49, 16, v29
	v_and_b32_e32 v29, 0xffff0000, v29
	v_mul_f32_e32 v26, v44, v26
	v_mul_f32_e32 v24, v24, v27
	v_fmac_f32_e32 v45, v32, v49
	v_fmac_f32_e32 v25, v33, v29
	v_cvt_pk_bf16_f32 v24, v26, v24
	v_mul_f32_e32 v26, 0x3d372713, v45
	v_mul_f32_e32 v27, 0x3d372713, v25
	v_mul_f32_e32 v26, v45, v26
	v_mul_f32_e32 v27, v25, v27
	v_fma_f32 v26, v45, v26, v45
	v_fma_f32 v27, v25, v27, v25
	v_mul_f32_e32 v26, 0x3f4c422a, v26
	v_mul_f32_e32 v27, 0x3f4c422a, v27
	v_add_f32_e32 v26, v26, v26
	v_add_f32_e32 v27, v27, v27
	v_mul_f32_e32 v26, 0xbfb8aa3b, v26
	v_mul_f32_e32 v27, 0xbfb8aa3b, v27
	v_exp_f32_e32 v26, v26
	v_exp_f32_e32 v27, v27
	v_add_f32_e32 v26, 1.0, v26
	v_add_f32_e32 v27, 1.0, v27
	v_rcp_f32_e32 v26, v26
	v_rcp_f32_e32 v27, v27
	v_mul_f32_e32 v26, v45, v26
	v_mul_f32_e32 v25, v25, v27
	v_cvt_pk_bf16_f32 v25, v26, v25
	ds_read_b128 v[38:41], v246 offset:656
	ds_read_b128 v[42:45], v246 offset:640
	s_waitcnt vmcnt(20) lgkmcnt(0)
; __device__ __forceinline__ unsigned cvt_pk_bf16(float lo, float hi) { unsigned r; asm volatile("v_cvt_pk_bf16_f32 %0, %1, %2" : "=v"(r) : "v"(lo), "v"(hi)); return r; }
; __device__ __forceinline__ float gelu_tanh(float x) { const float u = 0.7978845608028654f * (x + 0.044715f * x * x * x); return x * sigm(2.f * u); }
; #define UNPK8(VV_, XX_) float XX_[8] = {bflo((VV_).x), bfhi((VV_).x), bflo((VV_).y), bfhi((VV_).y), bflo((VV_).z), bfhi((VV_).z), bflo((VV_).w), bfhi((VV_).w)}
; __device__ __forceinline__ void glu_task(int t, int l, const float* s5d, const bf16_t* P, const bf16_t* YB, const bf16_t* WGLU, bf16_t* Z1, int fr, int fq) {
;     ...
;     for (int tb = 0; tb < 2; ++tb) { const size_t row = row0 + tb * 16;
; #pragma unroll
;         for (int ks = 0; ks < 8; ++ks) { const int k0 = ks * 32 + fq * 8; const u32x4 yw = ld8(YB + row * 256 + k0), uw = ld8(P + row * INP + OFF_S5 + k0);
;             const f32x4 d0 = *(const f32x4*)(s5d + l * 256 + k0), d1 = *(const f32x4*)(s5d + l * 256 + k0 + 4); UNPK8(yw, y); UNPK8(uw, u); u32x4 o;
;             o.x = cvt_pk_bf16(gelu_tanh(y[0] + d0[0] * u[0]), gelu_tanh(y[1] + d0[1] * u[1])); o.y = cvt_pk_bf16(gelu_tanh(y[2] + d0[2] * u[2]), gelu_tanh(y[3] + d0[3] * u[3]));
;             o.z = cvt_pk_bf16(gelu_tanh(y[4] + d1[0] * u[4]), gelu_tanh(y[5] + d1[1] * u[5])); o.w = cvt_pk_bf16(gelu_tanh(y[6] + d1[2] * u[6]), gelu_tanh(y[7] + d1[3] * u[7]));
;             bfr[tb][ks] = asfrag(o); } }
	v_mov_b32_e32 v26, v160
	v_mov_b32_e32 v27, v161
	v_mov_b32_e32 v28, v162
	v_mov_b32_e32 v29, v163
	v_mov_b32_e32 v30, v164
	v_mov_b32_e32 v31, v165
	v_mov_b32_e32 v32, v166
	v_mov_b32_e32 v33, v167
	v_lshlrev_b32_e32 v46, 16, v26
	v_and_b32_e32 v26, 0xffff0000, v26
	v_lshlrev_b32_e32 v50, 16, v30
	v_and_b32_e32 v30, 0xffff0000, v30
	v_fmac_f32_e32 v26, v43, v30
	v_mul_f32_e32 v30, 0x3d372713, v26
	v_mul_f32_e32 v30, v26, v30
	v_fma_f32 v30, v26, v30, v26
	v_mul_f32_e32 v30, 0x3f4c422a, v30
	v_add_f32_e32 v30, v30, v30
	v_mul_f32_e32 v30, 0xbfb8aa3b, v30
	v_exp_f32_e32 v30, v30
	v_lshlrev_b32_e32 v47, 16, v27
	v_and_b32_e32 v27, 0xffff0000, v27
	v_lshlrev_b32_e32 v51, 16, v31
	v_add_f32_e32 v30, 1.0, v30
	v_rcp_f32_e32 v30, v30
	v_and_b32_e32 v31, 0xffff0000, v31
	v_fmac_f32_e32 v47, v44, v51
	v_fmac_f32_e32 v27, v45, v31
	v_fmac_f32_e32 v46, v42, v50
	v_mul_f32_e32 v26, v26, v30
	v_mul_f32_e32 v30, 0x3d372713, v47
	v_mul_f32_e32 v31, 0x3d372713, v27
	v_mul_f32_e32 v42, 0x3d372713, v46
	v_mul_f32_e32 v30, v47, v30
	v_mul_f32_e32 v31, v27, v31
	v_mul_f32_e32 v42, v46, v42
	v_fma_f32 v30, v47, v30, v47
	v_fma_f32 v31, v27, v31, v27
	v_fma_f32 v42, v46, v42, v46
	v_mul_f32_e32 v30, 0x3f4c422a, v30
	v_mul_f32_e32 v31, 0x3f4c422a, v31
	v_mul_f32_e32 v42, 0x3f4c422a, v42
	v_add_f32_e32 v30, v30, v30
	v_add_f32_e32 v31, v31, v31
	v_add_f32_e32 v42, v42, v42
	v_mul_f32_e32 v30, 0xbfb8aa3b, v30
	v_mul_f32_e32 v31, 0xbfb8aa3b, v31
	v_mul_f32_e32 v42, 0xbfb8aa3b, v42
	v_exp_f32_e32 v30, v30
	v_exp_f32_e32 v31, v31
	v_exp_f32_e32 v42, v42
	v_lshlrev_b32_e32 v48, 16, v28
	v_add_f32_e32 v30, 1.0, v30
	v_add_f32_e32 v31, 1.0, v31
	v_add_f32_e32 v42, 1.0, v42
	v_rcp_f32_e32 v30, v30
	v_rcp_f32_e32 v31, v31
	v_rcp_f32_e32 v42, v42
	v_and_b32_e32 v28, 0xffff0000, v28
	v_lshlrev_b32_e32 v52, 16, v32
	v_and_b32_e32 v32, 0xffff0000, v32
	v_mul_f32_e32 v30, v47, v30
	v_mul_f32_e32 v27, v27, v31
	v_fmac_f32_e32 v48, v38, v52
	v_fmac_f32_e32 v28, v39, v32
	v_mul_f32_e32 v42, v46, v42
	v_cvt_pk_bf16_f32 v26, v42, v26
	v_cvt_pk_bf16_f32 v27, v30, v27
	v_mul_f32_e32 v30, 0x3d372713, v48
	v_mul_f32_e32 v31, 0x3d372713, v28
	v_mul_f32_e32 v30, v48, v30
	v_mul_f32_e32 v31, v28, v31
	v_fma_f32 v30, v48, v30, v48
	v_fma_f32 v31, v28, v31, v28
	v_mul_f32_e32 v30, 0x3f4c422a, v30
	v_mul_f32_e32 v31, 0x3f4c422a, v31
	v_add_f32_e32 v30, v30, v30
	v_add_f32_e32 v31, v31, v31
	v_mul_f32_e32 v30, 0xbfb8aa3b, v30
	v_mul_f32_e32 v31, 0xbfb8aa3b, v31
	v_exp_f32_e32 v30, v30
	v_exp_f32_e32 v31, v31
	v_lshlrev_b32_e32 v49, 16, v29
	v_and_b32_e32 v29, 0xffff0000, v29
	v_add_f32_e32 v30, 1.0, v30
	v_add_f32_e32 v31, 1.0, v31
	v_rcp_f32_e32 v30, v30
	v_rcp_f32_e32 v31, v31
	v_lshlrev_b32_e32 v53, 16, v33
	v_and_b32_e32 v33, 0xffff0000, v33
	v_mul_f32_e32 v30, v48, v30
	v_mul_f32_e32 v28, v28, v31
	v_fmac_f32_e32 v49, v40, v53
	v_fmac_f32_e32 v29, v41, v33
	v_cvt_pk_bf16_f32 v28, v30, v28
	v_mul_f32_e32 v30, 0x3d372713, v49
	v_mul_f32_e32 v31, 0x3d372713, v29
	v_mul_f32_e32 v30, v49, v30
	v_mul_f32_e32 v31, v29, v31
	v_fma_f32 v30, v49, v30, v49
	v_fma_f32 v31, v29, v31, v29
	v_mul_f32_e32 v30, 0x3f4c422a, v30
	v_mul_f32_e32 v31, 0x3f4c422a, v31
	v_add_f32_e32 v30, v30, v30
	v_add_f32_e32 v31, v31, v31
	v_mul_f32_e32 v30, 0xbfb8aa3b, v30
	v_mul_f32_e32 v31, 0xbfb8aa3b, v31
	v_exp_f32_e32 v30, v30
	v_exp_f32_e32 v31, v31
	v_add_f32_e32 v30, 1.0, v30
	v_add_f32_e32 v31, 1.0, v31
	v_rcp_f32_e32 v30, v30
	v_rcp_f32_e32 v31, v31
	v_mul_f32_e32 v30, v49, v30
	v_mul_f32_e32 v29, v29, v31
	v_cvt_pk_bf16_f32 v29, v30, v29
	ds_read_b128 v[42:45], v246 offset:784
	ds_read_b128 v[46:49], v246 offset:768
	s_waitcnt vmcnt(18) lgkmcnt(0)
	v_mov_b32_e32 v30, v180
	v_mov_b32_e32 v31, v181
	v_mov_b32_e32 v32, v182
	v_mov_b32_e32 v33, v183
	v_mov_b32_e32 v38, v184
	v_mov_b32_e32 v39, v185
	v_mov_b32_e32 v40, v186
	v_mov_b32_e32 v41, v187
	v_lshlrev_b32_e32 v50, 16, v30
	v_and_b32_e32 v30, 0xffff0000, v30
	v_lshlrev_b32_e32 v54, 16, v38
	v_and_b32_e32 v38, 0xffff0000, v38
	v_fmac_f32_e32 v30, v47, v38
	v_mul_f32_e32 v38, 0x3d372713, v30
	v_mul_f32_e32 v38, v30, v38
	v_fma_f32 v38, v30, v38, v30
	v_mul_f32_e32 v38, 0x3f4c422a, v38
	v_add_f32_e32 v38, v38, v38
	v_mul_f32_e32 v38, 0xbfb8aa3b, v38
	v_exp_f32_e32 v38, v38
	v_lshlrev_b32_e32 v51, 16, v31
	v_and_b32_e32 v31, 0xffff0000, v31
	v_lshlrev_b32_e32 v55, 16, v39
	v_add_f32_e32 v38, 1.0, v38
	v_rcp_f32_e32 v38, v38
	v_and_b32_e32 v39, 0xffff0000, v39
	v_fmac_f32_e32 v51, v48, v55
	v_fmac_f32_e32 v31, v49, v39
	v_fmac_f32_e32 v50, v46, v54
	v_mul_f32_e32 v30, v30, v38
	v_mul_f32_e32 v38, 0x3d372713, v51
	v_mul_f32_e32 v39, 0x3d372713, v31
	v_mul_f32_e32 v46, 0x3d372713, v50
	v_mul_f32_e32 v38, v51, v38
	v_mul_f32_e32 v39, v31, v39
	v_mul_f32_e32 v46, v50, v46
	v_fma_f32 v38, v51, v38, v51
	v_fma_f32 v39, v31, v39, v31
	v_fma_f32 v46, v50, v46, v50
	v_mul_f32_e32 v38, 0x3f4c422a, v38
	v_mul_f32_e32 v39, 0x3f4c422a, v39
	v_mul_f32_e32 v46, 0x3f4c422a, v46
	v_add_f32_e32 v38, v38, v38
	v_add_f32_e32 v39, v39, v39
	v_add_f32_e32 v46, v46, v46
	v_mul_f32_e32 v38, 0xbfb8aa3b, v38
	v_mul_f32_e32 v39, 0xbfb8aa3b, v39
	v_mul_f32_e32 v46, 0xbfb8aa3b, v46
	v_exp_f32_e32 v38, v38
	v_exp_f32_e32 v39, v39
	v_exp_f32_e32 v46, v46
	v_lshlrev_b32_e32 v52, 16, v32
	v_add_f32_e32 v38, 1.0, v38
	v_add_f32_e32 v39, 1.0, v39
	v_add_f32_e32 v46, 1.0, v46
	v_rcp_f32_e32 v38, v38
	v_rcp_f32_e32 v39, v39
	v_rcp_f32_e32 v46, v46
	v_and_b32_e32 v32, 0xffff0000, v32
	v_lshlrev_b32_e32 v56, 16, v40
	v_and_b32_e32 v40, 0xffff0000, v40
	v_mul_f32_e32 v38, v51, v38
	v_mul_f32_e32 v31, v31, v39
	v_fmac_f32_e32 v52, v42, v56
	v_fmac_f32_e32 v32, v43, v40
	v_mul_f32_e32 v46, v50, v46
; __device__ __forceinline__ unsigned cvt_pk_bf16(float lo, float hi) { unsigned r; asm volatile("v_cvt_pk_bf16_f32 %0, %1, %2" : "=v"(r) : "v"(lo), "v"(hi)); return r; }
; __device__ __forceinline__ float gelu_tanh(float x) { const float u = 0.7978845608028654f * (x + 0.044715f * x * x * x); return x * sigm(2.f * u); }
; #define UNPK8(VV_, XX_) float XX_[8] = {bflo((VV_).x), bfhi((VV_).x), bflo((VV_).y), bfhi((VV_).y), bflo((VV_).z), bfhi((VV_).z), bflo((VV_).w), bfhi((VV_).w)}
; __device__ __forceinline__ void glu_task(int t, int l, const float* s5d, const bf16_t* P, const bf16_t* YB, const bf16_t* WGLU, bf16_t* Z1, int fr, int fq) {
;     ...
;     for (int tb = 0; tb < 2; ++tb) { const size_t row = row0 + tb * 16;
; #pragma unroll
;         for (int ks = 0; ks < 8; ++ks) { const int k0 = ks * 32 + fq * 8; const u32x4 yw = ld8(YB + row * 256 + k0), uw = ld8(P + row * INP + OFF_S5 + k0);
;             const f32x4 d0 = *(const f32x4*)(s5d + l * 256 + k0), d1 = *(const f32x4*)(s5d + l * 256 + k0 + 4); UNPK8(yw, y); UNPK8(uw, u); u32x4 o;
;             o.x = cvt_pk_bf16(gelu_tanh(y[0] + d0[0] * u[0]), gelu_tanh(y[1] + d0[1] * u[1])); o.y = cvt_pk_bf16(gelu_tanh(y[2] + d0[2] * u[2]), gelu_tanh(y[3] + d0[3] * u[3]));
;             o.z = cvt_pk_bf16(gelu_tanh(y[4] + d1[0] * u[4]), gelu_tanh(y[5] + d1[1] * u[5])); o.w = cvt_pk_bf16(gelu_tanh(y[6] + d1[2] * u[6]), gelu_tanh(y[7] + d1[3] * u[7]));
;             bfr[tb][ks] = asfrag(o); } }
	v_cvt_pk_bf16_f32 v30, v46, v30
	v_cvt_pk_bf16_f32 v31, v38, v31
	v_mul_f32_e32 v38, 0x3d372713, v52
	v_mul_f32_e32 v39, 0x3d372713, v32
	v_mul_f32_e32 v38, v52, v38
	v_mul_f32_e32 v39, v32, v39
	v_fma_f32 v38, v52, v38, v52
	v_fma_f32 v39, v32, v39, v32
	v_mul_f32_e32 v38, 0x3f4c422a, v38
	v_mul_f32_e32 v39, 0x3f4c422a, v39
	v_add_f32_e32 v38, v38, v38
	v_add_f32_e32 v39, v39, v39
	v_mul_f32_e32 v38, 0xbfb8aa3b, v38
	v_mul_f32_e32 v39, 0xbfb8aa3b, v39
	v_exp_f32_e32 v38, v38
	v_exp_f32_e32 v39, v39
	v_lshlrev_b32_e32 v53, 16, v33
	v_and_b32_e32 v33, 0xffff0000, v33
	v_add_f32_e32 v38, 1.0, v38
	v_add_f32_e32 v39, 1.0, v39
	v_rcp_f32_e32 v38, v38
	v_rcp_f32_e32 v39, v39
	v_lshlrev_b32_e32 v57, 16, v41
	v_and_b32_e32 v41, 0xffff0000, v41
	v_mul_f32_e32 v38, v52, v38
	v_mul_f32_e32 v32, v32, v39
	v_fmac_f32_e32 v53, v44, v57
	v_fmac_f32_e32 v33, v45, v41
	v_cvt_pk_bf16_f32 v32, v38, v32
	v_mul_f32_e32 v38, 0x3d372713, v53
	v_mul_f32_e32 v39, 0x3d372713, v33
	v_mul_f32_e32 v38, v53, v38
	v_mul_f32_e32 v39, v33, v39
	v_fma_f32 v38, v53, v38, v53
	v_fma_f32 v39, v33, v39, v33
	v_mul_f32_e32 v38, 0x3f4c422a, v38
	v_mul_f32_e32 v39, 0x3f4c422a, v39
	v_add_f32_e32 v38, v38, v38
	v_add_f32_e32 v39, v39, v39
	v_mul_f32_e32 v38, 0xbfb8aa3b, v38
	v_mul_f32_e32 v39, 0xbfb8aa3b, v39
	v_exp_f32_e32 v38, v38
	v_exp_f32_e32 v39, v39
	v_add_f32_e32 v38, 1.0, v38
	v_add_f32_e32 v39, 1.0, v39
	v_rcp_f32_e32 v38, v38
	v_rcp_f32_e32 v39, v39
	v_mul_f32_e32 v38, v53, v38
	v_mul_f32_e32 v33, v33, v39
	v_cvt_pk_bf16_f32 v33, v38, v33
	s_nop 0
	s_nop 0
	ds_read_b128 v[42:45], v246 offset:912
	ds_read_b128 v[46:49], v246 offset:896
	s_waitcnt vmcnt(16) lgkmcnt(0)
	v_mov_b32_e32 v38, v214
	v_mov_b32_e32 v39, v215
	v_mov_b32_e32 v40, v216
	v_mov_b32_e32 v41, v217
	v_mov_b32_e32 v34, v218
	v_mov_b32_e32 v35, v219
	v_mov_b32_e32 v36, v220
	v_mov_b32_e32 v37, v221
	v_lshlrev_b32_e32 v50, 16, v38
	v_and_b32_e32 v38, 0xffff0000, v38
	v_lshlrev_b32_e32 v54, 16, v34
	v_and_b32_e32 v34, 0xffff0000, v34
	v_fmac_f32_e32 v38, v47, v34
	v_mul_f32_e32 v34, 0x3d372713, v38
	v_mul_f32_e32 v34, v38, v34
	v_fma_f32 v34, v38, v34, v38
	v_mul_f32_e32 v34, 0x3f4c422a, v34
	v_add_f32_e32 v34, v34, v34
	v_mul_f32_e32 v34, 0xbfb8aa3b, v34
	v_exp_f32_e32 v34, v34
	v_lshlrev_b32_e32 v51, 16, v39
	v_and_b32_e32 v39, 0xffff0000, v39
	v_lshlrev_b32_e32 v55, 16, v35
	v_add_f32_e32 v34, 1.0, v34
	v_rcp_f32_e32 v34, v34
	v_and_b32_e32 v35, 0xffff0000, v35
	v_fmac_f32_e32 v51, v48, v55
	v_fmac_f32_e32 v39, v49, v35
	v_fmac_f32_e32 v50, v46, v54
	v_mul_f32_e32 v34, v38, v34
	v_mul_f32_e32 v38, 0x3d372713, v51
	v_mul_f32_e32 v35, 0x3d372713, v39
	v_mul_f32_e32 v46, 0x3d372713, v50
	v_mul_f32_e32 v38, v51, v38
	v_mul_f32_e32 v35, v39, v35
	v_mul_f32_e32 v46, v50, v46
	v_fma_f32 v38, v51, v38, v51
	v_fma_f32 v35, v39, v35, v39
	v_fma_f32 v46, v50, v46, v50
	v_mul_f32_e32 v38, 0x3f4c422a, v38
	v_mul_f32_e32 v35, 0x3f4c422a, v35
	v_mul_f32_e32 v46, 0x3f4c422a, v46
	v_add_f32_e32 v38, v38, v38
	v_add_f32_e32 v35, v35, v35
	v_add_f32_e32 v46, v46, v46
	v_mul_f32_e32 v38, 0xbfb8aa3b, v38
	v_mul_f32_e32 v35, 0xbfb8aa3b, v35
	v_mul_f32_e32 v46, 0xbfb8aa3b, v46
	v_exp_f32_e32 v38, v38
	v_exp_f32_e32 v35, v35
	v_exp_f32_e32 v46, v46
	v_lshlrev_b32_e32 v52, 16, v40
	v_add_f32_e32 v38, 1.0, v38
	v_add_f32_e32 v35, 1.0, v35
	v_add_f32_e32 v46, 1.0, v46
	v_rcp_f32_e32 v38, v38
	v_rcp_f32_e32 v35, v35
	v_rcp_f32_e32 v46, v46
	v_and_b32_e32 v40, 0xffff0000, v40
	v_lshlrev_b32_e32 v56, 16, v36
	v_and_b32_e32 v36, 0xffff0000, v36
	v_mul_f32_e32 v38, v51, v38
	v_mul_f32_e32 v35, v39, v35
	v_fmac_f32_e32 v52, v42, v56
	v_fmac_f32_e32 v40, v43, v36
	v_mul_f32_e32 v46, v50, v46
	v_cvt_pk_bf16_f32 v34, v46, v34
	v_cvt_pk_bf16_f32 v35, v38, v35
	v_mul_f32_e32 v38, 0x3d372713, v52
	v_mul_f32_e32 v36, 0x3d372713, v40
	v_mul_f32_e32 v38, v52, v38
	v_mul_f32_e32 v36, v40, v36
	v_fma_f32 v38, v52, v38, v52
	v_fma_f32 v36, v40, v36, v40
	v_mul_f32_e32 v38, 0x3f4c422a, v38
	v_mul_f32_e32 v36, 0x3f4c422a, v36
	v_add_f32_e32 v38, v38, v38
	v_add_f32_e32 v36, v36, v36
	v_mul_f32_e32 v38, 0xbfb8aa3b, v38
	v_mul_f32_e32 v36, 0xbfb8aa3b, v36
	v_exp_f32_e32 v38, v38
	v_exp_f32_e32 v36, v36
	v_lshlrev_b32_e32 v53, 16, v41
	v_and_b32_e32 v41, 0xffff0000, v41
	v_add_f32_e32 v38, 1.0, v38
	v_add_f32_e32 v36, 1.0, v36
	v_rcp_f32_e32 v38, v38
	v_rcp_f32_e32 v36, v36
	v_lshlrev_b32_e32 v57, 16, v37
	v_and_b32_e32 v37, 0xffff0000, v37
	v_mul_f32_e32 v38, v52, v38
	v_mul_f32_e32 v36, v40, v36
	v_fmac_f32_e32 v53, v44, v57
	v_fmac_f32_e32 v41, v45, v37
	v_cvt_pk_bf16_f32 v36, v38, v36
	v_mul_f32_e32 v38, 0x3d372713, v53
	v_mul_f32_e32 v37, 0x3d372713, v41
	v_mul_f32_e32 v38, v53, v38
	v_mul_f32_e32 v37, v41, v37
	v_fma_f32 v38, v53, v38, v53
	v_fma_f32 v37, v41, v37, v41
	v_mul_f32_e32 v38, 0x3f4c422a, v38
	v_mul_f32_e32 v37, 0x3f4c422a, v37
	v_add_f32_e32 v38, v38, v38
	v_add_f32_e32 v37, v37, v37
	v_mul_f32_e32 v38, 0xbfb8aa3b, v38
	v_mul_f32_e32 v37, 0xbfb8aa3b, v37
	v_exp_f32_e32 v38, v38
	v_exp_f32_e32 v37, v37
	v_add_f32_e32 v38, 1.0, v38
	v_add_f32_e32 v37, 1.0, v37
	v_rcp_f32_e32 v38, v38
	v_rcp_f32_e32 v37, v37
	v_mul_f32_e32 v38, v53, v38
	v_mul_f32_e32 v37, v41, v37
	v_cvt_pk_bf16_f32 v37, v38, v37
	ds_read_b128 v[46:49], v246 offset:16
	ds_read_b128 v[50:53], v246
	s_waitcnt vmcnt(14) lgkmcnt(0)
; __device__ __forceinline__ unsigned cvt_pk_bf16(float lo, float hi) { unsigned r; asm volatile("v_cvt_pk_bf16_f32 %0, %1, %2" : "=v"(r) : "v"(lo), "v"(hi)); return r; }
; __device__ __forceinline__ float gelu_tanh(float x) { const float u = 0.7978845608028654f * (x + 0.044715f * x * x * x); return x * sigm(2.f * u); }
; #define UNPK8(VV_, XX_) float XX_[8] = {bflo((VV_).x), bfhi((VV_).x), bflo((VV_).y), bfhi((VV_).y), bflo((VV_).z), bfhi((VV_).z), bflo((VV_).w), bfhi((VV_).w)}
; __device__ __forceinline__ void glu_task(int t, int l, const float* s5d, const bf16_t* P, const bf16_t* YB, const bf16_t* WGLU, bf16_t* Z1, int fr, int fq) {
;     ...
;     for (int tb = 0; tb < 2; ++tb) { const size_t row = row0 + tb * 16;
; #pragma unroll
;         for (int ks = 0; ks < 8; ++ks) { const int k0 = ks * 32 + fq * 8; const u32x4 yw = ld8(YB + row * 256 + k0), uw = ld8(P + row * INP + OFF_S5 + k0);
;             const f32x4 d0 = *(const f32x4*)(s5d + l * 256 + k0), d1 = *(const f32x4*)(s5d + l * 256 + k0 + 4); UNPK8(yw, y); UNPK8(uw, u); u32x4 o;
;             o.x = cvt_pk_bf16(gelu_tanh(y[0] + d0[0] * u[0]), gelu_tanh(y[1] + d0[1] * u[1])); o.y = cvt_pk_bf16(gelu_tanh(y[2] + d0[2] * u[2]), gelu_tanh(y[3] + d0[3] * u[3]));
;             o.z = cvt_pk_bf16(gelu_tanh(y[4] + d1[0] * u[4]), gelu_tanh(y[5] + d1[1] * u[5])); o.w = cvt_pk_bf16(gelu_tanh(y[6] + d1[2] * u[6]), gelu_tanh(y[7] + d1[3] * u[7]));
;             bfr[tb][ks] = asfrag(o); } }
	v_mov_b32_e32 v38, v222
	v_mov_b32_e32 v39, v223
	v_mov_b32_e32 v40, v224
	v_mov_b32_e32 v41, v225
	v_mov_b32_e32 v42, v226
	v_mov_b32_e32 v43, v227
	v_mov_b32_e32 v44, v228
	v_mov_b32_e32 v45, v229
	v_lshlrev_b32_e32 v58, 16, v42
	v_lshlrev_b32_e32 v54, 16, v38
	v_and_b32_e32 v38, 0xffff0000, v38
	v_and_b32_e32 v42, 0xffff0000, v42
	v_fmac_f32_e32 v38, v51, v42
	v_mul_f32_e32 v42, 0x3d372713, v38
	v_mul_f32_e32 v42, v38, v42
	v_fma_f32 v42, v38, v42, v38
	v_mul_f32_e32 v42, 0x3f4c422a, v42
	v_add_f32_e32 v42, v42, v42
	v_mul_f32_e32 v42, 0xbfb8aa3b, v42
	v_exp_f32_e32 v42, v42
	v_lshlrev_b32_e32 v55, 16, v39
	v_and_b32_e32 v39, 0xffff0000, v39
	v_lshlrev_b32_e32 v59, 16, v43
	v_add_f32_e32 v42, 1.0, v42
	v_rcp_f32_e32 v42, v42
	v_and_b32_e32 v43, 0xffff0000, v43
	v_fmac_f32_e32 v55, v52, v59
	v_fmac_f32_e32 v39, v53, v43
	v_fmac_f32_e32 v54, v50, v58
	v_mul_f32_e32 v38, v38, v42
	v_mul_f32_e32 v42, 0x3d372713, v55
	v_mul_f32_e32 v43, 0x3d372713, v39
	v_mul_f32_e32 v50, 0x3d372713, v54
	v_mul_f32_e32 v42, v55, v42
	v_mul_f32_e32 v43, v39, v43
	v_mul_f32_e32 v50, v54, v50
	v_fma_f32 v42, v55, v42, v55
	v_fma_f32 v43, v39, v43, v39
	v_fma_f32 v50, v54, v50, v54
	v_mul_f32_e32 v42, 0x3f4c422a, v42
	v_mul_f32_e32 v43, 0x3f4c422a, v43
	v_mul_f32_e32 v50, 0x3f4c422a, v50
	v_add_f32_e32 v42, v42, v42
	v_add_f32_e32 v43, v43, v43
	v_add_f32_e32 v50, v50, v50
	v_mul_f32_e32 v42, 0xbfb8aa3b, v42
	v_mul_f32_e32 v43, 0xbfb8aa3b, v43
	v_mul_f32_e32 v50, 0xbfb8aa3b, v50
	v_exp_f32_e32 v42, v42
	v_exp_f32_e32 v43, v43
	v_exp_f32_e32 v50, v50
	v_lshlrev_b32_e32 v56, 16, v40
	v_add_f32_e32 v42, 1.0, v42
	v_add_f32_e32 v43, 1.0, v43
	v_add_f32_e32 v50, 1.0, v50
	v_rcp_f32_e32 v42, v42
	v_rcp_f32_e32 v43, v43
	v_rcp_f32_e32 v50, v50
	v_and_b32_e32 v40, 0xffff0000, v40
	v_lshlrev_b32_e32 v60, 16, v44
	v_and_b32_e32 v44, 0xffff0000, v44
	v_mul_f32_e32 v42, v55, v42
	v_mul_f32_e32 v39, v39, v43
	v_fmac_f32_e32 v56, v46, v60
	v_fmac_f32_e32 v40, v47, v44
	v_mul_f32_e32 v50, v54, v50
	v_cvt_pk_bf16_f32 v38, v50, v38
	v_cvt_pk_bf16_f32 v39, v42, v39
	v_mul_f32_e32 v42, 0x3d372713, v56
	v_mul_f32_e32 v43, 0x3d372713, v40
	v_mul_f32_e32 v42, v56, v42
	v_mul_f32_e32 v43, v40, v43
	v_fma_f32 v42, v56, v42, v56
	v_fma_f32 v43, v40, v43, v40
	v_mul_f32_e32 v42, 0x3f4c422a, v42
	v_mul_f32_e32 v43, 0x3f4c422a, v43
	v_add_f32_e32 v42, v42, v42
	v_add_f32_e32 v43, v43, v43
	v_mul_f32_e32 v42, 0xbfb8aa3b, v42
	v_mul_f32_e32 v43, 0xbfb8aa3b, v43
	v_exp_f32_e32 v42, v42
	v_exp_f32_e32 v43, v43
	v_lshlrev_b32_e32 v57, 16, v41
	v_and_b32_e32 v41, 0xffff0000, v41
	v_add_f32_e32 v42, 1.0, v42
	v_add_f32_e32 v43, 1.0, v43
	v_rcp_f32_e32 v42, v42
	v_rcp_f32_e32 v43, v43
	v_lshlrev_b32_e32 v61, 16, v45
	v_and_b32_e32 v45, 0xffff0000, v45
	v_mul_f32_e32 v42, v56, v42
	v_mul_f32_e32 v40, v40, v43
	v_fmac_f32_e32 v57, v48, v61
	v_fmac_f32_e32 v41, v49, v45
	v_cvt_pk_bf16_f32 v40, v42, v40
	v_mul_f32_e32 v42, 0x3d372713, v57
	v_mul_f32_e32 v43, 0x3d372713, v41
	v_mul_f32_e32 v42, v57, v42
	v_mul_f32_e32 v43, v41, v43
	v_fma_f32 v42, v57, v42, v57
	v_fma_f32 v43, v41, v43, v41
	v_mul_f32_e32 v42, 0x3f4c422a, v42
	v_mul_f32_e32 v43, 0x3f4c422a, v43
	v_add_f32_e32 v42, v42, v42
	v_add_f32_e32 v43, v43, v43
	v_mul_f32_e32 v42, 0xbfb8aa3b, v42
	v_mul_f32_e32 v43, 0xbfb8aa3b, v43
	v_exp_f32_e32 v42, v42
	v_exp_f32_e32 v43, v43
	v_add_f32_e32 v42, 1.0, v42
	v_add_f32_e32 v43, 1.0, v43
	v_rcp_f32_e32 v42, v42
	v_rcp_f32_e32 v43, v43
	v_mul_f32_e32 v42, v57, v42
	v_mul_f32_e32 v41, v41, v43
	v_cvt_pk_bf16_f32 v41, v42, v41
	ds_read_b128 v[50:53], v246 offset:144
	ds_read_b128 v[54:57], v246 offset:128
	s_waitcnt vmcnt(12) lgkmcnt(0)
	v_mov_b32_e32 v42, v230
	v_mov_b32_e32 v43, v231
	v_mov_b32_e32 v44, v232
	v_mov_b32_e32 v45, v233
	v_mov_b32_e32 v46, v234
	v_mov_b32_e32 v47, v235
	v_mov_b32_e32 v48, v236
	v_mov_b32_e32 v49, v237
	v_lshlrev_b32_e32 v58, 16, v42
	v_and_b32_e32 v42, 0xffff0000, v42
	v_lshlrev_b32_e32 v62, 16, v46
	v_and_b32_e32 v46, 0xffff0000, v46
	v_fmac_f32_e32 v42, v55, v46
	v_mul_f32_e32 v46, 0x3d372713, v42
	v_mul_f32_e32 v46, v42, v46
	v_fma_f32 v46, v42, v46, v42
	v_mul_f32_e32 v46, 0x3f4c422a, v46
	v_add_f32_e32 v46, v46, v46
	v_mul_f32_e32 v46, 0xbfb8aa3b, v46
	v_exp_f32_e32 v46, v46
	v_lshlrev_b32_e32 v59, 16, v43
	v_and_b32_e32 v43, 0xffff0000, v43
	v_lshlrev_b32_e32 v63, 16, v47
	v_add_f32_e32 v46, 1.0, v46
	v_rcp_f32_e32 v46, v46
	v_and_b32_e32 v47, 0xffff0000, v47
	v_fmac_f32_e32 v59, v56, v63
	v_fmac_f32_e32 v43, v57, v47
	v_fmac_f32_e32 v58, v54, v62
	v_mul_f32_e32 v42, v42, v46
	v_mul_f32_e32 v46, 0x3d372713, v59
	v_mul_f32_e32 v47, 0x3d372713, v43
	v_mul_f32_e32 v54, 0x3d372713, v58
	v_mul_f32_e32 v46, v59, v46
	v_mul_f32_e32 v47, v43, v47
	v_mul_f32_e32 v54, v58, v54
	v_fma_f32 v46, v59, v46, v59
	v_fma_f32 v47, v43, v47, v43
	v_fma_f32 v54, v58, v54, v58
	v_mul_f32_e32 v46, 0x3f4c422a, v46
	v_mul_f32_e32 v47, 0x3f4c422a, v47
	v_mul_f32_e32 v54, 0x3f4c422a, v54
	v_add_f32_e32 v46, v46, v46
	v_add_f32_e32 v47, v47, v47
	v_add_f32_e32 v54, v54, v54
	v_mul_f32_e32 v46, 0xbfb8aa3b, v46
	v_mul_f32_e32 v47, 0xbfb8aa3b, v47
	v_mul_f32_e32 v54, 0xbfb8aa3b, v54
	v_exp_f32_e32 v46, v46
	v_exp_f32_e32 v47, v47
	v_exp_f32_e32 v54, v54
	v_lshlrev_b32_e32 v60, 16, v44
	v_add_f32_e32 v46, 1.0, v46
	v_add_f32_e32 v47, 1.0, v47
	v_add_f32_e32 v54, 1.0, v54
	v_rcp_f32_e32 v46, v46
	v_rcp_f32_e32 v47, v47
	v_rcp_f32_e32 v54, v54
	v_and_b32_e32 v44, 0xffff0000, v44
	v_lshlrev_b32_e32 v64, 16, v48
	v_and_b32_e32 v48, 0xffff0000, v48
	v_mul_f32_e32 v46, v59, v46
	v_mul_f32_e32 v43, v43, v47
	v_fmac_f32_e32 v60, v50, v64
	v_fmac_f32_e32 v44, v51, v48
	v_mul_f32_e32 v54, v58, v54
; __device__ __forceinline__ unsigned cvt_pk_bf16(float lo, float hi) { unsigned r; asm volatile("v_cvt_pk_bf16_f32 %0, %1, %2" : "=v"(r) : "v"(lo), "v"(hi)); return r; }
; __device__ __forceinline__ float gelu_tanh(float x) { const float u = 0.7978845608028654f * (x + 0.044715f * x * x * x); return x * sigm(2.f * u); }
; #define UNPK8(VV_, XX_) float XX_[8] = {bflo((VV_).x), bfhi((VV_).x), bflo((VV_).y), bfhi((VV_).y), bflo((VV_).z), bfhi((VV_).z), bflo((VV_).w), bfhi((VV_).w)}
; __device__ __forceinline__ void glu_task(int t, int l, const float* s5d, const bf16_t* P, const bf16_t* YB, const bf16_t* WGLU, bf16_t* Z1, int fr, int fq) {
;     ...
;     for (int tb = 0; tb < 2; ++tb) { const size_t row = row0 + tb * 16;
; #pragma unroll
;         for (int ks = 0; ks < 8; ++ks) { const int k0 = ks * 32 + fq * 8; const u32x4 yw = ld8(YB + row * 256 + k0), uw = ld8(P + row * INP + OFF_S5 + k0);
;             const f32x4 d0 = *(const f32x4*)(s5d + l * 256 + k0), d1 = *(const f32x4*)(s5d + l * 256 + k0 + 4); UNPK8(yw, y); UNPK8(uw, u); u32x4 o;
;             o.x = cvt_pk_bf16(gelu_tanh(y[0] + d0[0] * u[0]), gelu_tanh(y[1] + d0[1] * u[1])); o.y = cvt_pk_bf16(gelu_tanh(y[2] + d0[2] * u[2]), gelu_tanh(y[3] + d0[3] * u[3]));
;             o.z = cvt_pk_bf16(gelu_tanh(y[4] + d1[0] * u[4]), gelu_tanh(y[5] + d1[1] * u[5])); o.w = cvt_pk_bf16(gelu_tanh(y[6] + d1[2] * u[6]), gelu_tanh(y[7] + d1[3] * u[7]));
;             bfr[tb][ks] = asfrag(o); } }
	v_cvt_pk_bf16_f32 v42, v54, v42
	v_cvt_pk_bf16_f32 v43, v46, v43
	v_mul_f32_e32 v46, 0x3d372713, v60
	v_mul_f32_e32 v47, 0x3d372713, v44
	v_mul_f32_e32 v46, v60, v46
	v_mul_f32_e32 v47, v44, v47
	v_fma_f32 v46, v60, v46, v60
	v_fma_f32 v47, v44, v47, v44
	v_mul_f32_e32 v46, 0x3f4c422a, v46
	v_mul_f32_e32 v47, 0x3f4c422a, v47
	v_add_f32_e32 v46, v46, v46
	v_add_f32_e32 v47, v47, v47
	v_mul_f32_e32 v46, 0xbfb8aa3b, v46
	v_mul_f32_e32 v47, 0xbfb8aa3b, v47
	v_exp_f32_e32 v46, v46
	v_exp_f32_e32 v47, v47
	v_lshlrev_b32_e32 v61, 16, v45
	v_and_b32_e32 v45, 0xffff0000, v45
	v_add_f32_e32 v46, 1.0, v46
	v_add_f32_e32 v47, 1.0, v47
	v_rcp_f32_e32 v46, v46
	v_rcp_f32_e32 v47, v47
	v_lshlrev_b32_e32 v65, 16, v49
	v_and_b32_e32 v49, 0xffff0000, v49
	v_mul_f32_e32 v46, v60, v46
	v_mul_f32_e32 v44, v44, v47
	v_fmac_f32_e32 v61, v52, v65
	v_fmac_f32_e32 v45, v53, v49
	v_cvt_pk_bf16_f32 v44, v46, v44
	v_mul_f32_e32 v46, 0x3d372713, v61
	v_mul_f32_e32 v47, 0x3d372713, v45
	v_mul_f32_e32 v46, v61, v46
	v_mul_f32_e32 v47, v45, v47
	v_fma_f32 v46, v61, v46, v61
	v_fma_f32 v47, v45, v47, v45
	v_mul_f32_e32 v46, 0x3f4c422a, v46
	v_mul_f32_e32 v47, 0x3f4c422a, v47
	v_add_f32_e32 v46, v46, v46
	v_add_f32_e32 v47, v47, v47
	v_mul_f32_e32 v46, 0xbfb8aa3b, v46
	v_mul_f32_e32 v47, 0xbfb8aa3b, v47
	v_exp_f32_e32 v46, v46
	v_exp_f32_e32 v47, v47
	v_add_f32_e32 v46, 1.0, v46
	v_add_f32_e32 v47, 1.0, v47
	v_rcp_f32_e32 v46, v46
	v_rcp_f32_e32 v47, v47
	v_mul_f32_e32 v46, v61, v46
	v_mul_f32_e32 v45, v45, v47
	v_cvt_pk_bf16_f32 v45, v46, v45
	ds_read_b128 v[54:57], v246 offset:272
	ds_read_b128 v[58:61], v246 offset:256
	s_waitcnt vmcnt(10) lgkmcnt(0)
	v_mov_b32_e32 v46, v238
	v_mov_b32_e32 v47, v239
	v_mov_b32_e32 v48, v240
	v_mov_b32_e32 v49, v241
	v_mov_b32_e32 v50, v242
	v_mov_b32_e32 v51, v243
	v_mov_b32_e32 v52, v244
	v_mov_b32_e32 v53, v245
	v_lshlrev_b32_e32 v62, 16, v46
	v_and_b32_e32 v46, 0xffff0000, v46
	v_lshlrev_b32_e32 v78, 16, v50
	v_and_b32_e32 v50, 0xffff0000, v50
	v_fmac_f32_e32 v46, v59, v50
	v_mul_f32_e32 v50, 0x3d372713, v46
	v_mul_f32_e32 v50, v46, v50
	v_fma_f32 v50, v46, v50, v46
	v_mul_f32_e32 v50, 0x3f4c422a, v50
	v_add_f32_e32 v50, v50, v50
	v_mul_f32_e32 v50, 0xbfb8aa3b, v50
	v_exp_f32_e32 v50, v50
	v_lshlrev_b32_e32 v63, 16, v47
	v_and_b32_e32 v47, 0xffff0000, v47
	v_lshlrev_b32_e32 v79, 16, v51
	v_add_f32_e32 v50, 1.0, v50
	v_rcp_f32_e32 v50, v50
	v_and_b32_e32 v51, 0xffff0000, v51
	v_fmac_f32_e32 v63, v60, v79
	v_fmac_f32_e32 v47, v61, v51
	v_fmac_f32_e32 v62, v58, v78
	v_mul_f32_e32 v46, v46, v50
	v_mul_f32_e32 v50, 0x3d372713, v63
	v_mul_f32_e32 v51, 0x3d372713, v47
	v_mul_f32_e32 v58, 0x3d372713, v62
	v_mul_f32_e32 v50, v63, v50
	v_mul_f32_e32 v51, v47, v51
	v_mul_f32_e32 v58, v62, v58
	v_fma_f32 v50, v63, v50, v63
	v_fma_f32 v51, v47, v51, v47
	v_fma_f32 v58, v62, v58, v62
	v_mul_f32_e32 v50, 0x3f4c422a, v50
	v_mul_f32_e32 v51, 0x3f4c422a, v51
	v_mul_f32_e32 v58, 0x3f4c422a, v58
	v_add_f32_e32 v50, v50, v50
	v_add_f32_e32 v51, v51, v51
	v_add_f32_e32 v58, v58, v58
	v_mul_f32_e32 v50, 0xbfb8aa3b, v50
	v_mul_f32_e32 v51, 0xbfb8aa3b, v51
	v_mul_f32_e32 v58, 0xbfb8aa3b, v58
	v_exp_f32_e32 v50, v50
	v_exp_f32_e32 v51, v51
	v_exp_f32_e32 v58, v58
	v_lshlrev_b32_e32 v64, 16, v48
	v_add_f32_e32 v50, 1.0, v50
	v_add_f32_e32 v51, 1.0, v51
	v_add_f32_e32 v58, 1.0, v58
	v_rcp_f32_e32 v50, v50
	v_rcp_f32_e32 v51, v51
	v_rcp_f32_e32 v58, v58
	v_and_b32_e32 v48, 0xffff0000, v48
	v_lshlrev_b32_e32 v80, 16, v52
	v_and_b32_e32 v52, 0xffff0000, v52
	v_mul_f32_e32 v50, v63, v50
	v_mul_f32_e32 v47, v47, v51
	v_fmac_f32_e32 v64, v54, v80
	v_fmac_f32_e32 v48, v55, v52
	v_mul_f32_e32 v58, v62, v58
	v_cvt_pk_bf16_f32 v46, v58, v46
	v_cvt_pk_bf16_f32 v47, v50, v47
	v_mul_f32_e32 v50, 0x3d372713, v64
	v_mul_f32_e32 v51, 0x3d372713, v48
	v_mul_f32_e32 v50, v64, v50
	v_mul_f32_e32 v51, v48, v51
	v_fma_f32 v50, v64, v50, v64
	v_fma_f32 v51, v48, v51, v48
	v_mul_f32_e32 v50, 0x3f4c422a, v50
	v_mul_f32_e32 v51, 0x3f4c422a, v51
	v_add_f32_e32 v50, v50, v50
	v_add_f32_e32 v51, v51, v51
	v_mul_f32_e32 v50, 0xbfb8aa3b, v50
	v_mul_f32_e32 v51, 0xbfb8aa3b, v51
	v_exp_f32_e32 v50, v50
	v_exp_f32_e32 v51, v51
	v_lshlrev_b32_e32 v65, 16, v49
	v_and_b32_e32 v49, 0xffff0000, v49
	v_add_f32_e32 v50, 1.0, v50
	v_add_f32_e32 v51, 1.0, v51
	v_rcp_f32_e32 v50, v50
	v_rcp_f32_e32 v51, v51
	v_lshlrev_b32_e32 v81, 16, v53
	v_and_b32_e32 v53, 0xffff0000, v53
	v_mul_f32_e32 v50, v64, v50
	v_mul_f32_e32 v48, v48, v51
	v_fmac_f32_e32 v65, v56, v81
	v_fmac_f32_e32 v49, v57, v53
	v_cvt_pk_bf16_f32 v48, v50, v48
	v_mul_f32_e32 v50, 0x3d372713, v65
	v_mul_f32_e32 v51, 0x3d372713, v49
	v_mul_f32_e32 v50, v65, v50
	v_mul_f32_e32 v51, v49, v51
	v_fma_f32 v50, v65, v50, v65
	v_fma_f32 v51, v49, v51, v49
	v_mul_f32_e32 v50, 0x3f4c422a, v50
	v_mul_f32_e32 v51, 0x3f4c422a, v51
	v_add_f32_e32 v50, v50, v50
	v_add_f32_e32 v51, v51, v51
	v_mul_f32_e32 v50, 0xbfb8aa3b, v50
	v_mul_f32_e32 v51, 0xbfb8aa3b, v51
	v_exp_f32_e32 v50, v50
	v_exp_f32_e32 v51, v51
	v_add_f32_e32 v50, 1.0, v50
	v_add_f32_e32 v51, 1.0, v51
	v_rcp_f32_e32 v50, v50
	v_rcp_f32_e32 v51, v51
	v_mul_f32_e32 v50, v65, v50
	v_mul_f32_e32 v49, v49, v51
	v_cvt_pk_bf16_f32 v49, v50, v49
	ds_read_b128 v[58:61], v246 offset:400
	ds_read_b128 v[62:65], v246 offset:384
	s_waitcnt vmcnt(8) lgkmcnt(0)
; __device__ __forceinline__ unsigned cvt_pk_bf16(float lo, float hi) { unsigned r; asm volatile("v_cvt_pk_bf16_f32 %0, %1, %2" : "=v"(r) : "v"(lo), "v"(hi)); return r; }
; __device__ __forceinline__ float gelu_tanh(float x) { const float u = 0.7978845608028654f * (x + 0.044715f * x * x * x); return x * sigm(2.f * u); }
; #define UNPK8(VV_, XX_) float XX_[8] = {bflo((VV_).x), bfhi((VV_).x), bflo((VV_).y), bfhi((VV_).y), bflo((VV_).z), bfhi((VV_).z), bflo((VV_).w), bfhi((VV_).w)}
; __device__ __forceinline__ void glu_task(int t, int l, const float* s5d, const bf16_t* P, const bf16_t* YB, const bf16_t* WGLU, bf16_t* Z1, int fr, int fq) {
;     ...
;     for (int tb = 0; tb < 2; ++tb) { const size_t row = row0 + tb * 16;
; #pragma unroll
;         for (int ks = 0; ks < 8; ++ks) { const int k0 = ks * 32 + fq * 8; const u32x4 yw = ld8(YB + row * 256 + k0), uw = ld8(P + row * INP + OFF_S5 + k0);
;             const f32x4 d0 = *(const f32x4*)(s5d + l * 256 + k0), d1 = *(const f32x4*)(s5d + l * 256 + k0 + 4); UNPK8(yw, y); UNPK8(uw, u); u32x4 o;
;             o.x = cvt_pk_bf16(gelu_tanh(y[0] + d0[0] * u[0]), gelu_tanh(y[1] + d0[1] * u[1])); o.y = cvt_pk_bf16(gelu_tanh(y[2] + d0[2] * u[2]), gelu_tanh(y[3] + d0[3] * u[3]));
;             o.z = cvt_pk_bf16(gelu_tanh(y[4] + d1[0] * u[4]), gelu_tanh(y[5] + d1[1] * u[5])); o.w = cvt_pk_bf16(gelu_tanh(y[6] + d1[2] * u[6]), gelu_tanh(y[7] + d1[3] * u[7]));
;             bfr[tb][ks] = asfrag(o); } }
	v_mov_b32_e32 v50, v168
	v_mov_b32_e32 v51, v169
	v_mov_b32_e32 v52, v170
	v_mov_b32_e32 v53, v171
	v_mov_b32_e32 v54, v188
	v_mov_b32_e32 v55, v189
	v_mov_b32_e32 v56, v190
	v_mov_b32_e32 v57, v191
	v_lshlrev_b32_e32 v78, 16, v50
	v_and_b32_e32 v50, 0xffff0000, v50
	v_lshlrev_b32_e32 v82, 16, v54
	v_and_b32_e32 v54, 0xffff0000, v54
	v_fmac_f32_e32 v50, v63, v54
	v_mul_f32_e32 v54, 0x3d372713, v50
	v_mul_f32_e32 v54, v50, v54
	v_fma_f32 v54, v50, v54, v50
	v_mul_f32_e32 v54, 0x3f4c422a, v54
	v_add_f32_e32 v54, v54, v54
	v_mul_f32_e32 v54, 0xbfb8aa3b, v54
	v_exp_f32_e32 v54, v54
	v_lshlrev_b32_e32 v79, 16, v51
	v_and_b32_e32 v51, 0xffff0000, v51
	v_lshlrev_b32_e32 v83, 16, v55
	v_add_f32_e32 v54, 1.0, v54
	v_rcp_f32_e32 v54, v54
	v_and_b32_e32 v55, 0xffff0000, v55
	v_fmac_f32_e32 v79, v64, v83
	v_fmac_f32_e32 v51, v65, v55
	v_fmac_f32_e32 v78, v62, v82
	v_mul_f32_e32 v50, v50, v54
	v_mul_f32_e32 v54, 0x3d372713, v79
	v_mul_f32_e32 v55, 0x3d372713, v51
	v_mul_f32_e32 v62, 0x3d372713, v78
	v_mul_f32_e32 v54, v79, v54
	v_mul_f32_e32 v55, v51, v55
	v_mul_f32_e32 v62, v78, v62
	v_fma_f32 v54, v79, v54, v79
	v_fma_f32 v55, v51, v55, v51
	v_fma_f32 v62, v78, v62, v78
	v_mul_f32_e32 v54, 0x3f4c422a, v54
	v_mul_f32_e32 v55, 0x3f4c422a, v55
	v_mul_f32_e32 v62, 0x3f4c422a, v62
	v_add_f32_e32 v54, v54, v54
	v_add_f32_e32 v55, v55, v55
	v_add_f32_e32 v62, v62, v62
	v_mul_f32_e32 v54, 0xbfb8aa3b, v54
	v_mul_f32_e32 v55, 0xbfb8aa3b, v55
	v_mul_f32_e32 v62, 0xbfb8aa3b, v62
	v_exp_f32_e32 v54, v54
	v_exp_f32_e32 v55, v55
	v_exp_f32_e32 v62, v62
	v_lshlrev_b32_e32 v80, 16, v52
	v_add_f32_e32 v54, 1.0, v54
	v_add_f32_e32 v55, 1.0, v55
	v_add_f32_e32 v62, 1.0, v62
	v_rcp_f32_e32 v54, v54
	v_rcp_f32_e32 v55, v55
	v_rcp_f32_e32 v62, v62
	v_and_b32_e32 v52, 0xffff0000, v52
	v_lshlrev_b32_e32 v84, 16, v56
	v_and_b32_e32 v56, 0xffff0000, v56
	v_mul_f32_e32 v54, v79, v54
	v_mul_f32_e32 v51, v51, v55
	v_fmac_f32_e32 v80, v58, v84
	v_fmac_f32_e32 v52, v59, v56
	v_mul_f32_e32 v62, v78, v62
	v_cvt_pk_bf16_f32 v50, v62, v50
	v_cvt_pk_bf16_f32 v51, v54, v51
	v_mul_f32_e32 v54, 0x3d372713, v80
	v_mul_f32_e32 v55, 0x3d372713, v52
	v_mul_f32_e32 v54, v80, v54
	v_mul_f32_e32 v55, v52, v55
	v_fma_f32 v54, v80, v54, v80
	v_fma_f32 v55, v52, v55, v52
	v_mul_f32_e32 v54, 0x3f4c422a, v54
	v_mul_f32_e32 v55, 0x3f4c422a, v55
	v_add_f32_e32 v54, v54, v54
	v_add_f32_e32 v55, v55, v55
	v_mul_f32_e32 v54, 0xbfb8aa3b, v54
	v_mul_f32_e32 v55, 0xbfb8aa3b, v55
	v_exp_f32_e32 v54, v54
	v_exp_f32_e32 v55, v55
	v_lshlrev_b32_e32 v81, 16, v53
	v_and_b32_e32 v53, 0xffff0000, v53
	v_add_f32_e32 v54, 1.0, v54
	v_add_f32_e32 v55, 1.0, v55
	v_rcp_f32_e32 v54, v54
	v_rcp_f32_e32 v55, v55
	v_lshlrev_b32_e32 v85, 16, v57
	v_and_b32_e32 v57, 0xffff0000, v57
	v_mul_f32_e32 v54, v80, v54
	v_mul_f32_e32 v52, v52, v55
	v_fmac_f32_e32 v81, v60, v85
	v_fmac_f32_e32 v53, v61, v57
	v_cvt_pk_bf16_f32 v52, v54, v52
	v_mul_f32_e32 v54, 0x3d372713, v81
	v_mul_f32_e32 v55, 0x3d372713, v53
	v_mul_f32_e32 v54, v81, v54
	v_mul_f32_e32 v55, v53, v55
	v_fma_f32 v54, v81, v54, v81
	v_fma_f32 v55, v53, v55, v53
	v_mul_f32_e32 v54, 0x3f4c422a, v54
	v_mul_f32_e32 v55, 0x3f4c422a, v55
	v_add_f32_e32 v54, v54, v54
	v_add_f32_e32 v55, v55, v55
	v_mul_f32_e32 v54, 0xbfb8aa3b, v54
	v_mul_f32_e32 v55, 0xbfb8aa3b, v55
	v_exp_f32_e32 v54, v54
	v_exp_f32_e32 v55, v55
	v_add_f32_e32 v54, 1.0, v54
	v_add_f32_e32 v55, 1.0, v55
	v_rcp_f32_e32 v54, v54
	v_rcp_f32_e32 v55, v55
	v_mul_f32_e32 v54, v81, v54
	v_mul_f32_e32 v53, v53, v55
	v_cvt_pk_bf16_f32 v53, v54, v53
	ds_read_b128 v[62:65], v246 offset:528
	ds_read_b128 v[78:81], v246 offset:512
	s_waitcnt vmcnt(6) lgkmcnt(0)
	v_mov_b32_e32 v54, v98
	v_mov_b32_e32 v55, v99
	v_mov_b32_e32 v56, v100
	v_mov_b32_e32 v57, v101
	v_mov_b32_e32 v58, v102
	v_mov_b32_e32 v59, v103
	v_mov_b32_e32 v60, v104
	v_mov_b32_e32 v61, v105
	v_lshlrev_b32_e32 v82, 16, v54
	v_and_b32_e32 v54, 0xffff0000, v54
	v_lshlrev_b32_e32 v86, 16, v58
	v_and_b32_e32 v58, 0xffff0000, v58
	v_fmac_f32_e32 v54, v79, v58
	v_mul_f32_e32 v58, 0x3d372713, v54
	v_mul_f32_e32 v58, v54, v58
	v_fma_f32 v58, v54, v58, v54
	v_mul_f32_e32 v58, 0x3f4c422a, v58
	v_add_f32_e32 v58, v58, v58
	v_mul_f32_e32 v58, 0xbfb8aa3b, v58
	v_exp_f32_e32 v58, v58
	v_lshlrev_b32_e32 v83, 16, v55
	v_and_b32_e32 v55, 0xffff0000, v55
	v_lshlrev_b32_e32 v87, 16, v59
	v_add_f32_e32 v58, 1.0, v58
	v_rcp_f32_e32 v58, v58
	v_and_b32_e32 v59, 0xffff0000, v59
	v_fmac_f32_e32 v83, v80, v87
	v_fmac_f32_e32 v55, v81, v59
	v_fmac_f32_e32 v82, v78, v86
	v_mul_f32_e32 v54, v54, v58
	v_mul_f32_e32 v58, 0x3d372713, v83
	v_mul_f32_e32 v59, 0x3d372713, v55
	v_mul_f32_e32 v78, 0x3d372713, v82
	v_mul_f32_e32 v58, v83, v58
	v_mul_f32_e32 v59, v55, v59
	v_mul_f32_e32 v78, v82, v78
	v_fma_f32 v58, v83, v58, v83
	v_fma_f32 v59, v55, v59, v55
	v_fma_f32 v78, v82, v78, v82
	v_mul_f32_e32 v58, 0x3f4c422a, v58
	v_mul_f32_e32 v59, 0x3f4c422a, v59
	v_mul_f32_e32 v78, 0x3f4c422a, v78
	v_add_f32_e32 v58, v58, v58
	v_add_f32_e32 v59, v59, v59
	v_add_f32_e32 v78, v78, v78
	v_mul_f32_e32 v58, 0xbfb8aa3b, v58
	v_mul_f32_e32 v59, 0xbfb8aa3b, v59
	v_mul_f32_e32 v78, 0xbfb8aa3b, v78
	v_exp_f32_e32 v58, v58
	v_exp_f32_e32 v59, v59
	v_exp_f32_e32 v78, v78
	v_lshlrev_b32_e32 v84, 16, v56
	v_add_f32_e32 v58, 1.0, v58
	v_add_f32_e32 v59, 1.0, v59
	v_add_f32_e32 v78, 1.0, v78
	v_rcp_f32_e32 v58, v58
	v_rcp_f32_e32 v59, v59
	v_rcp_f32_e32 v78, v78
	v_and_b32_e32 v56, 0xffff0000, v56
	v_lshlrev_b32_e32 v88, 16, v60
	v_and_b32_e32 v60, 0xffff0000, v60
	v_mul_f32_e32 v58, v83, v58
	v_mul_f32_e32 v55, v55, v59
	v_fmac_f32_e32 v84, v62, v88
	v_fmac_f32_e32 v56, v63, v60
	v_mul_f32_e32 v78, v82, v78
; __device__ __forceinline__ unsigned cvt_pk_bf16(float lo, float hi) { unsigned r; asm volatile("v_cvt_pk_bf16_f32 %0, %1, %2" : "=v"(r) : "v"(lo), "v"(hi)); return r; }
; __device__ __forceinline__ float gelu_tanh(float x) { const float u = 0.7978845608028654f * (x + 0.044715f * x * x * x); return x * sigm(2.f * u); }
; #define UNPK8(VV_, XX_) float XX_[8] = {bflo((VV_).x), bfhi((VV_).x), bflo((VV_).y), bfhi((VV_).y), bflo((VV_).z), bfhi((VV_).z), bflo((VV_).w), bfhi((VV_).w)}
; __device__ __forceinline__ void glu_task(int t, int l, const float* s5d, const bf16_t* P, const bf16_t* YB, const bf16_t* WGLU, bf16_t* Z1, int fr, int fq) {
;     ...
;     for (int tb = 0; tb < 2; ++tb) { const size_t row = row0 + tb * 16;
; #pragma unroll
;         for (int ks = 0; ks < 8; ++ks) { const int k0 = ks * 32 + fq * 8; const u32x4 yw = ld8(YB + row * 256 + k0), uw = ld8(P + row * INP + OFF_S5 + k0);
;             const f32x4 d0 = *(const f32x4*)(s5d + l * 256 + k0), d1 = *(const f32x4*)(s5d + l * 256 + k0 + 4); UNPK8(yw, y); UNPK8(uw, u); u32x4 o;
;             o.x = cvt_pk_bf16(gelu_tanh(y[0] + d0[0] * u[0]), gelu_tanh(y[1] + d0[1] * u[1])); o.y = cvt_pk_bf16(gelu_tanh(y[2] + d0[2] * u[2]), gelu_tanh(y[3] + d0[3] * u[3]));
;             o.z = cvt_pk_bf16(gelu_tanh(y[4] + d1[0] * u[4]), gelu_tanh(y[5] + d1[1] * u[5])); o.w = cvt_pk_bf16(gelu_tanh(y[6] + d1[2] * u[6]), gelu_tanh(y[7] + d1[3] * u[7]));
;             bfr[tb][ks] = asfrag(o); } }
	v_cvt_pk_bf16_f32 v54, v78, v54
	v_cvt_pk_bf16_f32 v55, v58, v55
	v_mul_f32_e32 v58, 0x3d372713, v84
	v_mul_f32_e32 v59, 0x3d372713, v56
	v_mul_f32_e32 v58, v84, v58
	v_mul_f32_e32 v59, v56, v59
	v_fma_f32 v58, v84, v58, v84
	v_fma_f32 v59, v56, v59, v56
	v_mul_f32_e32 v58, 0x3f4c422a, v58
	v_mul_f32_e32 v59, 0x3f4c422a, v59
	v_add_f32_e32 v58, v58, v58
	v_add_f32_e32 v59, v59, v59
	v_mul_f32_e32 v58, 0xbfb8aa3b, v58
	v_mul_f32_e32 v59, 0xbfb8aa3b, v59
	v_exp_f32_e32 v58, v58
	v_exp_f32_e32 v59, v59
	v_lshlrev_b32_e32 v85, 16, v57
	v_and_b32_e32 v57, 0xffff0000, v57
	v_add_f32_e32 v58, 1.0, v58
	v_add_f32_e32 v59, 1.0, v59
	v_rcp_f32_e32 v58, v58
	v_rcp_f32_e32 v59, v59
	v_lshlrev_b32_e32 v89, 16, v61
	v_and_b32_e32 v61, 0xffff0000, v61
	v_mul_f32_e32 v58, v84, v58
	v_mul_f32_e32 v56, v56, v59
	v_fmac_f32_e32 v85, v64, v89
	v_fmac_f32_e32 v57, v65, v61
	v_cvt_pk_bf16_f32 v56, v58, v56
	v_mul_f32_e32 v58, 0x3d372713, v85
	v_mul_f32_e32 v59, 0x3d372713, v57
	v_mul_f32_e32 v58, v85, v58
	v_mul_f32_e32 v59, v57, v59
	v_fma_f32 v58, v85, v58, v85
	v_fma_f32 v59, v57, v59, v57
	v_mul_f32_e32 v58, 0x3f4c422a, v58
	v_mul_f32_e32 v59, 0x3f4c422a, v59
	v_add_f32_e32 v58, v58, v58
	v_add_f32_e32 v59, v59, v59
	v_mul_f32_e32 v58, 0xbfb8aa3b, v58
	v_mul_f32_e32 v59, 0xbfb8aa3b, v59
	v_exp_f32_e32 v58, v58
	v_exp_f32_e32 v59, v59
	v_add_f32_e32 v58, 1.0, v58
	v_add_f32_e32 v59, 1.0, v59
	v_rcp_f32_e32 v58, v58
	v_rcp_f32_e32 v59, v59
	v_mul_f32_e32 v58, v85, v58
	v_mul_f32_e32 v57, v57, v59
	v_cvt_pk_bf16_f32 v57, v58, v57
	ds_read_b128 v[78:81], v246 offset:656
	ds_read_b128 v[82:85], v246 offset:640
	s_waitcnt vmcnt(4) lgkmcnt(0)
	v_mov_b32_e32 v58, v106
	v_mov_b32_e32 v59, v107
	v_mov_b32_e32 v60, v108
	v_mov_b32_e32 v61, v109
	v_mov_b32_e32 v62, v110
	v_mov_b32_e32 v63, v111
	v_mov_b32_e32 v64, v112
	v_mov_b32_e32 v65, v113
	v_lshlrev_b32_e32 v86, 16, v58
	v_and_b32_e32 v58, 0xffff0000, v58
	v_lshlrev_b32_e32 v90, 16, v62
	v_and_b32_e32 v62, 0xffff0000, v62
	v_fmac_f32_e32 v58, v83, v62
	v_mul_f32_e32 v62, 0x3d372713, v58
	v_mul_f32_e32 v62, v58, v62
	v_fma_f32 v62, v58, v62, v58
	v_mul_f32_e32 v62, 0x3f4c422a, v62
	v_add_f32_e32 v62, v62, v62
	v_mul_f32_e32 v62, 0xbfb8aa3b, v62
	v_exp_f32_e32 v62, v62
	v_lshlrev_b32_e32 v87, 16, v59
	v_and_b32_e32 v59, 0xffff0000, v59
	v_lshlrev_b32_e32 v91, 16, v63
	v_add_f32_e32 v62, 1.0, v62
	v_rcp_f32_e32 v62, v62
	v_and_b32_e32 v63, 0xffff0000, v63
	v_fmac_f32_e32 v87, v84, v91
	v_fmac_f32_e32 v59, v85, v63
	v_fmac_f32_e32 v86, v82, v90
	v_mul_f32_e32 v58, v58, v62
	v_mul_f32_e32 v62, 0x3d372713, v87
	v_mul_f32_e32 v63, 0x3d372713, v59
	v_mul_f32_e32 v82, 0x3d372713, v86
	v_mul_f32_e32 v62, v87, v62
	v_mul_f32_e32 v63, v59, v63
	v_mul_f32_e32 v82, v86, v82
	v_fma_f32 v62, v87, v62, v87
	v_fma_f32 v63, v59, v63, v59
	v_fma_f32 v82, v86, v82, v86
	v_mul_f32_e32 v62, 0x3f4c422a, v62
	v_mul_f32_e32 v63, 0x3f4c422a, v63
	v_mul_f32_e32 v82, 0x3f4c422a, v82
	v_add_f32_e32 v62, v62, v62
	v_add_f32_e32 v63, v63, v63
	v_add_f32_e32 v82, v82, v82
	v_mul_f32_e32 v62, 0xbfb8aa3b, v62
	v_mul_f32_e32 v63, 0xbfb8aa3b, v63
	v_mul_f32_e32 v82, 0xbfb8aa3b, v82
	v_exp_f32_e32 v62, v62
	v_exp_f32_e32 v63, v63
	v_exp_f32_e32 v82, v82
	v_lshlrev_b32_e32 v88, 16, v60
	v_add_f32_e32 v62, 1.0, v62
	v_add_f32_e32 v63, 1.0, v63
	v_add_f32_e32 v82, 1.0, v82
	v_rcp_f32_e32 v62, v62
	v_rcp_f32_e32 v63, v63
	v_rcp_f32_e32 v82, v82
	v_and_b32_e32 v60, 0xffff0000, v60
	v_lshlrev_b32_e32 v92, 16, v64
	v_and_b32_e32 v64, 0xffff0000, v64
	v_mul_f32_e32 v62, v87, v62
	v_mul_f32_e32 v59, v59, v63
	v_fmac_f32_e32 v88, v78, v92
	v_fmac_f32_e32 v60, v79, v64
	v_mul_f32_e32 v82, v86, v82
	v_cvt_pk_bf16_f32 v58, v82, v58
	v_cvt_pk_bf16_f32 v59, v62, v59
	v_mul_f32_e32 v62, 0x3d372713, v88
	v_mul_f32_e32 v63, 0x3d372713, v60
	v_mul_f32_e32 v62, v88, v62
	v_mul_f32_e32 v63, v60, v63
	v_fma_f32 v62, v88, v62, v88
	v_fma_f32 v63, v60, v63, v60
	v_mul_f32_e32 v62, 0x3f4c422a, v62
	v_mul_f32_e32 v63, 0x3f4c422a, v63
	v_add_f32_e32 v62, v62, v62
	v_add_f32_e32 v63, v63, v63
	v_mul_f32_e32 v62, 0xbfb8aa3b, v62
	v_mul_f32_e32 v63, 0xbfb8aa3b, v63
	v_exp_f32_e32 v62, v62
	v_exp_f32_e32 v63, v63
	v_lshlrev_b32_e32 v89, 16, v61
	v_and_b32_e32 v61, 0xffff0000, v61
	v_add_f32_e32 v62, 1.0, v62
	v_add_f32_e32 v63, 1.0, v63
	v_rcp_f32_e32 v62, v62
	v_rcp_f32_e32 v63, v63
	v_lshlrev_b32_e32 v93, 16, v65
	v_and_b32_e32 v65, 0xffff0000, v65
	v_mul_f32_e32 v62, v88, v62
	v_mul_f32_e32 v60, v60, v63
	v_fmac_f32_e32 v89, v80, v93
	v_fmac_f32_e32 v61, v81, v65
	v_cvt_pk_bf16_f32 v60, v62, v60
	v_mul_f32_e32 v62, 0x3d372713, v89
	v_mul_f32_e32 v63, 0x3d372713, v61
	v_mul_f32_e32 v62, v89, v62
	v_mul_f32_e32 v63, v61, v63
	v_fma_f32 v62, v89, v62, v89
	v_fma_f32 v63, v61, v63, v61
	v_mul_f32_e32 v62, 0x3f4c422a, v62
	v_mul_f32_e32 v63, 0x3f4c422a, v63
	v_add_f32_e32 v62, v62, v62
	v_add_f32_e32 v63, v63, v63
	v_mul_f32_e32 v62, 0xbfb8aa3b, v62
	v_mul_f32_e32 v63, 0xbfb8aa3b, v63
	v_exp_f32_e32 v62, v62
	v_exp_f32_e32 v63, v63
	v_add_f32_e32 v62, 1.0, v62
	v_add_f32_e32 v63, 1.0, v63
	v_rcp_f32_e32 v62, v62
	v_rcp_f32_e32 v63, v63
	v_mul_f32_e32 v62, v89, v62
	v_mul_f32_e32 v61, v61, v63
	v_cvt_pk_bf16_f32 v61, v62, v61
	ds_read_b128 v[82:85], v246 offset:784
	ds_read_b128 v[86:89], v246 offset:768
	s_waitcnt vmcnt(2) lgkmcnt(0)
; __device__ __forceinline__ unsigned cvt_pk_bf16(float lo, float hi) { unsigned r; asm volatile("v_cvt_pk_bf16_f32 %0, %1, %2" : "=v"(r) : "v"(lo), "v"(hi)); return r; }
; __device__ __forceinline__ float gelu_tanh(float x) { const float u = 0.7978845608028654f * (x + 0.044715f * x * x * x); return x * sigm(2.f * u); }
; #define UNPK8(VV_, XX_) float XX_[8] = {bflo((VV_).x), bfhi((VV_).x), bflo((VV_).y), bfhi((VV_).y), bflo((VV_).z), bfhi((VV_).z), bflo((VV_).w), bfhi((VV_).w)}
; __device__ __forceinline__ void glu_task(int t, int l, const float* s5d, const bf16_t* P, const bf16_t* YB, const bf16_t* WGLU, bf16_t* Z1, int fr, int fq) {
;     ...
;     for (int tb = 0; tb < 2; ++tb) { const size_t row = row0 + tb * 16;
; #pragma unroll
;         for (int ks = 0; ks < 8; ++ks) { const int k0 = ks * 32 + fq * 8; const u32x4 yw = ld8(YB + row * 256 + k0), uw = ld8(P + row * INP + OFF_S5 + k0);
;             const f32x4 d0 = *(const f32x4*)(s5d + l * 256 + k0), d1 = *(const f32x4*)(s5d + l * 256 + k0 + 4); UNPK8(yw, y); UNPK8(uw, u); u32x4 o;
;             o.x = cvt_pk_bf16(gelu_tanh(y[0] + d0[0] * u[0]), gelu_tanh(y[1] + d0[1] * u[1])); o.y = cvt_pk_bf16(gelu_tanh(y[2] + d0[2] * u[2]), gelu_tanh(y[3] + d0[3] * u[3]));
;             o.z = cvt_pk_bf16(gelu_tanh(y[4] + d1[0] * u[4]), gelu_tanh(y[5] + d1[1] * u[5])); o.w = cvt_pk_bf16(gelu_tanh(y[6] + d1[2] * u[6]), gelu_tanh(y[7] + d1[3] * u[7]));
;             bfr[tb][ks] = asfrag(o); } }
	v_mov_b32_e32 v62, v118
	v_mov_b32_e32 v63, v119
	v_mov_b32_e32 v64, v120
	v_mov_b32_e32 v65, v121
	v_mov_b32_e32 v78, v122
	v_mov_b32_e32 v79, v123
	v_mov_b32_e32 v80, v124
	v_mov_b32_e32 v81, v125
	v_lshlrev_b32_e32 v90, 16, v62
	v_and_b32_e32 v62, 0xffff0000, v62
	v_lshlrev_b32_e32 v94, 16, v78
	v_and_b32_e32 v78, 0xffff0000, v78
	v_fmac_f32_e32 v62, v87, v78
	v_mul_f32_e32 v78, 0x3d372713, v62
	v_mul_f32_e32 v78, v62, v78
	v_fma_f32 v78, v62, v78, v62
	v_mul_f32_e32 v78, 0x3f4c422a, v78
	v_add_f32_e32 v78, v78, v78
	v_mul_f32_e32 v78, 0xbfb8aa3b, v78
	v_exp_f32_e32 v78, v78
	v_lshlrev_b32_e32 v91, 16, v63
	v_and_b32_e32 v63, 0xffff0000, v63
	v_lshlrev_b32_e32 v95, 16, v79
	v_add_f32_e32 v78, 1.0, v78
	v_rcp_f32_e32 v78, v78
	v_and_b32_e32 v79, 0xffff0000, v79
	v_fmac_f32_e32 v91, v88, v95
	v_fmac_f32_e32 v63, v89, v79
	v_fmac_f32_e32 v90, v86, v94
	v_mul_f32_e32 v62, v62, v78
	v_mul_f32_e32 v78, 0x3d372713, v91
	v_mul_f32_e32 v79, 0x3d372713, v63
	v_mul_f32_e32 v86, 0x3d372713, v90
	v_mul_f32_e32 v78, v91, v78
	v_mul_f32_e32 v79, v63, v79
	v_mul_f32_e32 v86, v90, v86
	v_fma_f32 v78, v91, v78, v91
	v_fma_f32 v79, v63, v79, v63
	v_fma_f32 v86, v90, v86, v90
	v_mul_f32_e32 v78, 0x3f4c422a, v78
	v_mul_f32_e32 v79, 0x3f4c422a, v79
	v_mul_f32_e32 v86, 0x3f4c422a, v86
	v_add_f32_e32 v78, v78, v78
	v_add_f32_e32 v79, v79, v79
	v_add_f32_e32 v86, v86, v86
	v_mul_f32_e32 v78, 0xbfb8aa3b, v78
	v_mul_f32_e32 v79, 0xbfb8aa3b, v79
	v_mul_f32_e32 v86, 0xbfb8aa3b, v86
	v_exp_f32_e32 v78, v78
	v_exp_f32_e32 v79, v79
	v_exp_f32_e32 v86, v86
	v_lshlrev_b32_e32 v92, 16, v64
	v_add_f32_e32 v78, 1.0, v78
	v_add_f32_e32 v79, 1.0, v79
	v_add_f32_e32 v86, 1.0, v86
	v_rcp_f32_e32 v78, v78
	v_rcp_f32_e32 v79, v79
	v_rcp_f32_e32 v86, v86
	v_and_b32_e32 v64, 0xffff0000, v64
	v_lshlrev_b32_e32 v96, 16, v80
	v_and_b32_e32 v80, 0xffff0000, v80
	v_mul_f32_e32 v78, v91, v78
	v_mul_f32_e32 v63, v63, v79
	v_fmac_f32_e32 v92, v82, v96
	v_fmac_f32_e32 v64, v83, v80
	v_mul_f32_e32 v86, v90, v86
	v_cvt_pk_bf16_f32 v62, v86, v62
	v_cvt_pk_bf16_f32 v63, v78, v63
	v_mul_f32_e32 v78, 0x3d372713, v92
	v_mul_f32_e32 v79, 0x3d372713, v64
	v_mul_f32_e32 v78, v92, v78
	v_mul_f32_e32 v79, v64, v79
	v_fma_f32 v78, v92, v78, v92
	v_fma_f32 v79, v64, v79, v64
	v_mul_f32_e32 v78, 0x3f4c422a, v78
	v_mul_f32_e32 v79, 0x3f4c422a, v79
	v_add_f32_e32 v78, v78, v78
	v_add_f32_e32 v79, v79, v79
	v_mul_f32_e32 v78, 0xbfb8aa3b, v78
	v_mul_f32_e32 v79, 0xbfb8aa3b, v79
	v_exp_f32_e32 v78, v78
	v_exp_f32_e32 v79, v79
	v_lshlrev_b32_e32 v93, 16, v65
	v_and_b32_e32 v65, 0xffff0000, v65
	v_add_f32_e32 v78, 1.0, v78
	v_add_f32_e32 v79, 1.0, v79
	v_rcp_f32_e32 v78, v78
	v_rcp_f32_e32 v79, v79
	v_lshlrev_b32_e32 v97, 16, v81
	v_and_b32_e32 v81, 0xffff0000, v81
	v_mul_f32_e32 v78, v92, v78
	v_mul_f32_e32 v64, v64, v79
	v_fmac_f32_e32 v93, v84, v97
	v_fmac_f32_e32 v65, v85, v81
	v_cvt_pk_bf16_f32 v64, v78, v64
	v_mul_f32_e32 v78, 0x3d372713, v93
	v_mul_f32_e32 v79, 0x3d372713, v65
	v_mul_f32_e32 v78, v93, v78
	v_mul_f32_e32 v79, v65, v79
	v_fma_f32 v78, v93, v78, v93
	v_fma_f32 v79, v65, v79, v65
	v_mul_f32_e32 v78, 0x3f4c422a, v78
	v_mul_f32_e32 v79, 0x3f4c422a, v79
	v_add_f32_e32 v78, v78, v78
	v_add_f32_e32 v79, v79, v79
	v_mul_f32_e32 v78, 0xbfb8aa3b, v78
	v_mul_f32_e32 v79, 0xbfb8aa3b, v79
	v_exp_f32_e32 v78, v78
	v_exp_f32_e32 v79, v79
	v_add_f32_e32 v78, 1.0, v78
	v_add_f32_e32 v79, 1.0, v79
	v_rcp_f32_e32 v78, v78
	v_rcp_f32_e32 v79, v79
	v_mul_f32_e32 v78, v93, v78
	v_mul_f32_e32 v65, v65, v79
	v_cvt_pk_bf16_f32 v65, v78, v65
	s_nop 0
	s_nop 0
	ds_read_b128 v[82:85], v246 offset:912
	ds_read_b128 v[86:89], v246 offset:896
	s_waitcnt vmcnt(0) lgkmcnt(0)
	v_mov_b32_e32 v78, v126
	v_mov_b32_e32 v79, v127
	v_mov_b32_e32 v80, v128
	v_mov_b32_e32 v81, v129
	v_mov_b32_e32 v66, v130
	v_mov_b32_e32 v67, v131
	v_mov_b32_e32 v68, v132
	v_mov_b32_e32 v69, v133
	v_lshlrev_b32_e32 v90, 16, v78
	v_and_b32_e32 v78, 0xffff0000, v78
	v_lshlrev_b32_e32 v94, 16, v66
	v_and_b32_e32 v66, 0xffff0000, v66
	v_fmac_f32_e32 v78, v87, v66
	v_mul_f32_e32 v66, 0x3d372713, v78
	v_mul_f32_e32 v66, v78, v66
	v_fma_f32 v66, v78, v66, v78
	v_mul_f32_e32 v66, 0x3f4c422a, v66
	v_add_f32_e32 v66, v66, v66
	v_mul_f32_e32 v66, 0xbfb8aa3b, v66
	v_exp_f32_e32 v66, v66
	v_lshlrev_b32_e32 v91, 16, v79
	v_and_b32_e32 v79, 0xffff0000, v79
	v_lshlrev_b32_e32 v95, 16, v67
	v_add_f32_e32 v66, 1.0, v66
	v_rcp_f32_e32 v66, v66
	v_and_b32_e32 v67, 0xffff0000, v67
	v_fmac_f32_e32 v91, v88, v95
	v_fmac_f32_e32 v79, v89, v67
	v_fmac_f32_e32 v90, v86, v94
	v_mul_f32_e32 v66, v78, v66
	v_mul_f32_e32 v78, 0x3d372713, v91
	v_mul_f32_e32 v67, 0x3d372713, v79
	v_mul_f32_e32 v86, 0x3d372713, v90
	v_mul_f32_e32 v78, v91, v78
	v_mul_f32_e32 v67, v79, v67
	v_mul_f32_e32 v86, v90, v86
	v_fma_f32 v78, v91, v78, v91
	v_fma_f32 v67, v79, v67, v79
	v_fma_f32 v86, v90, v86, v90
	v_mul_f32_e32 v78, 0x3f4c422a, v78
	v_mul_f32_e32 v67, 0x3f4c422a, v67
	v_mul_f32_e32 v86, 0x3f4c422a, v86
	v_add_f32_e32 v78, v78, v78
	v_add_f32_e32 v67, v67, v67
	v_add_f32_e32 v86, v86, v86
	v_mul_f32_e32 v78, 0xbfb8aa3b, v78
	v_mul_f32_e32 v67, 0xbfb8aa3b, v67
	v_mul_f32_e32 v86, 0xbfb8aa3b, v86
	v_exp_f32_e32 v78, v78
	v_exp_f32_e32 v67, v67
	v_exp_f32_e32 v86, v86
	v_lshlrev_b32_e32 v92, 16, v80
	v_add_f32_e32 v78, 1.0, v78
	v_add_f32_e32 v67, 1.0, v67
	v_add_f32_e32 v86, 1.0, v86
	v_rcp_f32_e32 v78, v78
	v_rcp_f32_e32 v67, v67
	v_rcp_f32_e32 v86, v86
	v_and_b32_e32 v80, 0xffff0000, v80
	v_lshlrev_b32_e32 v96, 16, v68
	v_and_b32_e32 v68, 0xffff0000, v68
	v_mul_f32_e32 v78, v91, v78
	v_mul_f32_e32 v67, v79, v67
	v_fmac_f32_e32 v92, v82, v96
	v_fmac_f32_e32 v80, v83, v68
; __device__ __forceinline__ unsigned cvt_pk_bf16(float lo, float hi) { unsigned r; asm volatile("v_cvt_pk_bf16_f32 %0, %1, %2" : "=v"(r) : "v"(lo), "v"(hi)); return r; }
; __device__ __forceinline__ float gelu_tanh(float x) { const float u = 0.7978845608028654f * (x + 0.044715f * x * x * x); return x * sigm(2.f * u); }
; #define MFMA16(a, b, c) __builtin_amdgcn_mfma_f32_16x16x32_bf16((a), (b), (c), 0, 0, 0)
; __device__ __forceinline__ void glu_task(int t, int l, const float* s5d, const bf16_t* P, const bf16_t* YB, const bf16_t* WGLU, bf16_t* Z1, int fr, int fq) {
;     ...
;             o.x = cvt_pk_bf16(gelu_tanh(y[0] + d0[0] * u[0]), gelu_tanh(y[1] + d0[1] * u[1])); o.y = cvt_pk_bf16(gelu_tanh(y[2] + d0[2] * u[2]), gelu_tanh(y[3] + d0[3] * u[3]));
;             o.z = cvt_pk_bf16(gelu_tanh(y[4] + d1[0] * u[4]), gelu_tanh(y[5] + d1[1] * u[5])); o.w = cvt_pk_bf16(gelu_tanh(y[6] + d1[2] * u[6]), gelu_tanh(y[7] + d1[3] * u[7]));
;             bfr[tb][ks] = asfrag(o); } }
;     const bf16_t* wg0 = WGLU + ((size_t)l * 256 + cb0 * 16 + fr) * 256 + fq * 8;
;     bf16x8 wf[2][8];
; #pragma unroll
;     for (int ks = 0; ks < 8; ++ks) wf[0][ks] = asfrag(ld8(wg0 + ks * 32));
;     u32x2 eyw[2][4], euw[2][4], egw[2][4];
; #pragma unroll
;     for (int tb = 0; tb < 2; ++tb)
; #pragma unroll
;         for (int c4 = 0; c4 < 4; ++c4) { const size_t row = row0 + tb * 16; const int n4 = (cb0 + c4) * 16 + fq * 4; eyw[tb][c4] = ld4(YB + row * 256 + n4); euw[tb][c4] = ld4(P + row * INP + OFF_S5 + n4); egw[tb][c4] = ld4(P + row * INP + OFF_GATE + 256 + n4); }
; #pragma unroll
;     for (int c4 = 0; c4 < 4; ++c4) { f32x4 acc[2]; acc[0] = (f32x4){0.f, 0.f, 0.f, 0.f}; acc[1] = acc[0];
;         const int nrow = c4 < 3 ? (c4 + 1) * 16 : 0;
; #pragma unroll
;         for (int ks = 0; ks < 8; ++ks) wf[(c4 + 1) & 1][ks] = asfrag(ld8(wg0 + (size_t)nrow * 256 + ks * 32));
; #pragma unroll
;         for (int ks = 0; ks < 8; ++ks) { acc[0] = MFMA16(wf[c4 & 1][ks], bfr[0][ks], acc[0]); acc[1] = MFMA16(wf[c4 & 1][ks], bfr[1][ks], acc[1]); }
	v_mul_f32_e32 v86, v90, v86
	v_cvt_pk_bf16_f32 v66, v86, v66
	v_cvt_pk_bf16_f32 v67, v78, v67
	v_mul_f32_e32 v78, 0x3d372713, v92
	v_mul_f32_e32 v68, 0x3d372713, v80
	v_mul_f32_e32 v78, v92, v78
	v_mul_f32_e32 v68, v80, v68
	v_fma_f32 v78, v92, v78, v92
	v_fma_f32 v68, v80, v68, v80
	v_mul_f32_e32 v78, 0x3f4c422a, v78
	v_mul_f32_e32 v68, 0x3f4c422a, v68
	v_add_f32_e32 v78, v78, v78
	v_add_f32_e32 v68, v68, v68
	v_mul_f32_e32 v78, 0xbfb8aa3b, v78
	v_mul_f32_e32 v68, 0xbfb8aa3b, v68
	v_exp_f32_e32 v78, v78
	v_exp_f32_e32 v68, v68
	v_lshlrev_b32_e32 v93, 16, v81
	v_and_b32_e32 v81, 0xffff0000, v81
	v_add_f32_e32 v78, 1.0, v78
	v_add_f32_e32 v68, 1.0, v68
	v_rcp_f32_e32 v78, v78
	v_rcp_f32_e32 v68, v68
	v_lshlrev_b32_e32 v97, 16, v69
	v_and_b32_e32 v69, 0xffff0000, v69
	v_mul_f32_e32 v78, v92, v78
	v_mul_f32_e32 v68, v80, v68
	v_fmac_f32_e32 v93, v84, v97
	v_fmac_f32_e32 v81, v85, v69
	v_cvt_pk_bf16_f32 v68, v78, v68
	v_mul_f32_e32 v78, 0x3d372713, v93
	v_mul_f32_e32 v69, 0x3d372713, v81
	v_mul_f32_e32 v78, v93, v78
	v_mul_f32_e32 v69, v81, v69
	v_fma_f32 v78, v93, v78, v93
	v_fma_f32 v69, v81, v69, v81
	v_mul_f32_e32 v78, 0x3f4c422a, v78
	v_mul_f32_e32 v69, 0x3f4c422a, v69
	v_add_f32_e32 v78, v78, v78
	v_add_f32_e32 v69, v69, v69
	v_mul_f32_e32 v78, 0xbfb8aa3b, v78
	v_mul_f32_e32 v69, 0xbfb8aa3b, v69
	v_exp_f32_e32 v78, v78
	v_exp_f32_e32 v69, v69
	v_mov_b32_e32 v79, v1
	v_add_f32_e32 v78, 1.0, v78
	v_add_f32_e32 v69, 1.0, v69
	v_rcp_f32_e32 v78, v78
	v_rcp_f32_e32 v69, v69
	v_mul_f32_e32 v78, v93, v78
	v_mul_f32_e32 v69, v81, v69
	v_cvt_pk_bf16_f32 v69, v78, v69
	v_or_b32_e32 v78, s5, v176
	v_lshlrev_b32_e32 v78, 9, v78
	v_lshl_add_u64 v[116:117], v[136:137], 0, v[78:79]
	flat_load_dwordx4 v[78:81], v[116:117]
	flat_load_dwordx4 v[82:85], v[116:117] offset:64
	flat_load_dwordx4 v[86:89], v[116:117] offset:128
	flat_load_dwordx4 v[90:93], v[116:117] offset:192
	flat_load_dwordx4 v[94:97], v[116:117] offset:256
	flat_load_dwordx4 v[98:101], v[116:117] offset:320
	flat_load_dwordx4 v[102:105], v[116:117] offset:384
	flat_load_dwordx4 v[106:109], v[116:117] offset:448
	flat_load_dwordx2 v[172:173], v[70:71]
	flat_load_dwordx2 v[192:193], v[72:73] offset:320
	flat_load_dwordx2 v[226:227], v[72:73] offset:2880
	flat_load_dwordx2 v[128:129], v[70:71] offset:32
	flat_load_dwordx2 v[126:127], v[72:73] offset:352
	flat_load_dwordx2 v[124:125], v[72:73] offset:2912
	flat_load_dwordx2 v[170:171], v[70:71] offset:64
	flat_load_dwordx2 v[168:169], v[72:73] offset:384
	flat_load_dwordx2 v[166:167], v[72:73] offset:2944
	flat_load_dwordx2 v[156:157], v[70:71] offset:96
	flat_load_dwordx2 v[148:149], v[72:73] offset:416
	flat_load_dwordx2 v[146:147], v[72:73] offset:2976
	v_lshl_add_u64 v[70:71], v[74:75], 0, v[158:159]
	v_lshl_add_u64 v[72:73], v[76:77], 0, v[158:159]
	flat_load_dwordx2 v[228:229], v[70:71]
	flat_load_dwordx2 v[230:231], v[72:73] offset:320
	flat_load_dwordx2 v[232:233], v[72:73] offset:2880
	flat_load_dwordx2 v[122:123], v[70:71] offset:32
	flat_load_dwordx2 v[120:121], v[72:73] offset:352
	flat_load_dwordx2 v[118:119], v[72:73] offset:2912
	flat_load_dwordx2 v[164:165], v[70:71] offset:64
	flat_load_dwordx2 v[162:163], v[72:73] offset:384
	flat_load_dwordx2 v[160:161], v[72:73] offset:2944
	flat_load_dwordx2 v[144:145], v[70:71] offset:96
	flat_load_dwordx2 v[142:143], v[72:73] offset:416
	flat_load_dwordx2 v[140:141], v[72:73] offset:2976
	v_add_co_u32_e32 v70, vcc, s33, v116
	s_waitcnt vmcnt(0) lgkmcnt(0)
	v_mfma_f32_16x16x32_bf16 v[74:77], v[78:81], v[38:41], 0
	v_addc_co_u32_e32 v71, vcc, 0, v117, vcc
	flat_load_dwordx4 v[110:113], v[70:71]
	flat_load_dwordx4 v[130:133], v[70:71] offset:64
	flat_load_dwordx4 v[180:183], v[70:71] offset:128
	flat_load_dwordx4 v[184:187], v[70:71] offset:192
	flat_load_dwordx4 v[188:191], v[70:71] offset:256
	flat_load_dwordx4 v[214:217], v[70:71] offset:320
	flat_load_dwordx4 v[218:221], v[70:71] offset:384
	flat_load_dwordx4 v[222:225], v[70:71] offset:448
	v_mfma_f32_16x16x32_bf16 v[70:73], v[78:81], v[2:5], 0
	global_load_dwordx4 v[78:81], v178, s[22:23]
	v_and_b32_e32 v179, 0xffff0000, v129
	v_mfma_f32_16x16x32_bf16 v[70:73], v[82:85], v[6:9], v[70:73]
	v_mfma_f32_16x16x32_bf16 v[74:77], v[82:85], v[42:45], v[74:77]
	v_lshlrev_b32_e32 v84, 16, v172
	v_lshlrev_b32_e32 v85, 16, v192
	v_lshl_add_u64 v[82:83], s[40:41], 0, v[158:159]
	v_mfma_f32_16x16x32_bf16 v[70:73], v[86:89], v[14:17], v[70:73]
	v_lshlrev_b32_e32 v159, 16, v128
	v_and_b32_e32 v128, 0xffff0000, v128
	s_waitcnt vmcnt(0)
; __device__ __forceinline__ unsigned cvt_pk_bf16(float lo, float hi) { unsigned r; asm volatile("v_cvt_pk_bf16_f32 %0, %1, %2" : "=v"(r) : "v"(lo), "v"(hi)); return r; }
; __device__ __forceinline__ float bflo(unsigned w) { return __uint_as_float(w << 16); }
; __device__ __forceinline__ float bfhi(unsigned w) { return __uint_as_float(w & 0xffff0000u); }
; __device__ __forceinline__ float sigm(float x) { return __builtin_amdgcn_rcpf(1.f + __expf(-x)); }
; __device__ __forceinline__ float siluf(float x) { return x * __builtin_amdgcn_rcpf(1.f + __expf(-x)); }
; __device__ __forceinline__ float gelu_tanh(float x) { const float u = 0.7978845608028654f * (x + 0.044715f * x * x * x); return x * sigm(2.f * u); }
; #define MFMA16(a, b, c) __builtin_amdgcn_mfma_f32_16x16x32_bf16((a), (b), (c), 0, 0, 0)
; __device__ __forceinline__ void glu_task(int t, int l, const float* s5d, const bf16_t* P, const bf16_t* YB, const bf16_t* WGLU, bf16_t* Z1, int fr, int fq) {
;     ...
;         for (int ks = 0; ks < 8; ++ks) { acc[0] = MFMA16(wf[c4 & 1][ks], bfr[0][ks], acc[0]); acc[1] = MFMA16(wf[c4 & 1][ks], bfr[1][ks], acc[1]); }
;         const int n4 = (cb0 + c4) * 16 + fq * 4;
;         const f32x4 dd = *(const f32x4*)(s5d + l * 256 + n4);
; #pragma unroll
;         for (int tb = 0; tb < 2; ++tb) { const u32x2 yw = eyw[tb][c4], uw = euw[tb][c4], gw = egw[tb][c4];
;             const float y0 = bflo(yw.x), y1 = bfhi(yw.x), y2 = bflo(yw.y), y3 = bfhi(yw.y), u0 = bflo(uw.x), u1 = bfhi(uw.x), u2 = bflo(uw.y), u3 = bfhi(uw.y);
;             const float g0 = gelu_tanh(y0 + dd[0] * u0), g1 = gelu_tanh(y1 + dd[1] * u1), g2 = gelu_tanh(y2 + dd[2] * u2), g3 = gelu_tanh(y3 + dd[3] * u3);
;             u32x2 w; w.x = cvt_pk_bf16(g0 * sigm(acc[tb][0]) * siluf(bflo(gw.x)), g1 * sigm(acc[tb][1]) * siluf(bfhi(gw.x)));
;             w.y = cvt_pk_bf16(g2 * sigm(acc[tb][2]) * siluf(bflo(gw.y)), g3 * sigm(acc[tb][3]) * siluf(bfhi(gw.y)));
;             *(u32x2*)(Z1 + (row0 + tb * 16) * 256 + n4) = w; } }
	v_fmac_f32_e32 v84, v78, v85
	v_mul_f32_e32 v85, 0x3d372713, v84
	v_mul_f32_e32 v85, v84, v85
	v_fma_f32 v85, v84, v85, v84
	v_mul_f32_e32 v85, 0x3f4c422a, v85
	v_add_f32_e32 v85, v85, v85
	v_mul_f32_e32 v85, 0xbfb8aa3b, v85
	v_exp_f32_e32 v85, v85
	v_mfma_f32_16x16x32_bf16 v[74:77], v[86:89], v[46:49], v[74:77]
	v_and_b32_e32 v86, 0xffff0000, v172
	v_and_b32_e32 v87, 0xffff0000, v192
	v_add_f32_e32 v85, 1.0, v85
	v_rcp_f32_e32 v85, v85
	v_fmac_f32_e32 v86, v79, v87
	v_lshlrev_b32_e32 v88, 16, v173
	v_lshlrev_b32_e32 v89, 16, v193
	v_mul_f32_e32 v85, v84, v85
	v_mul_f32_e32 v84, 0x3d372713, v86
	v_mul_f32_e32 v84, v86, v84
	v_fma_f32 v84, v86, v84, v86
	v_mul_f32_e32 v84, 0x3f4c422a, v84
	v_add_f32_e32 v84, v84, v84
	v_mul_f32_e32 v84, 0xbfb8aa3b, v84
	v_exp_f32_e32 v84, v84
	v_fmac_f32_e32 v88, v80, v89
	v_mfma_f32_16x16x32_bf16 v[70:73], v[90:93], v[18:21], v[70:73]
	v_lshlrev_b32_e32 v172, 16, v129
	v_add_f32_e32 v84, 1.0, v84
	v_rcp_f32_e32 v84, v84
	v_mfma_f32_16x16x32_bf16 v[70:73], v[94:97], v[22:25], v[70:73]
	v_lshlrev_b32_e32 v129, 16, v126
	v_and_b32_e32 v126, 0xffff0000, v126
	v_mul_f32_e32 v87, v86, v84
	v_mul_f32_e32 v84, 0x3d372713, v88
	v_mul_f32_e32 v84, v88, v84
	v_fma_f32 v84, v88, v84, v88
	v_mul_f32_e32 v84, 0x3f4c422a, v84
	v_add_f32_e32 v84, v84, v84
	v_mul_f32_e32 v84, 0xbfb8aa3b, v84
	v_exp_f32_e32 v84, v84
	v_mfma_f32_16x16x32_bf16 v[74:77], v[90:93], v[50:53], v[74:77]
	v_and_b32_e32 v90, 0xffff0000, v173
	v_and_b32_e32 v91, 0xffff0000, v193
	v_add_f32_e32 v84, 1.0, v84
	v_rcp_f32_e32 v84, v84
	v_mfma_f32_16x16x32_bf16 v[70:73], v[98:101], v[26:29], v[70:73]
	v_fmac_f32_e32 v90, v81, v91
	v_and_b32_e32 v86, 0xffff0000, v226
	v_mul_f32_e32 v89, v88, v84
	v_mul_f32_e32 v84, 0x3d372713, v90
	v_mul_f32_e32 v84, v90, v84
	v_mfma_f32_16x16x32_bf16 v[70:73], v[102:105], v[30:33], v[70:73]
	v_fma_f32 v84, v90, v84, v90
	v_mul_f32_e32 v84, 0x3f4c422a, v84
	v_add_f32_e32 v84, v84, v84
	v_mul_f32_e32 v84, 0xbfb8aa3b, v84
	v_mfma_f32_16x16x32_bf16 v[70:73], v[106:109], v[34:37], v[70:73]
	v_exp_f32_e32 v84, v84
	v_lshlrev_b32_e32 v88, 16, v227
	v_lshlrev_b32_e32 v173, 16, v127
	v_mfma_f32_16x16x32_bf16 v[74:77], v[94:97], v[54:57], v[74:77]
	v_add_f32_e32 v84, 1.0, v84
	s_nop 2
	v_mul_f32_e32 v70, 0xbfb8aa3b, v70
	v_rcp_f32_e32 v84, v84
	v_exp_f32_e32 v70, v70
	v_mfma_f32_16x16x32_bf16 v[74:77], v[98:101], v[58:61], v[74:77]
	v_mul_f32_e32 v91, v90, v84
	v_add_f32_e32 v70, 1.0, v70
	v_lshlrev_b32_e32 v84, 16, v226
	v_rcp_f32_e32 v93, v70
	v_mul_f32_e32 v70, 0xbfb8aa3b, v84
	v_exp_f32_e32 v70, v70
	v_and_b32_e32 v90, 0xffff0000, v227
	v_mfma_f32_16x16x32_bf16 v[74:77], v[102:105], v[62:65], v[74:77]
	v_add_f32_e32 v70, 1.0, v70
	v_rcp_f32_e32 v92, v70
	v_mul_f32_e32 v70, 0xbfb8aa3b, v71
	v_exp_f32_e32 v70, v70
	v_mfma_f32_16x16x32_bf16 v[74:77], v[106:109], v[66:69], v[74:77]
	v_mul_f32_e64 v84, v92, v84
	v_mul_f32_e64 v85, v93, v85
	v_add_f32_e32 v70, 1.0, v70
	v_rcp_f32_e32 v71, v70
	v_mul_f32_e32 v70, 0xbfb8aa3b, v86
	v_exp_f32_e32 v70, v70
	v_mul_f32_e32 v84, v84, v85
	s_waitcnt lgkmcnt(0)
	v_mfma_f32_16x16x32_bf16 v[102:105], v[110:113], v[2:5], 0
	v_add_f32_e32 v70, 1.0, v70
	v_rcp_f32_e32 v70, v70
	v_mfma_f32_16x16x32_bf16 v[106:109], v[110:113], v[38:41], 0
	v_mul_f32_e64 v70, v70, v86
	v_mul_f32_e64 v71, v71, v87
	v_mul_f32_e32 v70, v70, v71
	v_mul_f32_e32 v71, 0xbfb8aa3b, v72
	v_mul_f32_e32 v72, 0xbfb8aa3b, v73
	v_exp_f32_e32 v71, v71
	v_exp_f32_e32 v72, v72
	v_cvt_pk_bf16_f32 v70, v84, v70
	v_lshlrev_b32_e32 v86, 16, v231
	v_add_f32_e32 v71, 1.0, v71
	v_add_f32_e32 v72, 1.0, v72
	v_rcp_f32_e32 v85, v71
	v_mul_f32_e32 v71, 0xbfb8aa3b, v88
	v_rcp_f32_e32 v73, v72
	v_mul_f32_e32 v72, 0xbfb8aa3b, v90
	v_exp_f32_e32 v71, v71
	v_exp_f32_e32 v72, v72
	v_and_b32_e32 v87, 0xffff0000, v231
	v_mfma_f32_16x16x32_bf16 v[102:105], v[130:133], v[6:9], v[102:105]
	v_add_f32_e32 v71, 1.0, v71
	v_add_f32_e32 v72, 1.0, v72
	v_rcp_f32_e32 v84, v71
	v_rcp_f32_e32 v72, v72
	v_mfma_f32_16x16x32_bf16 v[106:109], v[130:133], v[42:45], v[106:109]
	v_or_b32_e32 v130, 32, v158
	v_pk_mul_f32 v[84:85], v[84:85], v[88:89]
	v_pk_mul_f32 v[72:73], v[72:73], v[90:91]
	v_mul_f32_e32 v71, v84, v85
	v_mul_f32_e32 v72, v72, v73
	v_cvt_pk_bf16_f32 v71, v71, v72
	v_lshl_add_u64 v[72:73], v[82:83], 0, v[114:115]
	flat_store_dwordx2 v[72:73], v[70:71]
	v_lshlrev_b32_e32 v70, 16, v228
	v_lshlrev_b32_e32 v71, 16, v230
	v_fmac_f32_e32 v70, v78, v71
	v_mul_f32_e32 v71, 0x3d372713, v70
	v_mul_f32_e32 v71, v70, v71
	v_fma_f32 v71, v70, v71, v70
	v_mul_f32_e32 v71, 0x3f4c422a, v71
	v_add_f32_e32 v71, v71, v71
	v_mul_f32_e32 v71, 0xbfb8aa3b, v71
	v_exp_f32_e32 v71, v71
	v_and_b32_e32 v72, 0xffff0000, v228
	v_and_b32_e32 v73, 0xffff0000, v230
	v_fmac_f32_e32 v72, v79, v73
	v_add_f32_e32 v71, 1.0, v71
	v_rcp_f32_e32 v71, v71
	v_lshlrev_b32_e32 v84, 16, v229
	v_fmac_f32_e32 v84, v80, v86
	v_and_b32_e32 v85, 0xffff0000, v229
	v_mul_f32_e32 v71, v70, v71
	v_mul_f32_e32 v70, 0x3d372713, v72
	v_mul_f32_e32 v70, v72, v70
	v_fma_f32 v70, v72, v70, v72
	v_mul_f32_e32 v70, 0x3f4c422a, v70
	v_add_f32_e32 v70, v70, v70
	v_mul_f32_e32 v70, 0xbfb8aa3b, v70
	v_exp_f32_e32 v70, v70
	v_fmac_f32_e32 v85, v81, v87
	v_lshlrev_b32_e32 v78, 16, v233
	v_mfma_f32_16x16x32_bf16 v[102:105], v[180:183], v[14:17], v[102:105]
	v_add_f32_e32 v70, 1.0, v70
	v_rcp_f32_e32 v70, v70
	v_and_b32_e32 v80, 0xffff0000, v233
	v_mfma_f32_16x16x32_bf16 v[106:109], v[180:183], v[46:49], v[106:109]
	v_and_b32_e32 v180, 0xffff0000, v127
	v_mul_f32_e32 v73, v72, v70
	v_mul_f32_e32 v70, 0x3d372713, v84
	v_mul_f32_e32 v70, v84, v70
	v_fma_f32 v70, v84, v70, v84
	v_mul_f32_e32 v70, 0x3f4c422a, v70
; __device__ __forceinline__ unsigned cvt_pk_bf16(float lo, float hi) { unsigned r; asm volatile("v_cvt_pk_bf16_f32 %0, %1, %2" : "=v"(r) : "v"(lo), "v"(hi)); return r; }
; __device__ __forceinline__ float bflo(unsigned w) { return __uint_as_float(w << 16); }
; __device__ __forceinline__ float bfhi(unsigned w) { return __uint_as_float(w & 0xffff0000u); }
; __device__ __forceinline__ float sigm(float x) { return __builtin_amdgcn_rcpf(1.f + __expf(-x)); }
; __device__ __forceinline__ float siluf(float x) { return x * __builtin_amdgcn_rcpf(1.f + __expf(-x)); }
; __device__ __forceinline__ float gelu_tanh(float x) { const float u = 0.7978845608028654f * (x + 0.044715f * x * x * x); return x * sigm(2.f * u); }
; #define MFMA16(a, b, c) __builtin_amdgcn_mfma_f32_16x16x32_bf16((a), (b), (c), 0, 0, 0)
; __device__ __forceinline__ void glu_task(int t, int l, const float* s5d, const bf16_t* P, const bf16_t* YB, const bf16_t* WGLU, bf16_t* Z1, int fr, int fq) {
;     ...
;     for (int c4 = 0; c4 < 4; ++c4) { f32x4 acc[2]; acc[0] = (f32x4){0.f, 0.f, 0.f, 0.f}; acc[1] = acc[0];
;         const int nrow = c4 < 3 ? (c4 + 1) * 16 : 0;
; #pragma unroll
;         for (int ks = 0; ks < 8; ++ks) wf[(c4 + 1) & 1][ks] = asfrag(ld8(wg0 + (size_t)nrow * 256 + ks * 32));
; #pragma unroll
;         for (int ks = 0; ks < 8; ++ks) { acc[0] = MFMA16(wf[c4 & 1][ks], bfr[0][ks], acc[0]); acc[1] = MFMA16(wf[c4 & 1][ks], bfr[1][ks], acc[1]); }
;         const int n4 = (cb0 + c4) * 16 + fq * 4;
;         const f32x4 dd = *(const f32x4*)(s5d + l * 256 + n4);
; #pragma unroll
;         for (int tb = 0; tb < 2; ++tb) { const u32x2 yw = eyw[tb][c4], uw = euw[tb][c4], gw = egw[tb][c4];
;             const float y0 = bflo(yw.x), y1 = bfhi(yw.x), y2 = bflo(yw.y), y3 = bfhi(yw.y), u0 = bflo(uw.x), u1 = bfhi(uw.x), u2 = bflo(uw.y), u3 = bfhi(uw.y);
;             const float g0 = gelu_tanh(y0 + dd[0] * u0), g1 = gelu_tanh(y1 + dd[1] * u1), g2 = gelu_tanh(y2 + dd[2] * u2), g3 = gelu_tanh(y3 + dd[3] * u3);
;             u32x2 w; w.x = cvt_pk_bf16(g0 * sigm(acc[tb][0]) * siluf(bflo(gw.x)), g1 * sigm(acc[tb][1]) * siluf(bfhi(gw.x)));
;             w.y = cvt_pk_bf16(g2 * sigm(acc[tb][2]) * siluf(bflo(gw.y)), g3 * sigm(acc[tb][3]) * siluf(bfhi(gw.y)));
;             *(u32x2*)(Z1 + (row0 + tb * 16) * 256 + n4) = w; } }
	v_add_f32_e32 v70, v70, v70
	v_mul_f32_e32 v70, 0xbfb8aa3b, v70
	v_exp_f32_e32 v70, v70
	v_mfma_f32_16x16x32_bf16 v[102:105], v[184:187], v[18:21], v[102:105]
	v_mov_b32_e32 v131, v1
	v_lshl_add_u64 v[132:133], s[40:41], 0, v[130:131]
	v_add_f32_e32 v70, 1.0, v70
	v_rcp_f32_e32 v70, v70
	v_mfma_f32_16x16x32_bf16 v[106:109], v[184:187], v[50:53], v[106:109]
	v_mul_f32_e32 v79, v84, v70
	v_mul_f32_e32 v70, 0x3d372713, v85
	v_mul_f32_e32 v70, v85, v70
	v_fma_f32 v70, v85, v70, v85
	v_mul_f32_e32 v70, 0x3f4c422a, v70
	v_add_f32_e32 v70, v70, v70
	v_mul_f32_e32 v70, 0xbfb8aa3b, v70
	v_exp_f32_e32 v70, v70
	v_mfma_f32_16x16x32_bf16 v[102:105], v[188:191], v[22:25], v[102:105]
	v_add_f32_e32 v70, 1.0, v70
	v_rcp_f32_e32 v70, v70
	v_mfma_f32_16x16x32_bf16 v[106:109], v[188:191], v[54:57], v[106:109]
	v_mul_f32_e32 v81, v85, v70
	v_mul_f32_e32 v70, 0xbfb8aa3b, v74
	v_exp_f32_e32 v70, v70
	v_mfma_f32_16x16x32_bf16 v[102:105], v[214:217], v[26:29], v[102:105]
	v_add_f32_e32 v70, 1.0, v70
	v_rcp_f32_e32 v85, v70
	v_lshlrev_b32_e32 v70, 16, v232
	v_mul_f32_e32 v72, 0xbfb8aa3b, v70
	v_exp_f32_e32 v72, v72
	v_mfma_f32_16x16x32_bf16 v[106:109], v[214:217], v[58:61], v[106:109]
	v_add_f32_e32 v72, 1.0, v72
	v_rcp_f32_e32 v84, v72
	v_and_b32_e32 v72, 0xffff0000, v232
	v_mfma_f32_16x16x32_bf16 v[102:105], v[218:221], v[30:33], v[102:105]
	v_mul_f32_e64 v70, v84, v70
	v_mul_f32_e64 v71, v85, v71
	v_mul_f32_e32 v74, v70, v71
	v_mul_f32_e32 v70, 0xbfb8aa3b, v75
	v_exp_f32_e32 v70, v70
	v_mfma_f32_16x16x32_bf16 v[106:109], v[218:221], v[62:65], v[106:109]
	v_add_f32_e32 v70, 1.0, v70
	v_rcp_f32_e32 v71, v70
	v_mul_f32_e32 v70, 0xbfb8aa3b, v72
	v_exp_f32_e32 v70, v70
	v_mfma_f32_16x16x32_bf16 v[110:113], v[222:225], v[34:37], v[102:105]
	v_add_f32_e32 v70, 1.0, v70
	v_rcp_f32_e32 v70, v70
	v_mfma_f32_16x16x32_bf16 v[102:105], v[222:225], v[66:69], v[106:109]
	s_nop 4
	v_mul_f32_e32 v110, 0xbfb8aa3b, v110
	v_exp_f32_e32 v110, v110
	v_pk_mul_f32 v[70:71], v[70:71], v[72:73]
	v_add_f32_e32 v110, 1.0, v110
	v_mul_f32_e32 v70, v70, v71
	v_mul_f32_e32 v71, 0xbfb8aa3b, v76
	v_exp_f32_e32 v71, v71
	v_cvt_pk_bf16_f32 v70, v74, v70
	v_rcp_f32_e32 v183, v110
	v_mul_f32_e32 v102, 0xbfb8aa3b, v102
	v_add_f32_e32 v71, 1.0, v71
	v_rcp_f32_e32 v73, v71
	v_mul_f32_e32 v71, 0xbfb8aa3b, v78
	v_exp_f32_e32 v71, v71
	v_exp_f32_e32 v102, v102
	v_add_f32_e32 v71, 1.0, v71
	v_rcp_f32_e32 v72, v71
	v_add_f32_e32 v102, 1.0, v102
	v_pk_mul_f32 v[72:73], v[72:73], v[78:79]
	s_nop 0
	v_mul_f32_e32 v71, v72, v73
	v_mul_f32_e32 v72, 0xbfb8aa3b, v77
	v_exp_f32_e32 v72, v72
	s_nop 0
	v_add_f32_e32 v72, 1.0, v72
	v_rcp_f32_e32 v73, v72
	v_mul_f32_e32 v72, 0xbfb8aa3b, v80
	v_exp_f32_e32 v72, v72
	s_nop 0
	v_add_f32_e32 v72, 1.0, v72
	v_rcp_f32_e32 v72, v72
	s_nop 0
	v_pk_mul_f32 v[72:73], v[72:73], v[80:81]
	s_nop 0
	v_mul_f32_e32 v72, v72, v73
	v_cvt_pk_bf16_f32 v71, v71, v72
	v_lshl_add_u64 v[72:73], v[82:83], 0, v[138:139]
	flat_store_dwordx2 v[72:73], v[70:71]
	v_add_co_u32_e32 v70, vcc, s0, v116
	s_nop 1
	v_addc_co_u32_e32 v71, vcc, 0, v117, vcc
	flat_load_dwordx4 v[98:101], v[70:71]
	flat_load_dwordx4 v[94:97], v[70:71] offset:64
	flat_load_dwordx4 v[90:93], v[70:71] offset:128
	flat_load_dwordx4 v[86:89], v[70:71] offset:192
	flat_load_dwordx4 v[82:85], v[70:71] offset:256
	flat_load_dwordx4 v[78:81], v[70:71] offset:320
	flat_load_dwordx4 v[74:77], v[70:71] offset:384
	s_nop 0
	flat_load_dwordx4 v[70:73], v[70:71] offset:448
	s_nop 0
	global_load_dwordx4 v[106:109], v178, s[22:23] offset:64
	s_waitcnt vmcnt(0)
	v_fmac_f32_e32 v128, v107, v126
	v_mul_f32_e32 v126, 0x3d372713, v128
	v_mul_f32_e32 v126, v128, v126
	v_fma_f32 v126, v128, v126, v128
	v_mul_f32_e32 v126, 0x3f4c422a, v126
	v_add_f32_e32 v126, v126, v126
	v_mul_f32_e32 v126, 0xbfb8aa3b, v126
	v_exp_f32_e32 v126, v126
	v_fmac_f32_e32 v172, v108, v173
	v_fmac_f32_e32 v159, v106, v129
	v_fmac_f32_e32 v179, v109, v180
	v_add_f32_e32 v126, 1.0, v126
	v_rcp_f32_e32 v126, v126
	v_mul_f32_e32 v127, 0x3d372713, v159
	v_mul_f32_e32 v127, v159, v127
	v_fma_f32 v127, v159, v127, v159
	v_mul_f32_e32 v129, v128, v126
	v_mul_f32_e32 v126, 0x3d372713, v172
	v_mul_f32_e32 v126, v172, v126
	v_fma_f32 v126, v172, v126, v172
	v_mul_f32_e32 v126, 0x3f4c422a, v126
	v_add_f32_e32 v126, v126, v126
	v_mul_f32_e32 v126, 0xbfb8aa3b, v126
	v_exp_f32_e32 v126, v126
	v_and_b32_e32 v128, 0xffff0000, v124
	v_mul_f32_e32 v127, 0x3f4c422a, v127
	v_add_f32_e32 v127, v127, v127
	v_add_f32_e32 v126, 1.0, v126
	v_rcp_f32_e32 v126, v126
	v_mul_f32_e32 v127, 0xbfb8aa3b, v127
	v_exp_f32_e32 v127, v127
	v_and_b32_e32 v180, 0xffff0000, v125
	v_mul_f32_e32 v173, v172, v126
	v_mul_f32_e32 v126, 0x3d372713, v179
	v_mul_f32_e32 v126, v179, v126
	v_fma_f32 v126, v179, v126, v179
	v_mul_f32_e32 v126, 0x3f4c422a, v126
	v_add_f32_e32 v126, v126, v126
	v_mul_f32_e32 v126, 0xbfb8aa3b, v126
	v_exp_f32_e32 v126, v126
	v_add_f32_e32 v127, 1.0, v127
	v_rcp_f32_e32 v127, v127
	v_lshlrev_b32_e32 v172, 16, v125
	v_add_f32_e32 v126, 1.0, v126
	v_rcp_f32_e32 v126, v126
	v_mul_f32_e32 v127, v159, v127
	v_mul_f32_e32 v181, v179, v126
	v_lshlrev_b32_e32 v126, 16, v124
	v_mul_f32_e32 v110, 0xbfb8aa3b, v126
	v_exp_f32_e32 v110, v110
	s_nop 0
	v_add_f32_e32 v110, 1.0, v110
	v_rcp_f32_e32 v182, v110
	v_mul_f32_e32 v110, 0xbfb8aa3b, v111
	v_exp_f32_e32 v110, v110
	v_pk_mul_f32 v[126:127], v[182:183], v[126:127]
	s_nop 0
	v_mul_f32_e32 v126, v126, v127
	v_add_f32_e32 v110, 1.0, v110
	v_rcp_f32_e32 v111, v110
	v_mul_f32_e32 v110, 0xbfb8aa3b, v128
	v_exp_f32_e32 v110, v110
	s_nop 0
	v_add_f32_e32 v110, 1.0, v110
	v_rcp_f32_e32 v110, v110
	s_nop 0
	v_pk_mul_f32 v[110:111], v[110:111], v[128:129]
; __device__ __forceinline__ unsigned cvt_pk_bf16(float lo, float hi) { unsigned r; asm volatile("v_cvt_pk_bf16_f32 %0, %1, %2" : "=v"(r) : "v"(lo), "v"(hi)); return r; }
; __device__ __forceinline__ float bflo(unsigned w) { return __uint_as_float(w << 16); }
; __device__ __forceinline__ float bfhi(unsigned w) { return __uint_as_float(w & 0xffff0000u); }
; __device__ __forceinline__ float sigm(float x) { return __builtin_amdgcn_rcpf(1.f + __expf(-x)); }
; __device__ __forceinline__ float siluf(float x) { return x * __builtin_amdgcn_rcpf(1.f + __expf(-x)); }
; __device__ __forceinline__ float gelu_tanh(float x) { const float u = 0.7978845608028654f * (x + 0.044715f * x * x * x); return x * sigm(2.f * u); }
; #define MFMA16(a, b, c) __builtin_amdgcn_mfma_f32_16x16x32_bf16((a), (b), (c), 0, 0, 0)
; __device__ __forceinline__ void glu_task(int t, int l, const float* s5d, const bf16_t* P, const bf16_t* YB, const bf16_t* WGLU, bf16_t* Z1, int fr, int fq) {
;     ...
;     for (int c4 = 0; c4 < 4; ++c4) { f32x4 acc[2]; acc[0] = (f32x4){0.f, 0.f, 0.f, 0.f}; acc[1] = acc[0];
;         const int nrow = c4 < 3 ? (c4 + 1) * 16 : 0;
; #pragma unroll
;         for (int ks = 0; ks < 8; ++ks) wf[(c4 + 1) & 1][ks] = asfrag(ld8(wg0 + (size_t)nrow * 256 + ks * 32));
; #pragma unroll
;         for (int ks = 0; ks < 8; ++ks) { acc[0] = MFMA16(wf[c4 & 1][ks], bfr[0][ks], acc[0]); acc[1] = MFMA16(wf[c4 & 1][ks], bfr[1][ks], acc[1]); }
;         const int n4 = (cb0 + c4) * 16 + fq * 4;
;         const f32x4 dd = *(const f32x4*)(s5d + l * 256 + n4);
; #pragma unroll
;         for (int tb = 0; tb < 2; ++tb) { const u32x2 yw = eyw[tb][c4], uw = euw[tb][c4], gw = egw[tb][c4];
;             const float y0 = bflo(yw.x), y1 = bfhi(yw.x), y2 = bflo(yw.y), y3 = bfhi(yw.y), u0 = bflo(uw.x), u1 = bfhi(uw.x), u2 = bflo(uw.y), u3 = bfhi(uw.y);
;             const float g0 = gelu_tanh(y0 + dd[0] * u0), g1 = gelu_tanh(y1 + dd[1] * u1), g2 = gelu_tanh(y2 + dd[2] * u2), g3 = gelu_tanh(y3 + dd[3] * u3);
;             u32x2 w; w.x = cvt_pk_bf16(g0 * sigm(acc[tb][0]) * siluf(bflo(gw.x)), g1 * sigm(acc[tb][1]) * siluf(bfhi(gw.x)));
;             w.y = cvt_pk_bf16(g2 * sigm(acc[tb][2]) * siluf(bflo(gw.y)), g3 * sigm(acc[tb][3]) * siluf(bfhi(gw.y)));
;             *(u32x2*)(Z1 + (row0 + tb * 16) * 256 + n4) = w; } }
	s_nop 0
	v_mul_f32_e32 v110, v110, v111
	v_mul_f32_e32 v111, 0xbfb8aa3b, v112
	v_mul_f32_e32 v112, 0xbfb8aa3b, v113
	v_exp_f32_e32 v111, v111
	v_exp_f32_e32 v112, v112
	v_cvt_pk_bf16_f32 v110, v126, v110
	v_add_f32_e32 v111, 1.0, v111
	v_add_f32_e32 v112, 1.0, v112
	v_rcp_f32_e32 v127, v111
	v_mul_f32_e32 v111, 0xbfb8aa3b, v172
	v_rcp_f32_e32 v113, v112
	v_mul_f32_e32 v112, 0xbfb8aa3b, v180
	v_exp_f32_e32 v111, v111
	v_exp_f32_e32 v112, v112
	v_add_f32_e32 v111, 1.0, v111
	v_add_f32_e32 v112, 1.0, v112
	v_rcp_f32_e32 v126, v111
	v_rcp_f32_e32 v112, v112
	v_pk_mul_f32 v[126:127], v[126:127], v[172:173]
	v_pk_mul_f32 v[112:113], v[112:113], v[180:181]
	v_mul_f32_e32 v111, v126, v127
	v_mul_f32_e32 v112, v112, v113
	v_lshl_add_u64 v[172:173], s[40:41], 0, v[114:115]
	v_cvt_pk_bf16_f32 v111, v111, v112
	v_lshl_add_u64 v[112:113], v[172:173], 0, v[130:131]
	flat_store_dwordx2 v[112:113], v[110:111]
	v_lshlrev_b32_e32 v110, 16, v122
	v_lshlrev_b32_e32 v111, 16, v120
	v_fmac_f32_e32 v110, v106, v111
	v_mul_f32_e32 v106, 0x3d372713, v110
	v_mul_f32_e32 v106, v110, v106
	v_fma_f32 v106, v110, v106, v110
	v_mul_f32_e32 v106, 0x3f4c422a, v106
	v_add_f32_e32 v106, v106, v106
	v_mul_f32_e32 v106, 0xbfb8aa3b, v106
	v_exp_f32_e32 v106, v106
	v_and_b32_e32 v112, 0xffff0000, v122
	v_and_b32_e32 v115, 0xffff0000, v120
	v_fmac_f32_e32 v112, v107, v115
	v_add_f32_e32 v106, 1.0, v106
	v_rcp_f32_e32 v106, v106
	v_lshlrev_b32_e32 v113, 16, v123
	v_lshlrev_b32_e32 v120, 16, v121
	v_fmac_f32_e32 v113, v108, v120
	v_mul_f32_e32 v111, v110, v106
	v_mul_f32_e32 v106, 0x3d372713, v112
	v_mul_f32_e32 v106, v112, v106
	v_fma_f32 v106, v112, v106, v112
	v_mul_f32_e32 v106, 0x3f4c422a, v106
	v_add_f32_e32 v106, v106, v106
	v_mul_f32_e32 v106, 0xbfb8aa3b, v106
	v_exp_f32_e32 v106, v106
	v_and_b32_e32 v114, 0xffff0000, v123
	v_and_b32_e32 v121, 0xffff0000, v121
	v_fmac_f32_e32 v114, v109, v121
	v_add_f32_e32 v106, 1.0, v106
	v_rcp_f32_e32 v106, v106
	v_lshlrev_b32_e32 v110, 16, v118
	v_rcp_f32_e32 v115, v102
	v_mul_f32_e32 v102, 0xbfb8aa3b, v110
	v_mul_f32_e32 v107, v112, v106
	v_mul_f32_e32 v106, 0x3d372713, v113
	v_mul_f32_e32 v106, v113, v106
	v_fma_f32 v106, v113, v106, v113
	v_mul_f32_e32 v106, 0x3f4c422a, v106
	v_add_f32_e32 v106, v106, v106
	v_mul_f32_e32 v106, 0xbfb8aa3b, v106
	v_exp_f32_e32 v106, v106
	v_exp_f32_e32 v102, v102
	s_waitcnt lgkmcnt(0)
	v_mfma_f32_16x16x32_bf16 v[180:183], v[98:101], v[2:5], 0
	v_lshlrev_b32_e32 v112, 16, v119
	v_add_f32_e32 v106, 1.0, v106
	v_rcp_f32_e32 v106, v106
	v_add_f32_e32 v102, 1.0, v102
	v_mfma_f32_16x16x32_bf16 v[98:101], v[98:101], v[38:41], 0
	v_mul_f32_e32 v113, v113, v106
	v_mul_f32_e32 v106, 0x3d372713, v114
	v_mul_f32_e32 v106, v114, v106
	v_fma_f32 v106, v114, v106, v114
	v_mul_f32_e32 v106, 0x3f4c422a, v106
	v_add_f32_e32 v106, v106, v106
	v_mul_f32_e32 v106, 0xbfb8aa3b, v106
	v_exp_f32_e32 v106, v106
	v_mfma_f32_16x16x32_bf16 v[180:183], v[94:97], v[6:9], v[180:183]
	v_add_f32_e32 v106, 1.0, v106
	v_rcp_f32_e32 v106, v106
	v_mfma_f32_16x16x32_bf16 v[94:97], v[94:97], v[42:45], v[98:101]
	v_mul_f32_e32 v109, v114, v106
	v_rcp_f32_e32 v114, v102
	v_mul_f32_e32 v102, 0xbfb8aa3b, v103
	v_exp_f32_e32 v102, v102
	v_and_b32_e32 v106, 0xffff0000, v118
	v_mfma_f32_16x16x32_bf16 v[98:101], v[90:93], v[14:17], v[180:183]
	v_mul_f32_e64 v110, v114, v110
	v_mul_f32_e64 v111, v115, v111
	v_add_f32_e32 v102, 1.0, v102
	v_rcp_f32_e32 v103, v102
	v_mul_f32_e32 v102, 0xbfb8aa3b, v106
	v_exp_f32_e32 v102, v102
	v_mfma_f32_16x16x32_bf16 v[90:93], v[90:93], v[46:49], v[94:97]
	v_mul_f32_e32 v108, v110, v111
	v_add_f32_e32 v102, 1.0, v102
	v_rcp_f32_e32 v102, v102
	v_mfma_f32_16x16x32_bf16 v[94:97], v[86:89], v[18:21], v[98:101]
	v_mul_f32_e64 v102, v102, v106
	v_mul_f32_e64 v103, v103, v107
	v_mul_f32_e32 v102, v102, v103
	v_mul_f32_e32 v103, 0xbfb8aa3b, v104
	v_mul_f32_e32 v104, 0xbfb8aa3b, v105
	v_exp_f32_e32 v103, v103
	v_exp_f32_e32 v104, v104
	v_cvt_pk_bf16_f32 v102, v108, v102
	v_and_b32_e32 v108, 0xffff0000, v119
	v_add_f32_e32 v103, 1.0, v103
	v_add_f32_e32 v104, 1.0, v104
	v_mfma_f32_16x16x32_bf16 v[86:89], v[86:89], v[50:53], v[90:93]
	v_rcp_f32_e32 v107, v103
	v_mul_f32_e32 v103, 0xbfb8aa3b, v112
	v_rcp_f32_e32 v105, v104
	v_mul_f32_e32 v104, 0xbfb8aa3b, v108
	v_exp_f32_e32 v103, v103
	v_exp_f32_e32 v104, v104
	v_mfma_f32_16x16x32_bf16 v[90:93], v[82:85], v[22:25], v[94:97]
	v_add_f32_e32 v103, 1.0, v103
	v_add_f32_e32 v104, 1.0, v104
	v_mfma_f32_16x16x32_bf16 v[82:85], v[82:85], v[54:57], v[86:89]
	v_rcp_f32_e32 v106, v103
	v_rcp_f32_e32 v104, v104
	v_pk_mul_f32 v[106:107], v[106:107], v[112:113]
	v_mfma_f32_16x16x32_bf16 v[86:89], v[78:81], v[26:29], v[90:93]
	v_mul_f32_e64 v104, v104, v108
	v_mul_f32_e64 v105, v105, v109
	v_mul_f32_e32 v103, v106, v107
	v_mul_f32_e32 v104, v104, v105
	v_mfma_f32_16x16x32_bf16 v[78:81], v[78:81], v[58:61], v[82:85]
	v_cvt_pk_bf16_f32 v103, v103, v104
	v_lshl_add_u64 v[104:105], v[132:133], 0, v[138:139]
	flat_store_dwordx2 v[104:105], v[102:103]
	v_mfma_f32_16x16x32_bf16 v[82:85], v[74:77], v[30:33], v[86:89]
	v_add_co_u32_e32 v102, vcc, s18, v116
	v_lshlrev_b32_e32 v90, 16, v171
	v_mfma_f32_16x16x32_bf16 v[74:77], v[74:77], v[62:65], v[78:81]
	v_addc_co_u32_e32 v103, vcc, 0, v117, vcc
	flat_load_dwordx4 v[130:133], v[102:103]
	flat_load_dwordx4 v[126:129], v[102:103] offset:64
	flat_load_dwordx4 v[122:125], v[102:103] offset:128
	flat_load_dwordx4 v[118:121], v[102:103] offset:192
	flat_load_dwordx4 v[114:117], v[102:103] offset:256
	flat_load_dwordx4 v[110:113], v[102:103] offset:320
	flat_load_dwordx4 v[106:109], v[102:103] offset:384
	s_nop 0
	flat_load_dwordx4 v[102:105], v[102:103] offset:448
	v_mfma_f32_16x16x32_bf16 v[78:81], v[70:73], v[34:37], v[82:85]
	v_lshlrev_b32_e32 v86, 16, v170
	v_lshlrev_b32_e32 v87, 16, v168
	v_and_b32_e32 v88, 0xffff0000, v170
	v_mfma_f32_16x16x32_bf16 v[70:73], v[70:73], v[66:69], v[74:77]
	v_and_b32_e32 v89, 0xffff0000, v168
	v_lshlrev_b32_e32 v91, 16, v169
	v_and_b32_e32 v92, 0xffff0000, v171
	global_load_dwordx4 v[74:77], v178, s[22:23] offset:128
	v_and_b32_e32 v93, 0xffff0000, v169
	v_mul_f32_e32 v78, 0xbfb8aa3b, v78
	v_exp_f32_e32 v78, v78
	v_or_b32_e32 v82, 64, v158
	v_mov_b32_e32 v83, v1
	v_lshl_add_u64 v[84:85], s[40:41], 0, v[82:83]
	v_add_f32_e32 v78, 1.0, v78
	v_rcp_f32_e32 v95, v78
	v_mul_f32_e32 v70, 0xbfb8aa3b, v70
	v_exp_f32_e32 v70, v70
	s_waitcnt vmcnt(0) lgkmcnt(0)
; __device__ __forceinline__ unsigned cvt_pk_bf16(float lo, float hi) { unsigned r; asm volatile("v_cvt_pk_bf16_f32 %0, %1, %2" : "=v"(r) : "v"(lo), "v"(hi)); return r; }
; __device__ __forceinline__ float bflo(unsigned w) { return __uint_as_float(w << 16); }
; __device__ __forceinline__ float bfhi(unsigned w) { return __uint_as_float(w & 0xffff0000u); }
; __device__ __forceinline__ float sigm(float x) { return __builtin_amdgcn_rcpf(1.f + __expf(-x)); }
; __device__ __forceinline__ float siluf(float x) { return x * __builtin_amdgcn_rcpf(1.f + __expf(-x)); }
; __device__ __forceinline__ float gelu_tanh(float x) { const float u = 0.7978845608028654f * (x + 0.044715f * x * x * x); return x * sigm(2.f * u); }
; #define MFMA16(a, b, c) __builtin_amdgcn_mfma_f32_16x16x32_bf16((a), (b), (c), 0, 0, 0)
; __device__ __forceinline__ void glu_task(int t, int l, const float* s5d, const bf16_t* P, const bf16_t* YB, const bf16_t* WGLU, bf16_t* Z1, int fr, int fq) {
;     ...
;     for (int c4 = 0; c4 < 4; ++c4) { f32x4 acc[2]; acc[0] = (f32x4){0.f, 0.f, 0.f, 0.f}; acc[1] = acc[0];
;         const int nrow = c4 < 3 ? (c4 + 1) * 16 : 0;
; #pragma unroll
;         for (int ks = 0; ks < 8; ++ks) wf[(c4 + 1) & 1][ks] = asfrag(ld8(wg0 + (size_t)nrow * 256 + ks * 32));
; #pragma unroll
;         for (int ks = 0; ks < 8; ++ks) { acc[0] = MFMA16(wf[c4 & 1][ks], bfr[0][ks], acc[0]); acc[1] = MFMA16(wf[c4 & 1][ks], bfr[1][ks], acc[1]); }
;         const int n4 = (cb0 + c4) * 16 + fq * 4;
;         const f32x4 dd = *(const f32x4*)(s5d + l * 256 + n4);
; #pragma unroll
;         for (int tb = 0; tb < 2; ++tb) { const u32x2 yw = eyw[tb][c4], uw = euw[tb][c4], gw = egw[tb][c4];
;             const float y0 = bflo(yw.x), y1 = bfhi(yw.x), y2 = bflo(yw.y), y3 = bfhi(yw.y), u0 = bflo(uw.x), u1 = bfhi(uw.x), u2 = bflo(uw.y), u3 = bfhi(uw.y);
;             const float g0 = gelu_tanh(y0 + dd[0] * u0), g1 = gelu_tanh(y1 + dd[1] * u1), g2 = gelu_tanh(y2 + dd[2] * u2), g3 = gelu_tanh(y3 + dd[3] * u3);
;             u32x2 w; w.x = cvt_pk_bf16(g0 * sigm(acc[tb][0]) * siluf(bflo(gw.x)), g1 * sigm(acc[tb][1]) * siluf(bfhi(gw.x)));
;             w.y = cvt_pk_bf16(g2 * sigm(acc[tb][2]) * siluf(bflo(gw.y)), g3 * sigm(acc[tb][3]) * siluf(bfhi(gw.y)));
;             *(u32x2*)(Z1 + (row0 + tb * 16) * 256 + n4) = w; } }
	v_mfma_f32_16x16x32_bf16 v[2:5], v[130:133], v[2:5], 0
	v_add_f32_e32 v70, 1.0, v70
	v_subrev_co_u32_e32 v177, vcc, 1, v177
	v_mfma_f32_16x16x32_bf16 v[38:41], v[130:133], v[38:41], 0
	s_and_b64 s[6:7], s[42:43], vcc
	s_and_b64 s[6:7], s[6:7], exec
	s_cselect_b32 s5, s4, s19
	v_mfma_f32_16x16x32_bf16 v[2:5], v[126:129], v[6:9], v[2:5]
	s_and_b64 s[6:7], s[14:15], exec
	s_cselect_b32 s20, s5, s1
	s_cmp_ge_i32 s20, s19
	v_mfma_f32_16x16x32_bf16 v[6:9], v[126:129], v[42:45], v[38:41]
	v_fmac_f32_e32 v86, v74, v87
	v_mul_f32_e32 v87, 0x3d372713, v86
	v_mul_f32_e32 v87, v86, v87
	v_fma_f32 v87, v86, v87, v86
	v_mul_f32_e32 v87, 0x3f4c422a, v87
	v_add_f32_e32 v87, v87, v87
	v_mul_f32_e32 v87, 0xbfb8aa3b, v87
	v_exp_f32_e32 v87, v87
	v_fmac_f32_e32 v88, v75, v89
	v_fmac_f32_e32 v90, v76, v91
	v_fmac_f32_e32 v92, v77, v93
	v_add_f32_e32 v87, 1.0, v87
	v_rcp_f32_e32 v87, v87
	v_mfma_f32_16x16x32_bf16 v[2:5], v[122:125], v[14:17], v[2:5]
	v_mul_f32_e32 v87, v86, v87
	v_mul_f32_e32 v86, 0x3d372713, v88
	v_mul_f32_e32 v86, v88, v86
	v_fma_f32 v86, v88, v86, v88
	v_mul_f32_e32 v86, 0x3f4c422a, v86
	v_add_f32_e32 v86, v86, v86
	v_mul_f32_e32 v86, 0xbfb8aa3b, v86
	v_exp_f32_e32 v86, v86
	v_mfma_f32_16x16x32_bf16 v[6:9], v[122:125], v[46:49], v[6:9]
	v_add_f32_e32 v86, 1.0, v86
	v_rcp_f32_e32 v86, v86
	v_mfma_f32_16x16x32_bf16 v[2:5], v[118:121], v[18:21], v[2:5]
	v_or_b32_e32 v18, 0x60, v158
	v_mov_b32_e32 v19, v1
	v_mul_f32_e32 v89, v88, v86
	v_mul_f32_e32 v86, 0x3d372713, v90
	v_mul_f32_e32 v86, v90, v86
	v_fma_f32 v86, v90, v86, v90
	v_mul_f32_e32 v86, 0x3f4c422a, v86
	v_add_f32_e32 v86, v86, v86
	v_mul_f32_e32 v86, 0xbfb8aa3b, v86
	v_exp_f32_e32 v86, v86
	v_and_b32_e32 v88, 0xffff0000, v166
	v_mfma_f32_16x16x32_bf16 v[6:9], v[118:121], v[50:53], v[6:9]
	v_lshl_add_u64 v[20:21], s[40:41], 0, v[18:19]
	v_add_f32_e32 v86, 1.0, v86
	v_rcp_f32_e32 v86, v86
	v_mfma_f32_16x16x32_bf16 v[2:5], v[114:117], v[22:25], v[2:5]
	v_lshlrev_b32_e32 v22, 16, v156
	v_lshlrev_b32_e32 v23, 16, v148
	v_mul_f32_e32 v91, v90, v86
	v_mul_f32_e32 v86, 0x3d372713, v92
	v_mul_f32_e32 v86, v92, v86
	v_fma_f32 v86, v92, v86, v92
	v_mul_f32_e32 v86, 0x3f4c422a, v86
	v_add_f32_e32 v86, v86, v86
	v_mul_f32_e32 v86, 0xbfb8aa3b, v86
	v_exp_f32_e32 v86, v86
	v_lshlrev_b32_e32 v90, 16, v167
	v_mfma_f32_16x16x32_bf16 v[6:9], v[114:117], v[54:57], v[6:9]
	v_and_b32_e32 v24, 0xffff0000, v156
	v_add_f32_e32 v86, 1.0, v86
	v_rcp_f32_e32 v86, v86
	v_mfma_f32_16x16x32_bf16 v[2:5], v[110:113], v[26:29], v[2:5]
	v_and_b32_e32 v25, 0xffff0000, v148
	v_lshlrev_b32_e32 v26, 16, v157
	v_mul_f32_e32 v93, v92, v86
	v_lshlrev_b32_e32 v86, 16, v166
	v_mul_f32_e32 v78, 0xbfb8aa3b, v86
	v_exp_f32_e32 v78, v78
	v_and_b32_e32 v92, 0xffff0000, v167
	v_mfma_f32_16x16x32_bf16 v[6:9], v[110:113], v[58:61], v[6:9]
	v_lshlrev_b32_e32 v27, 16, v149
	v_add_f32_e32 v78, 1.0, v78
	v_rcp_f32_e32 v94, v78
	v_mul_f32_e32 v78, 0xbfb8aa3b, v79
	v_exp_f32_e32 v78, v78
	v_mfma_f32_16x16x32_bf16 v[2:5], v[106:109], v[30:33], v[2:5]
	v_mul_f32_e64 v86, v94, v86
	v_mul_f32_e64 v87, v95, v87
	v_and_b32_e32 v28, 0xffff0000, v157
	v_add_f32_e32 v78, 1.0, v78
	v_rcp_f32_e32 v79, v78
	v_mul_f32_e32 v78, 0xbfb8aa3b, v88
	v_exp_f32_e32 v78, v78
	v_mul_f32_e32 v86, v86, v87
	v_mfma_f32_16x16x32_bf16 v[6:9], v[106:109], v[62:65], v[6:9]
	v_and_b32_e32 v29, 0xffff0000, v149
	v_add_f32_e32 v78, 1.0, v78
	v_rcp_f32_e32 v78, v78
	v_mfma_f32_16x16x32_bf16 v[14:17], v[102:105], v[34:37], v[2:5]
	v_mul_f32_e64 v78, v78, v88
	v_mul_f32_e64 v79, v79, v89
	v_mul_f32_e32 v78, v78, v79
	v_mul_f32_e32 v79, 0xbfb8aa3b, v80
	v_mul_f32_e32 v80, 0xbfb8aa3b, v81
	v_exp_f32_e32 v79, v79
	v_exp_f32_e32 v80, v80
	v_cvt_pk_bf16_f32 v78, v86, v78
	v_mfma_f32_16x16x32_bf16 v[2:5], v[102:105], v[66:69], v[6:9]
	v_add_f32_e32 v79, 1.0, v79
	v_add_f32_e32 v80, 1.0, v80
	v_rcp_f32_e32 v87, v79
	v_mul_f32_e32 v79, 0xbfb8aa3b, v90
	v_rcp_f32_e32 v81, v80
	v_mul_f32_e32 v80, 0xbfb8aa3b, v92
	v_exp_f32_e32 v79, v79
	v_exp_f32_e32 v80, v80
	v_mul_f32_e32 v14, 0xbfb8aa3b, v14
	v_exp_f32_e32 v14, v14
	v_add_f32_e32 v79, 1.0, v79
	v_add_f32_e32 v80, 1.0, v80
	v_rcp_f32_e32 v86, v79
	v_rcp_f32_e32 v80, v80
	v_add_f32_e32 v14, 1.0, v14
	v_rcp_f32_e32 v31, v14
	v_pk_mul_f32 v[86:87], v[86:87], v[90:91]
	v_pk_mul_f32 v[80:81], v[80:81], v[92:93]
	v_mul_f32_e32 v79, v86, v87
	v_mul_f32_e32 v80, v80, v81
	v_cvt_pk_bf16_f32 v79, v79, v80
	v_lshl_add_u64 v[80:81], v[172:173], 0, v[82:83]
	flat_store_dwordx2 v[80:81], v[78:79]
	v_lshlrev_b32_e32 v78, 16, v164
	v_lshlrev_b32_e32 v79, 16, v162
	v_fmac_f32_e32 v78, v74, v79
	v_mul_f32_e32 v74, 0x3d372713, v78
	v_mul_f32_e32 v74, v78, v74
	v_fma_f32 v74, v78, v74, v78
	v_mul_f32_e32 v74, 0x3f4c422a, v74
	v_add_f32_e32 v74, v74, v74
	v_mul_f32_e32 v74, 0xbfb8aa3b, v74
	v_exp_f32_e32 v74, v74
	v_and_b32_e32 v80, 0xffff0000, v164
	v_and_b32_e32 v83, 0xffff0000, v162
	v_fmac_f32_e32 v80, v75, v83
	v_add_f32_e32 v74, 1.0, v74
	v_rcp_f32_e32 v74, v74
	v_lshlrev_b32_e32 v81, 16, v165
	v_lshlrev_b32_e32 v86, 16, v163
	v_fmac_f32_e32 v81, v76, v86
	v_mul_f32_e32 v79, v78, v74
	v_mul_f32_e32 v74, 0x3d372713, v80
	v_mul_f32_e32 v74, v80, v74
	v_fma_f32 v74, v80, v74, v80
	v_mul_f32_e32 v74, 0x3f4c422a, v74
	v_add_f32_e32 v74, v74, v74
	v_mul_f32_e32 v74, 0xbfb8aa3b, v74
	v_exp_f32_e32 v74, v74
	v_and_b32_e32 v82, 0xffff0000, v165
	v_and_b32_e32 v87, 0xffff0000, v163
	v_fmac_f32_e32 v82, v77, v87
	v_add_f32_e32 v74, 1.0, v74
	v_rcp_f32_e32 v74, v74
	v_lshlrev_b32_e32 v78, 16, v160
	v_rcp_f32_e32 v83, v70
	v_mul_f32_e32 v70, 0xbfb8aa3b, v78
	v_mul_f32_e32 v75, v80, v74
	v_mul_f32_e32 v74, 0x3d372713, v81
	v_mul_f32_e32 v74, v81, v74
; __device__ __forceinline__ unsigned cvt_pk_bf16(float lo, float hi) { unsigned r; asm volatile("v_cvt_pk_bf16_f32 %0, %1, %2" : "=v"(r) : "v"(lo), "v"(hi)); return r; }
; __device__ __forceinline__ float bflo(unsigned w) { return __uint_as_float(w << 16); }
; __device__ __forceinline__ float bfhi(unsigned w) { return __uint_as_float(w & 0xffff0000u); }
; __device__ __forceinline__ float sigm(float x) { return __builtin_amdgcn_rcpf(1.f + __expf(-x)); }
; __device__ __forceinline__ float siluf(float x) { return x * __builtin_amdgcn_rcpf(1.f + __expf(-x)); }
; __device__ __forceinline__ float gelu_tanh(float x) { const float u = 0.7978845608028654f * (x + 0.044715f * x * x * x); return x * sigm(2.f * u); }
; __device__ __forceinline__ void glu_task(int t, int l, const float* s5d, const bf16_t* P, const bf16_t* YB, const bf16_t* WGLU, bf16_t* Z1, int fr, int fq) {
;     ...
;         const int n4 = (cb0 + c4) * 16 + fq * 4;
;         const f32x4 dd = *(const f32x4*)(s5d + l * 256 + n4);
; #pragma unroll
;         for (int tb = 0; tb < 2; ++tb) { const u32x2 yw = eyw[tb][c4], uw = euw[tb][c4], gw = egw[tb][c4];
;             const float y0 = bflo(yw.x), y1 = bfhi(yw.x), y2 = bflo(yw.y), y3 = bfhi(yw.y), u0 = bflo(uw.x), u1 = bfhi(uw.x), u2 = bflo(uw.y), u3 = bfhi(uw.y);
;             const float g0 = gelu_tanh(y0 + dd[0] * u0), g1 = gelu_tanh(y1 + dd[1] * u1), g2 = gelu_tanh(y2 + dd[2] * u2), g3 = gelu_tanh(y3 + dd[3] * u3);
;             u32x2 w; w.x = cvt_pk_bf16(g0 * sigm(acc[tb][0]) * siluf(bflo(gw.x)), g1 * sigm(acc[tb][1]) * siluf(bfhi(gw.x)));
;             w.y = cvt_pk_bf16(g2 * sigm(acc[tb][2]) * siluf(bflo(gw.y)), g3 * sigm(acc[tb][3]) * siluf(bfhi(gw.y)));
;             *(u32x2*)(Z1 + (row0 + tb * 16) * 256 + n4) = w; } }
	v_fma_f32 v74, v81, v74, v81
	v_mul_f32_e32 v74, 0x3f4c422a, v74
	v_add_f32_e32 v74, v74, v74
	v_mul_f32_e32 v74, 0xbfb8aa3b, v74
	v_exp_f32_e32 v74, v74
	v_exp_f32_e32 v70, v70
	v_lshlrev_b32_e32 v80, 16, v161
	v_mul_f32_e32 v2, 0xbfb8aa3b, v2
	v_add_f32_e32 v74, 1.0, v74
	v_rcp_f32_e32 v74, v74
	v_add_f32_e32 v70, 1.0, v70
	v_exp_f32_e32 v2, v2
	v_mul_f32_e32 v81, v81, v74
	v_mul_f32_e32 v74, 0x3d372713, v82
	v_mul_f32_e32 v74, v82, v74
	v_fma_f32 v74, v82, v74, v82
	v_mul_f32_e32 v74, 0x3f4c422a, v74
	v_add_f32_e32 v74, v74, v74
	v_mul_f32_e32 v74, 0xbfb8aa3b, v74
	v_exp_f32_e32 v74, v74
	v_add_f32_e32 v2, 1.0, v2
	v_add_f32_e32 v74, 1.0, v74
	v_rcp_f32_e32 v74, v74
	s_nop 0
	v_mul_f32_e32 v77, v82, v74
	v_rcp_f32_e32 v82, v70
	v_mul_f32_e32 v70, 0xbfb8aa3b, v71
	v_exp_f32_e32 v70, v70
	v_and_b32_e32 v74, 0xffff0000, v160
	v_pk_mul_f32 v[78:79], v[82:83], v[78:79]
	v_add_f32_e32 v70, 1.0, v70
	v_rcp_f32_e32 v71, v70
	v_mul_f32_e32 v70, 0xbfb8aa3b, v74
	v_exp_f32_e32 v70, v70
	v_mul_f32_e32 v76, v78, v79
	v_add_f32_e32 v70, 1.0, v70
	v_rcp_f32_e32 v70, v70
	s_nop 0
	v_pk_mul_f32 v[70:71], v[70:71], v[74:75]
	s_nop 0
	v_mul_f32_e32 v70, v70, v71
	v_mul_f32_e32 v71, 0xbfb8aa3b, v72
	v_mul_f32_e32 v72, 0xbfb8aa3b, v73
	v_exp_f32_e32 v71, v71
	v_exp_f32_e32 v72, v72
	v_cvt_pk_bf16_f32 v70, v76, v70
	v_and_b32_e32 v76, 0xffff0000, v161
	v_add_f32_e32 v71, 1.0, v71
	v_add_f32_e32 v72, 1.0, v72
	v_rcp_f32_e32 v75, v71
	v_mul_f32_e32 v71, 0xbfb8aa3b, v80
	v_rcp_f32_e32 v73, v72
	v_mul_f32_e32 v72, 0xbfb8aa3b, v76
	v_exp_f32_e32 v71, v71
	v_exp_f32_e32 v72, v72
	v_add_f32_e32 v71, 1.0, v71
	v_add_f32_e32 v72, 1.0, v72
	v_rcp_f32_e32 v74, v71
	v_rcp_f32_e32 v72, v72
	v_pk_mul_f32 v[74:75], v[74:75], v[80:81]
	v_pk_mul_f32 v[72:73], v[72:73], v[76:77]
	v_mul_f32_e32 v71, v74, v75
	v_mul_f32_e32 v72, v72, v73
	v_cvt_pk_bf16_f32 v71, v71, v72
	v_lshl_add_u64 v[72:73], v[84:85], 0, v[138:139]
	flat_store_dwordx2 v[72:73], v[70:71]
	global_load_dwordx4 v[6:9], v178, s[22:23] offset:192
	s_waitcnt vmcnt(0)
; __device__ __forceinline__ unsigned cvt_pk_bf16(float lo, float hi) { unsigned r; asm volatile("v_cvt_pk_bf16_f32 %0, %1, %2" : "=v"(r) : "v"(lo), "v"(hi)); return r; }
; __device__ __forceinline__ float bflo(unsigned w) { return __uint_as_float(w << 16); }
; __device__ __forceinline__ float bfhi(unsigned w) { return __uint_as_float(w & 0xffff0000u); }
; __device__ __forceinline__ float sigm(float x) { return __builtin_amdgcn_rcpf(1.f + __expf(-x)); }
; __device__ __forceinline__ float siluf(float x) { return x * __builtin_amdgcn_rcpf(1.f + __expf(-x)); }
; __device__ __forceinline__ float gelu_tanh(float x) { const float u = 0.7978845608028654f * (x + 0.044715f * x * x * x); return x * sigm(2.f * u); }
; __device__ __forceinline__ void glu_task(int t, int l, const float* s5d, const bf16_t* P, const bf16_t* YB, const bf16_t* WGLU, bf16_t* Z1, int fr, int fq) {
;     ...
;         const int n4 = (cb0 + c4) * 16 + fq * 4;
;         const f32x4 dd = *(const f32x4*)(s5d + l * 256 + n4);
; #pragma unroll
;         for (int tb = 0; tb < 2; ++tb) { const u32x2 yw = eyw[tb][c4], uw = euw[tb][c4], gw = egw[tb][c4];
;             const float y0 = bflo(yw.x), y1 = bfhi(yw.x), y2 = bflo(yw.y), y3 = bfhi(yw.y), u0 = bflo(uw.x), u1 = bfhi(uw.x), u2 = bflo(uw.y), u3 = bfhi(uw.y);
;             const float g0 = gelu_tanh(y0 + dd[0] * u0), g1 = gelu_tanh(y1 + dd[1] * u1), g2 = gelu_tanh(y2 + dd[2] * u2), g3 = gelu_tanh(y3 + dd[3] * u3);
;             u32x2 w; w.x = cvt_pk_bf16(g0 * sigm(acc[tb][0]) * siluf(bflo(gw.x)), g1 * sigm(acc[tb][1]) * siluf(bfhi(gw.x)));
;             w.y = cvt_pk_bf16(g2 * sigm(acc[tb][2]) * siluf(bflo(gw.y)), g3 * sigm(acc[tb][3]) * siluf(bfhi(gw.y)));
;             *(u32x2*)(Z1 + (row0 + tb * 16) * 256 + n4) = w; } }
; __global__ void __launch_bounds__(512, 2) fwd_kernel(KArgs a) {
;     ...
;             { IDS; for (int t = gw, k_ = 0; t < (wctx ? MH : ML) / 8; t = NGW != 2048 ? t + NGW : (((gw & 7) == 0 && k_ == 0) ? NGW + (gw >> 3) : (wctx ? MH : ML) / 8), ++k_) glu_task(t, l, a.in[21], P, YB, WGLU, Z1, fr, fq); }
	v_fmac_f32_e32 v22, v6, v23
	v_mul_f32_e32 v23, 0x3d372713, v22
	v_mul_f32_e32 v23, v22, v23
	v_fma_f32 v23, v22, v23, v22
	v_mul_f32_e32 v23, 0x3f4c422a, v23
	v_add_f32_e32 v23, v23, v23
	v_mul_f32_e32 v23, 0xbfb8aa3b, v23
	v_exp_f32_e32 v23, v23
	v_fmac_f32_e32 v24, v7, v25
	v_fmac_f32_e32 v26, v8, v27
	v_fmac_f32_e32 v28, v9, v29
	v_add_f32_e32 v23, 1.0, v23
	v_rcp_f32_e32 v23, v23
	s_nop 0
	v_mul_f32_e32 v23, v22, v23
	v_mul_f32_e32 v22, 0x3d372713, v24
	v_mul_f32_e32 v22, v24, v22
	v_fma_f32 v22, v24, v22, v24
	v_mul_f32_e32 v22, 0x3f4c422a, v22
	v_add_f32_e32 v22, v22, v22
	v_mul_f32_e32 v22, 0xbfb8aa3b, v22
	v_exp_f32_e32 v22, v22
	s_nop 0
	v_add_f32_e32 v22, 1.0, v22
	v_rcp_f32_e32 v22, v22
	s_nop 0
	v_mul_f32_e32 v25, v24, v22
	v_mul_f32_e32 v22, 0x3d372713, v26
	v_mul_f32_e32 v22, v26, v22
	v_fma_f32 v22, v26, v22, v26
	v_mul_f32_e32 v22, 0x3f4c422a, v22
	v_add_f32_e32 v22, v22, v22
	v_mul_f32_e32 v22, 0xbfb8aa3b, v22
	v_exp_f32_e32 v22, v22
	v_and_b32_e32 v24, 0xffff0000, v146
	v_add_f32_e32 v22, 1.0, v22
	v_rcp_f32_e32 v22, v22
	s_nop 0
	v_mul_f32_e32 v27, v26, v22
	v_mul_f32_e32 v22, 0x3d372713, v28
	v_mul_f32_e32 v22, v28, v22
	v_fma_f32 v22, v28, v22, v28
	v_mul_f32_e32 v22, 0x3f4c422a, v22
	v_add_f32_e32 v22, v22, v22
	v_mul_f32_e32 v22, 0xbfb8aa3b, v22
	v_exp_f32_e32 v22, v22
	v_lshlrev_b32_e32 v26, 16, v147
	v_add_f32_e32 v22, 1.0, v22
	v_rcp_f32_e32 v22, v22
	s_nop 0
	v_mul_f32_e32 v29, v28, v22
	v_lshlrev_b32_e32 v22, 16, v146
	v_mul_f32_e32 v14, 0xbfb8aa3b, v22
	v_exp_f32_e32 v14, v14
	v_and_b32_e32 v28, 0xffff0000, v147
	v_add_f32_e32 v14, 1.0, v14
	v_rcp_f32_e32 v30, v14
	v_mul_f32_e32 v14, 0xbfb8aa3b, v15
	v_exp_f32_e32 v14, v14
	v_pk_mul_f32 v[22:23], v[30:31], v[22:23]
	s_nop 0
	v_mul_f32_e32 v22, v22, v23
	v_add_f32_e32 v14, 1.0, v14
	v_rcp_f32_e32 v15, v14
	v_mul_f32_e32 v14, 0xbfb8aa3b, v24
	v_exp_f32_e32 v14, v14
	s_nop 0
	v_add_f32_e32 v14, 1.0, v14
	v_rcp_f32_e32 v14, v14
	s_nop 0
	v_pk_mul_f32 v[14:15], v[14:15], v[24:25]
	s_nop 0
	v_mul_f32_e32 v14, v14, v15
	v_mul_f32_e32 v15, 0xbfb8aa3b, v16
	v_mul_f32_e32 v16, 0xbfb8aa3b, v17
	v_exp_f32_e32 v15, v15
	v_exp_f32_e32 v16, v16
	v_cvt_pk_bf16_f32 v14, v22, v14
	v_add_f32_e32 v15, 1.0, v15
	v_add_f32_e32 v16, 1.0, v16
	v_rcp_f32_e32 v23, v15
	v_mul_f32_e32 v15, 0xbfb8aa3b, v26
	v_rcp_f32_e32 v17, v16
	v_mul_f32_e32 v16, 0xbfb8aa3b, v28
	v_exp_f32_e32 v15, v15
	v_exp_f32_e32 v16, v16
	v_add_f32_e32 v15, 1.0, v15
	v_add_f32_e32 v16, 1.0, v16
	v_rcp_f32_e32 v22, v15
	v_rcp_f32_e32 v16, v16
	v_pk_mul_f32 v[22:23], v[22:23], v[26:27]
	v_pk_mul_f32 v[16:17], v[16:17], v[28:29]
	v_mul_f32_e32 v15, v22, v23
	v_mul_f32_e32 v16, v16, v17
	v_cvt_pk_bf16_f32 v15, v15, v16
	v_lshl_add_u64 v[16:17], v[172:173], 0, v[18:19]
	flat_store_dwordx2 v[16:17], v[14:15]
	v_lshlrev_b32_e32 v14, 16, v144
	v_lshlrev_b32_e32 v15, 16, v142
	v_fmac_f32_e32 v14, v6, v15
	v_mul_f32_e32 v6, 0x3d372713, v14
	v_mul_f32_e32 v6, v14, v6
	v_fma_f32 v6, v14, v6, v14
	v_mul_f32_e32 v6, 0x3f4c422a, v6
	v_add_f32_e32 v6, v6, v6
	v_mul_f32_e32 v6, 0xbfb8aa3b, v6
	v_exp_f32_e32 v6, v6
	v_and_b32_e32 v16, 0xffff0000, v144
	v_and_b32_e32 v19, 0xffff0000, v142
	v_fmac_f32_e32 v16, v7, v19
	v_add_f32_e32 v6, 1.0, v6
	v_rcp_f32_e32 v6, v6
	v_lshlrev_b32_e32 v17, 16, v145
	v_lshlrev_b32_e32 v22, 16, v143
	v_fmac_f32_e32 v17, v8, v22
	v_mul_f32_e32 v15, v14, v6
	v_mul_f32_e32 v6, 0x3d372713, v16
	v_mul_f32_e32 v6, v16, v6
	v_fma_f32 v6, v16, v6, v16
	v_mul_f32_e32 v6, 0x3f4c422a, v6
	v_add_f32_e32 v6, v6, v6
	v_mul_f32_e32 v6, 0xbfb8aa3b, v6
	v_exp_f32_e32 v6, v6
	v_and_b32_e32 v18, 0xffff0000, v145
	v_and_b32_e32 v23, 0xffff0000, v143
	v_fmac_f32_e32 v18, v9, v23
	v_add_f32_e32 v6, 1.0, v6
	v_rcp_f32_e32 v6, v6
	v_lshlrev_b32_e32 v14, 16, v140
	v_rcp_f32_e32 v19, v2
	v_mul_f32_e32 v2, 0xbfb8aa3b, v14
	v_mul_f32_e32 v7, v16, v6
	v_mul_f32_e32 v6, 0x3d372713, v17
	v_mul_f32_e32 v6, v17, v6
	v_fma_f32 v6, v17, v6, v17
	v_mul_f32_e32 v6, 0x3f4c422a, v6
	v_add_f32_e32 v6, v6, v6
	v_mul_f32_e32 v6, 0xbfb8aa3b, v6
	v_exp_f32_e32 v6, v6
	v_exp_f32_e32 v2, v2
	v_lshlrev_b32_e32 v16, 16, v141
	v_add_f32_e32 v6, 1.0, v6
	v_rcp_f32_e32 v6, v6
	v_add_f32_e32 v2, 1.0, v2
	v_mul_f32_e32 v17, v17, v6
	v_mul_f32_e32 v6, 0x3d372713, v18
	v_mul_f32_e32 v6, v18, v6
	v_fma_f32 v6, v18, v6, v18
	v_mul_f32_e32 v6, 0x3f4c422a, v6
	v_add_f32_e32 v6, v6, v6
	v_mul_f32_e32 v6, 0xbfb8aa3b, v6
	v_exp_f32_e32 v6, v6
	s_nop 0
	v_add_f32_e32 v6, 1.0, v6
	v_rcp_f32_e32 v6, v6
	s_nop 0
	v_mul_f32_e32 v9, v18, v6
	v_rcp_f32_e32 v18, v2
	v_mul_f32_e32 v2, 0xbfb8aa3b, v3
	v_exp_f32_e32 v2, v2
	v_and_b32_e32 v6, 0xffff0000, v140
	v_pk_mul_f32 v[14:15], v[18:19], v[14:15]
	v_add_f32_e32 v2, 1.0, v2
	v_rcp_f32_e32 v3, v2
	v_mul_f32_e32 v2, 0xbfb8aa3b, v6
	v_exp_f32_e32 v2, v2
	v_mul_f32_e32 v8, v14, v15
	v_add_f32_e32 v2, 1.0, v2
	v_rcp_f32_e32 v2, v2
	s_nop 0
	v_pk_mul_f32 v[2:3], v[2:3], v[6:7]
	s_nop 0
	v_mul_f32_e32 v2, v2, v3
	v_mul_f32_e32 v3, 0xbfb8aa3b, v4
	v_mul_f32_e32 v4, 0xbfb8aa3b, v5
	v_exp_f32_e32 v3, v3
	v_exp_f32_e32 v4, v4
	v_cvt_pk_bf16_f32 v2, v8, v2
	v_and_b32_e32 v8, 0xffff0000, v141
	v_add_f32_e32 v3, 1.0, v3
	v_add_f32_e32 v4, 1.0, v4
	v_rcp_f32_e32 v7, v3
	v_mul_f32_e32 v3, 0xbfb8aa3b, v16
	v_rcp_f32_e32 v5, v4
	v_mul_f32_e32 v4, 0xbfb8aa3b, v8
	v_exp_f32_e32 v3, v3
	v_exp_f32_e32 v4, v4
	v_add_f32_e32 v3, 1.0, v3
	v_add_f32_e32 v4, 1.0, v4
	v_rcp_f32_e32 v6, v3
	v_rcp_f32_e32 v4, v4
	v_pk_mul_f32 v[6:7], v[6:7], v[16:17]
	v_pk_mul_f32 v[4:5], v[4:5], v[8:9]
	v_mul_f32_e32 v3, v6, v7
	v_mul_f32_e32 v4, v4, v5
	v_cvt_pk_bf16_f32 v3, v3, v4
	v_lshl_add_u64 v[4:5], v[20:21], 0, v[138:139]
	flat_store_dwordx2 v[4:5], v[2:3]
	s_cbranch_scc0 .LBB0_1282
